# GEMM K-loops P3/P5/P6/P8/P9: per-segment s_setprio flips removed, static s_setprio 1 for waves 4-7 for the whole phase (P1 and KV loops unchanged); on top of p1pk + p8pk + czero
# speedup vs baseline: 1.0033x; 1.0033x over previous
; #define PG8_LAS __attribute__((address_space(3)))
;     __device__ bool next(int i, Unit& u) const { if (!so.next(i >> 1, u)) return false; u.sel = i & 1; return true; }
;     __host__ __device__ bool next(int i, Unit& u) const {
;         const long L = (long)i * G + c; if (L >= nwg) return false;
;         int wgid = (int)L; { const int q = nwg / NXCD, r = nwg % NXCD, xcd = wgid % NXCD, off = wgid / NXCD; wgid = (xcd < r ? xcd * (q + 1) : r * (q + 1) + (xcd - r) * q) + off; }
;         const int nig = WGM * nN, gid = wgid / nig, fm = gid * WGM, gsz = (nM - fm) < WGM ? (nM - fm) : WGM;
;         u.pm = fm + ((wgid % nig) % gsz); u.pn = (wgid % nig) / gsz; u.sel = 0; return true;
; template <class Epi, class Sched, bool ALIGN_EPI = false, bool SP2 = false>
; __device__ __forceinline__ void gemm_phase(PG8_LAS unsigned char* lds, const Gemm g, const Sched& S, const Epi& E) {
;     int tid_ = threadIdx.x; asm volatile("" : "+v"(tid_));
;     const int tid = tid_, wid = __builtin_amdgcn_readfirstlane(tid >> 6), lane = tid & 63, wr = wid >> 2, wc = wid & 3, fr = lane & 15, fq = lane >> 4;
;     int K_ = g.K; asm volatile("" : "+s"(K_));
;     const int K = K_, nt = K / BK;
;     unsigned voffA[2], voffB[2];
; #pragma unroll
;     for (int i = 0; i < 2; ++i) { int R, C; stage_rc(tid * 16 + i * 8192, R, C); const int Rb = Epi::PERM ? ((R & ~31) + perm32(R & 31)) : R;
;         voffA[i] = (unsigned)(R * K + C) * 2u; voffB[i] = (unsigned)(Rb * K + C) * 2u; }
;     const size_t kstep = (size_t)(BK * 2);
;     const size_t hstep = (size_t)HALF * K * 2;
;     const size_t tstep = 2 * hstep;
;     const unsigned ldsw = (unsigned)wid * 1024u;
;     const int aoff = lds_byte(wr * 64 + fr, fq * 8), boff = lds_byte(wc * 32 + fr, fq * 8);
;     ...
;     Unit cur, nxt; int ui = 0;
;     if (!S.next(0, cur)) return;
.LBB0_519:
	s_or_b64 exec, exec, s[0:1]
	v_readfirstlane_b32 s99, v201
	s_nop 3
	s_lshr_b32 s99, s99, 8
	s_cmp_eq_u32 s99, 1
	s_cbranch_scc0 .Lprio3_skip
	s_setprio 1
.Lprio3_skip:
	v_mov_b32_e32 v12, v201
	s_cmpk_lt_i32 s2, 0x600
	s_waitcnt lgkmcnt(0)
	s_barrier
	s_movk_i32 s0, 0x100
	v_readfirstlane_b32 s46, v12
	s_cselect_b64 s[4:5], -1, 0
	s_cmpk_gt_i32 s2, 0x5ff
	s_cbranch_scc1 .LBB0_521
	s_ashr_i32 s1, s2, 31
	s_lshr_b32 s1, s1, 29
	s_add_i32 s1, s2, s1
	s_ashr_i32 s3, s1, 3
	s_and_b32 s1, s1, -8
	s_sub_i32 s1, s2, s1
	s_cmp_lt_i32 s1, 0
	s_movk_i32 s8, 0xc1
	s_cselect_b32 s8, s8, 0xc0
	s_mul_i32 s1, s1, s8
	s_add_i32 s1, s1, s3
	s_mul_hi_i32 s3, s1, 0x2aaaaaab
	s_lshr_b32 s8, s3, 31
	s_ashr_i32 s3, s3, 3
	s_add_i32 s3, s3, s8
	s_lshl_b32 s8, s3, 3
	s_mul_i32 s3, s3, 48
	s_sub_i32 s1, s1, s3
	s_bfe_i32 s3, s1, 0x80000
	s_bfe_u32 s3, s3, 0x3000c
	s_add_i32 s3, s1, s3
	s_bfe_i32 s9, s3, 0x80000
	s_and_b32 s3, s3, 0xf8
	s_sub_i32 s1, s1, s3
	s_sext_i32_i16 s9, s9
	s_sext_i32_i8 s1, s1
	s_add_i32 s94, s8, s1
	s_ashr_i32 s12, s9, 3

; #define PG8_STAGE(bufoff, gbase, voff) do { _Pragma("unroll") for (int _i = 0; _i < 2; ++_i) \
;         __builtin_amdgcn_global_load_lds((const unsigned*)((const char*)(gbase) + (voff)[_i]), (PG8_LAS unsigned*)(lds + (bufoff) + ldsw + _i * 8192), 16, 0, 0); } while (0)
; #define PG8_LDA(dst, b, h) do { _Pragma("unroll") for (int m = 0; m < 4; ++m) _Pragma("unroll") for (int k = 0; k < 2; ++k) dst[m][k] = *(const PG8_LAS bf16x8*)(lds + PG8_SA(b, h) + aoff + m * 2048 + k * 1024); } while (0)
; #define PG8_LDB(dst, b, h) do { _Pragma("unroll") for (int n = 0; n < 2; ++n) _Pragma("unroll") for (int k = 0; k < 2; ++k) dst[n][k] = *(const PG8_LAS bf16x8*)(lds + PG8_SB(b, h) + boff + n * 2048 + k * 1024); } while (0)
; #define PG8_MMA(ai, bj, At, Bt) do { __builtin_amdgcn_s_setprio(1); _Pragma("unroll") for (int m = 0; m < 4; ++m) _Pragma("unroll") for (int n = 0; n < 2; ++n) _Pragma("unroll") for (int k = 0; k < 2; ++k) \
;         acc[ai][bj][m][n] = __builtin_amdgcn_mfma_f32_16x16x32_bf16(Bt[n][k], At[m][k], acc[ai][bj][m][n], 0, 0, 0); __builtin_amdgcn_s_setprio(0); } while (0)
; #define PG8_WAIT_V(n) asm volatile("s_waitcnt vmcnt(" #n ")" ::: "memory")
; #define PG8_BAR __builtin_amdgcn_s_barrier()
; template <class Epi, class Sched, bool ALIGN_EPI = false, bool SP2 = false>
; __device__ __forceinline__ void gemm_phase(PG8_LAS unsigned char* lds, const Gemm g, const Sched& S, const Epi& E) {
;     ...
;         for (int t = 0; t < nt; t += 2) {
;             const bool last = (t == nt - 2);
;             const char* a1 = cA + (size_t)(t + 1) * kstep;
;             const char* a2 = last ? nA : cA + (size_t)(t + 2) * kstep; const char* b2 = last ? nB : cB + (size_t)(t + 2) * kstep;
;             const char* a3 = a2 + kstep; const char* b3 = b2 + kstep;
;             if (last && has_next) S.a_ready(nxt);
;             if constexpr (SP2) {
;             PG8_LDB(B0, 0, 0); PG8_LDB(B1, 0, 1); PG8_SCHED; PG8_LDA(At, 0, 0); PG8_STAGE(PG8_SA(1, 1), a1 + hstep, voffA);
;             PG8_WAIT_V(8); PG8_WAIT_L(0); PG8_BAR; PG8_MMA(0, 0, At, B0); PG8_MMA(0, 1, At, B1); PG8_BAR; PG8_SCHED;
;             PG8_LDA(At, 0, 1); PG8_STAGE(PG8_SB(0, 0), b2, voffB); PG8_STAGE(PG8_SB(0, 1), b2 + hstep, voffB); PG8_STAGE(PG8_SA(0, 0), a2, voffA);
;             PG8_WAIT_V(8); PG8_WAIT_L(0); PG8_BAR; PG8_MMA(1, 0, At, B0); PG8_MMA(1, 1, At, B1); PG8_BAR; PG8_SCHED;
.Lcz_go_535:
	s_add_u32 s58, s58, 0x80
	s_addc_u32 s59, s59, 0
	s_add_u32 s95, s60, 0x100
	s_addc_u32 s96, s61, 0
	s_mov_b32 s60, 0
	ds_read_b128 v[128:131], v166
	ds_read_b128 v[156:159], v166 offset:1024
	ds_read_b128 v[160:163], v166 offset:2048
	ds_read_b128 v[170:173], v166 offset:3072
	ds_read_b128 v[174:177], v167
	ds_read_b128 v[178:181], v167 offset:1024
	ds_read_b128 v[182:185], v167 offset:2048
	ds_read_b128 v[186:189], v167 offset:3072
	s_add_i32 s97, s60, 2
	s_add_u32 s16, s58, 0x80
	s_addc_u32 s17, s59, 0
	s_cmp_eq_u32 s76, s60
	s_cselect_b32 s60, s0, s16
	s_cselect_b32 s61, s1, s17
	s_cselect_b32 vcc_hi, s57, s96
	s_cselect_b32 vcc_lo, s56, s95
	v_lshl_add_u64 v[198:199], s[58:59], 0, v[148:149]
	s_add_i32 m0, s62, 0xc000
	ds_read_b128 v[190:193], v168
	ds_read_b128 v[194:197], v168 offset:1024
	ds_read_b128 v[202:205], v168 offset:2048
	ds_read_b128 v[206:209], v168 offset:3072
	ds_read_b128 v[210:213], v168 offset:4096
	ds_read_b128 v[214:217], v168 offset:5120
	ds_read_b128 v[218:221], v168 offset:6144
	ds_read_b128 v[222:225], v168 offset:7168
	global_load_lds_dwordx4 v[198:199], off
	v_lshl_add_u64 v[198:199], s[58:59], 0, v[150:151]
	s_add_i32 m0, s62, 0xe000
	s_nop 0
	global_load_lds_dwordx4 v[198:199], off
	s_waitcnt vmcnt(8)
	s_waitcnt lgkmcnt(0)
	s_barrier
	s_waitcnt lgkmcnt(0)
	v_mfma_f32_16x16x32_bf16 v[120:123], v[128:131], v[190:193], 0
	v_mfma_f32_16x16x32_bf16 v[124:127], v[160:163], v[190:193], 0
	v_mfma_f32_16x16x32_bf16 v[108:111], v[128:131], v[202:205], 0
	v_mfma_f32_16x16x32_bf16 v[104:107], v[160:163], v[202:205], 0
	v_mfma_f32_16x16x32_bf16 v[92:95], v[128:131], v[210:213], 0
	v_mfma_f32_16x16x32_bf16 v[88:91], v[160:163], v[210:213], 0
	v_mfma_f32_16x16x32_bf16 v[76:79], v[128:131], v[218:221], 0
	v_mfma_f32_16x16x32_bf16 v[72:75], v[160:163], v[218:221], 0
	v_mfma_f32_16x16x32_bf16 v[120:123], v[156:159], v[194:197], v[120:123]
	v_mfma_f32_16x16x32_bf16 v[124:127], v[170:173], v[194:197], v[124:127]
	v_mfma_f32_16x16x32_bf16 v[108:111], v[156:159], v[206:209], v[108:111]
	v_mfma_f32_16x16x32_bf16 v[104:107], v[170:173], v[206:209], v[104:107]
	v_mfma_f32_16x16x32_bf16 v[92:95], v[156:159], v[214:217], v[92:95]
	v_mfma_f32_16x16x32_bf16 v[88:91], v[170:173], v[214:217], v[88:91]
	v_mfma_f32_16x16x32_bf16 v[76:79], v[156:159], v[222:225], v[76:79]
	v_mfma_f32_16x16x32_bf16 v[72:75], v[170:173], v[222:225], v[72:75]
	v_mfma_f32_16x16x32_bf16 v[116:119], v[174:177], v[190:193], 0
	v_mfma_f32_16x16x32_bf16 v[112:115], v[182:185], v[190:193], 0
	v_mfma_f32_16x16x32_bf16 v[100:103], v[174:177], v[202:205], 0
	v_mfma_f32_16x16x32_bf16 v[96:99], v[182:185], v[202:205], 0
	v_mfma_f32_16x16x32_bf16 v[84:87], v[174:177], v[210:213], 0
	v_mfma_f32_16x16x32_bf16 v[80:83], v[182:185], v[210:213], 0
	v_mfma_f32_16x16x32_bf16 v[68:71], v[174:177], v[218:221], 0
	v_mfma_f32_16x16x32_bf16 v[64:67], v[182:185], v[218:221], 0
	v_mfma_f32_16x16x32_bf16 v[116:119], v[178:181], v[194:197], v[116:119]
	v_mfma_f32_16x16x32_bf16 v[112:115], v[186:189], v[194:197], v[112:115]
	v_mfma_f32_16x16x32_bf16 v[100:103], v[178:181], v[206:209], v[100:103]
	v_mfma_f32_16x16x32_bf16 v[96:99], v[186:189], v[206:209], v[96:99]
	v_mfma_f32_16x16x32_bf16 v[84:87], v[178:181], v[214:217], v[84:87]
	v_mfma_f32_16x16x32_bf16 v[80:83], v[186:189], v[214:217], v[80:83]
	v_mfma_f32_16x16x32_bf16 v[68:71], v[178:181], v[222:225], v[68:71]
	v_mfma_f32_16x16x32_bf16 v[64:67], v[186:189], v[222:225], v[64:67]
	s_barrier
	s_add_i32 s16, s79, s49
	v_lshl_add_u64 v[198:199], vcc, 0, v[134:135]
	s_mov_b32 m0, s16
	ds_read_b128 v[190:193], v168 offset:16384
	ds_read_b128 v[194:197], v168 offset:17408
	ds_read_b128 v[202:205], v168 offset:18432
	ds_read_b128 v[206:209], v168 offset:19456
	ds_read_b128 v[210:213], v168 offset:20480
	ds_read_b128 v[214:217], v168 offset:21504
	ds_read_b128 v[218:221], v168 offset:22528
	ds_read_b128 v[222:225], v168 offset:23552
	global_load_lds_dwordx4 v[198:199], off
	s_add_i32 m0, s16, 0x2000
	v_lshl_add_u64 v[226:227], vcc, 0, v[138:139]
	s_add_u32 vcc_lo, vcc_lo, s8
	s_addc_u32 vcc_hi, vcc_hi, s9
	s_add_i32 s16, s80, s49
	global_load_lds_dwordx4 v[226:227], off
	v_lshl_add_u64 v[228:229], vcc, 0, v[134:135]
	s_mov_b32 m0, s16
	v_lshl_add_u64 v[230:231], vcc, 0, v[138:139]
	global_load_lds_dwordx4 v[228:229], off
	s_add_i32 m0, s16, 0x2000
	v_lshl_add_u64 v[232:233], s[60:61], 0, v[132:133]
	global_load_lds_dwordx4 v[230:231], off
	s_mov_b32 m0, s62
	v_lshl_add_u64 v[236:237], s[60:61], 0, v[136:137]
	global_load_lds_dwordx4 v[232:233], off
	s_mov_b32 m0, s63
	s_nop 0
	global_load_lds_dwordx4 v[236:237], off
	s_waitcnt vmcnt(8)
	s_waitcnt lgkmcnt(0)
	s_barrier
; #define PG8_STAGE(bufoff, gbase, voff) do { _Pragma("unroll") for (int _i = 0; _i < 2; ++_i) \
;         __builtin_amdgcn_global_load_lds((const unsigned*)((const char*)(gbase) + (voff)[_i]), (PG8_LAS unsigned*)(lds + (bufoff) + ldsw + _i * 8192), 16, 0, 0); } while (0)
; #define PG8_LDA(dst, b, h) do { _Pragma("unroll") for (int m = 0; m < 4; ++m) _Pragma("unroll") for (int k = 0; k < 2; ++k) dst[m][k] = *(const PG8_LAS bf16x8*)(lds + PG8_SA(b, h) + aoff + m * 2048 + k * 1024); } while (0)
; #define PG8_LDB(dst, b, h) do { _Pragma("unroll") for (int n = 0; n < 2; ++n) _Pragma("unroll") for (int k = 0; k < 2; ++k) dst[n][k] = *(const PG8_LAS bf16x8*)(lds + PG8_SB(b, h) + boff + n * 2048 + k * 1024); } while (0)
; #define PG8_MMA(ai, bj, At, Bt) do { __builtin_amdgcn_s_setprio(1); _Pragma("unroll") for (int m = 0; m < 4; ++m) _Pragma("unroll") for (int n = 0; n < 2; ++n) _Pragma("unroll") for (int k = 0; k < 2; ++k) \
;         acc[ai][bj][m][n] = __builtin_amdgcn_mfma_f32_16x16x32_bf16(Bt[n][k], At[m][k], acc[ai][bj][m][n], 0, 0, 0); __builtin_amdgcn_s_setprio(0); } while (0)
; #define PG8_WAIT_V(n) asm volatile("s_waitcnt vmcnt(" #n ")" ::: "memory")
; #define PG8_WAIT_L(n) asm volatile("s_waitcnt lgkmcnt(" #n ")" ::: "memory")
; #define PG8_BAR __builtin_amdgcn_s_barrier()
; #define PG8_SCHED __builtin_amdgcn_sched_barrier(0)
; template <class Epi, class Sched, bool ALIGN_EPI = false, bool SP2 = false>
; __device__ __forceinline__ void gemm_phase(PG8_LAS unsigned char* lds, const Gemm g, const Sched& S, const Epi& E) {
;     ...
;             if constexpr (SP2) {
;             PG8_LDB(B0, 0, 0); PG8_LDB(B1, 0, 1); PG8_SCHED; PG8_LDA(At, 0, 0); PG8_STAGE(PG8_SA(1, 1), a1 + hstep, voffA);
;             PG8_WAIT_V(8); PG8_WAIT_L(0); PG8_BAR; PG8_MMA(0, 0, At, B0); PG8_MMA(0, 1, At, B1); PG8_BAR; PG8_SCHED;
;             PG8_LDA(At, 0, 1); PG8_STAGE(PG8_SB(0, 0), b2, voffB); PG8_STAGE(PG8_SB(0, 1), b2 + hstep, voffB); PG8_STAGE(PG8_SA(0, 0), a2, voffA);
;             PG8_WAIT_V(8); PG8_WAIT_L(0); PG8_BAR; PG8_MMA(1, 0, At, B0); PG8_MMA(1, 1, At, B1); PG8_BAR; PG8_SCHED;
;             PG8_LDB(B0, 1, 0); PG8_LDB(B1, 1, 1); PG8_SCHED; PG8_LDA(At, 1, 0); PG8_STAGE(PG8_SA(0, 1), a2 + hstep, voffA);
;             PG8_WAIT_V(8); PG8_WAIT_L(0); PG8_BAR; PG8_MMA(0, 0, At, B0); PG8_MMA(0, 1, At, B1); PG8_BAR; PG8_SCHED;
	s_waitcnt lgkmcnt(0)
	v_mfma_f32_16x16x32_bf16 v[60:63], v[128:131], v[190:193], 0
	v_mfma_f32_16x16x32_bf16 v[56:59], v[160:163], v[190:193], 0
	v_mfma_f32_16x16x32_bf16 v[44:47], v[128:131], v[202:205], 0
	v_mfma_f32_16x16x32_bf16 v[40:43], v[160:163], v[202:205], 0
	v_mfma_f32_16x16x32_bf16 v[28:31], v[128:131], v[210:213], 0
	v_mfma_f32_16x16x32_bf16 v[24:27], v[160:163], v[210:213], 0
	v_mfma_f32_16x16x32_bf16 v[12:15], v[128:131], v[218:221], 0
	v_mfma_f32_16x16x32_bf16 v[8:11], v[160:163], v[218:221], 0
	v_mfma_f32_16x16x32_bf16 v[60:63], v[156:159], v[194:197], v[60:63]
	v_mfma_f32_16x16x32_bf16 v[56:59], v[170:173], v[194:197], v[56:59]
	v_mfma_f32_16x16x32_bf16 v[44:47], v[156:159], v[206:209], v[44:47]
	v_mfma_f32_16x16x32_bf16 v[40:43], v[170:173], v[206:209], v[40:43]
	v_mfma_f32_16x16x32_bf16 v[28:31], v[156:159], v[214:217], v[28:31]
	v_mfma_f32_16x16x32_bf16 v[24:27], v[170:173], v[214:217], v[24:27]
	v_mfma_f32_16x16x32_bf16 v[12:15], v[156:159], v[222:225], v[12:15]
	v_mfma_f32_16x16x32_bf16 v[8:11], v[170:173], v[222:225], v[8:11]
	v_mfma_f32_16x16x32_bf16 v[52:55], v[174:177], v[190:193], 0
	v_mfma_f32_16x16x32_bf16 v[48:51], v[182:185], v[190:193], 0
	v_mfma_f32_16x16x32_bf16 v[36:39], v[174:177], v[202:205], 0
	v_mfma_f32_16x16x32_bf16 v[32:35], v[182:185], v[202:205], 0
	v_mfma_f32_16x16x32_bf16 v[20:23], v[174:177], v[210:213], 0
	v_mfma_f32_16x16x32_bf16 v[16:19], v[182:185], v[210:213], 0
	v_mfma_f32_16x16x32_bf16 v[4:7], v[174:177], v[218:221], 0
	v_mfma_f32_16x16x32_bf16 v[0:3], v[182:185], v[218:221], 0
	v_mfma_f32_16x16x32_bf16 v[52:55], v[178:181], v[194:197], v[52:55]
	v_mfma_f32_16x16x32_bf16 v[48:51], v[186:189], v[194:197], v[48:51]
	v_mfma_f32_16x16x32_bf16 v[36:39], v[178:181], v[206:209], v[36:39]
	v_mfma_f32_16x16x32_bf16 v[32:35], v[186:189], v[206:209], v[32:35]
	v_mfma_f32_16x16x32_bf16 v[20:23], v[178:181], v[214:217], v[20:23]
	v_mfma_f32_16x16x32_bf16 v[16:19], v[186:189], v[214:217], v[16:19]
	v_mfma_f32_16x16x32_bf16 v[4:7], v[178:181], v[222:225], v[4:7]
	v_mfma_f32_16x16x32_bf16 v[0:3], v[186:189], v[222:225], v[0:3]
	s_barrier
	s_add_i32 s16, 0, 0x18000
	v_add_u32_e32 v140, s16, v165
	s_add_i32 s17, 0, 0x1c000
	ds_read_b128 v[128:131], v140
	ds_read_b128 v[156:159], v140 offset:1024
	ds_read_b128 v[160:163], v140 offset:2048
	ds_read_b128 v[170:173], v140 offset:3072
	v_add_u32_e32 v140, s17, v165
	ds_read_b128 v[174:177], v140
	ds_read_b128 v[178:181], v140 offset:1024
	ds_read_b128 v[182:185], v140 offset:2048
	ds_read_b128 v[186:189], v140 offset:3072
	s_add_u32 s60, s60, s8
	s_addc_u32 s61, s61, s9
	s_mov_b32 m0, s70
	v_lshl_add_u64 v[238:239], s[60:61], 0, v[132:133]
	ds_read_b128 v[190:193], v168 offset:32768
	ds_read_b128 v[194:197], v168 offset:33792
	ds_read_b128 v[202:205], v168 offset:34816
	ds_read_b128 v[206:209], v168 offset:35840
	ds_read_b128 v[210:213], v168 offset:36864
	ds_read_b128 v[214:217], v168 offset:37888
	ds_read_b128 v[218:221], v168 offset:38912
	ds_read_b128 v[222:225], v168 offset:39936
	global_load_lds_dwordx4 v[238:239], off
	v_lshl_add_u64 v[238:239], s[60:61], 0, v[136:137]
	s_mov_b32 m0, s71
	s_nop 0
	global_load_lds_dwordx4 v[238:239], off
	s_waitcnt vmcnt(8)
	s_waitcnt lgkmcnt(0)
	s_barrier
	s_waitcnt lgkmcnt(0)
	v_mfma_f32_16x16x32_bf16 v[120:123], v[128:131], v[190:193], v[120:123]
	v_mfma_f32_16x16x32_bf16 v[124:127], v[160:163], v[190:193], v[124:127]
	v_mfma_f32_16x16x32_bf16 v[108:111], v[128:131], v[202:205], v[108:111]
	v_mfma_f32_16x16x32_bf16 v[104:107], v[160:163], v[202:205], v[104:107]
	v_mfma_f32_16x16x32_bf16 v[92:95], v[128:131], v[210:213], v[92:95]
	v_mfma_f32_16x16x32_bf16 v[88:91], v[160:163], v[210:213], v[88:91]
	v_mfma_f32_16x16x32_bf16 v[76:79], v[128:131], v[218:221], v[76:79]
	v_mfma_f32_16x16x32_bf16 v[72:75], v[160:163], v[218:221], v[72:75]
	v_mfma_f32_16x16x32_bf16 v[120:123], v[156:159], v[194:197], v[120:123]
	v_mfma_f32_16x16x32_bf16 v[124:127], v[170:173], v[194:197], v[124:127]
	v_mfma_f32_16x16x32_bf16 v[108:111], v[156:159], v[206:209], v[108:111]
	v_mfma_f32_16x16x32_bf16 v[104:107], v[170:173], v[206:209], v[104:107]
	v_mfma_f32_16x16x32_bf16 v[92:95], v[156:159], v[214:217], v[92:95]
	v_mfma_f32_16x16x32_bf16 v[88:91], v[170:173], v[214:217], v[88:91]
	v_mfma_f32_16x16x32_bf16 v[76:79], v[156:159], v[222:225], v[76:79]
	v_mfma_f32_16x16x32_bf16 v[72:75], v[170:173], v[222:225], v[72:75]
	v_mfma_f32_16x16x32_bf16 v[116:119], v[174:177], v[190:193], v[116:119]
	v_mfma_f32_16x16x32_bf16 v[112:115], v[182:185], v[190:193], v[112:115]
	v_mfma_f32_16x16x32_bf16 v[100:103], v[174:177], v[202:205], v[100:103]
	v_mfma_f32_16x16x32_bf16 v[96:99], v[182:185], v[202:205], v[96:99]
	v_mfma_f32_16x16x32_bf16 v[84:87], v[174:177], v[210:213], v[84:87]
	v_mfma_f32_16x16x32_bf16 v[80:83], v[182:185], v[210:213], v[80:83]
	v_mfma_f32_16x16x32_bf16 v[68:71], v[174:177], v[218:221], v[68:71]
	v_mfma_f32_16x16x32_bf16 v[64:67], v[182:185], v[218:221], v[64:67]
	v_mfma_f32_16x16x32_bf16 v[116:119], v[178:181], v[194:197], v[116:119]
	v_mfma_f32_16x16x32_bf16 v[112:115], v[186:189], v[194:197], v[112:115]
	v_mfma_f32_16x16x32_bf16 v[100:103], v[178:181], v[206:209], v[100:103]
	v_mfma_f32_16x16x32_bf16 v[96:99], v[186:189], v[206:209], v[96:99]
	v_mfma_f32_16x16x32_bf16 v[84:87], v[178:181], v[214:217], v[84:87]
	v_mfma_f32_16x16x32_bf16 v[80:83], v[186:189], v[214:217], v[80:83]
	v_mfma_f32_16x16x32_bf16 v[68:71], v[178:181], v[222:225], v[68:71]
	v_mfma_f32_16x16x32_bf16 v[64:67], v[186:189], v[222:225], v[64:67]
	s_barrier
; #define PG8_STAGE(bufoff, gbase, voff) do { _Pragma("unroll") for (int _i = 0; _i < 2; ++_i) \
;         __builtin_amdgcn_global_load_lds((const unsigned*)((const char*)(gbase) + (voff)[_i]), (PG8_LAS unsigned*)(lds + (bufoff) + ldsw + _i * 8192), 16, 0, 0); } while (0)
; #define PG8_LDA(dst, b, h) do { _Pragma("unroll") for (int m = 0; m < 4; ++m) _Pragma("unroll") for (int k = 0; k < 2; ++k) dst[m][k] = *(const PG8_LAS bf16x8*)(lds + PG8_SA(b, h) + aoff + m * 2048 + k * 1024); } while (0)
; #define PG8_LDB(dst, b, h) do { _Pragma("unroll") for (int n = 0; n < 2; ++n) _Pragma("unroll") for (int k = 0; k < 2; ++k) dst[n][k] = *(const PG8_LAS bf16x8*)(lds + PG8_SB(b, h) + boff + n * 2048 + k * 1024); } while (0)
; template <class Epi, class Sched, bool ALIGN_EPI = false, bool SP2 = false>
; __device__ __forceinline__ void gemm_phase(PG8_LAS unsigned char* lds, const Gemm g, const Sched& S, const Epi& E) {
;     ...
;         for (int t = 0; t < nt; t += 2) {
;             const bool last = (t == nt - 2);
;             const char* a1 = cA + (size_t)(t + 1) * kstep;
;             const char* a2 = last ? nA : cA + (size_t)(t + 2) * kstep; const char* b2 = last ? nB : cB + (size_t)(t + 2) * kstep;
;             const char* a3 = a2 + kstep; const char* b3 = b2 + kstep;
;             if (last && has_next) S.a_ready(nxt);
;             if constexpr (SP2) {
;             PG8_LDB(B0, 0, 0); PG8_LDB(B1, 0, 1); PG8_SCHED; PG8_LDA(At, 0, 0); PG8_STAGE(PG8_SA(1, 1), a1 + hstep, voffA);
;             PG8_WAIT_V(8); PG8_WAIT_L(0); PG8_BAR; PG8_MMA(0, 0, At, B0); PG8_MMA(0, 1, At, B1); PG8_BAR; PG8_SCHED;
;             PG8_LDA(At, 0, 1); PG8_STAGE(PG8_SB(0, 0), b2, voffB); PG8_STAGE(PG8_SB(0, 1), b2 + hstep, voffB); PG8_STAGE(PG8_SA(0, 0), a2, voffA);
;             PG8_WAIT_V(8); PG8_WAIT_L(0); PG8_BAR; PG8_MMA(1, 0, At, B0); PG8_MMA(1, 1, At, B1); PG8_BAR; PG8_SCHED;
;             PG8_LDB(B0, 1, 0); PG8_LDB(B1, 1, 1); PG8_SCHED; PG8_LDA(At, 1, 0); PG8_STAGE(PG8_SA(0, 1), a2 + hstep, voffA);
;             PG8_WAIT_V(8); PG8_WAIT_L(0); PG8_BAR; PG8_MMA(0, 0, At, B0); PG8_MMA(0, 1, At, B1); PG8_BAR; PG8_SCHED;
;             PG8_LDA(At, 1, 1); PG8_STAGE(PG8_SB(1, 0), b3, voffB); PG8_STAGE(PG8_SB(1, 1), b3 + hstep, voffB); PG8_STAGE(PG8_SA(1, 0), a3, voffA);
;             PG8_WAIT_V(8); PG8_WAIT_L(0); PG8_BAR; PG8_MMA(1, 0, At, B0); PG8_MMA(1, 1, At, B1); PG8_BAR; PG8_SCHED;
	s_add_i32 s16, s16, s49
	v_lshl_add_u64 v[198:199], v[198:199], 0, s[42:43]
	s_mov_b32 m0, s16
	ds_read_b128 v[190:193], v168 offset:49152
	ds_read_b128 v[194:197], v168 offset:50176
	ds_read_b128 v[202:205], v168 offset:51200
	ds_read_b128 v[206:209], v168 offset:52224
	ds_read_b128 v[210:213], v168 offset:53248
	ds_read_b128 v[214:217], v168 offset:54272
	ds_read_b128 v[218:221], v168 offset:55296
	ds_read_b128 v[222:225], v168 offset:56320
	global_load_lds_dwordx4 v[198:199], off
	v_lshl_add_u64 v[198:199], v[226:227], 0, s[42:43]
	s_add_i32 m0, s16, 0x2000
	s_add_i32 s16, s17, s49
	global_load_lds_dwordx4 v[198:199], off
	v_lshl_add_u64 v[198:199], v[228:229], 0, s[42:43]
	s_mov_b32 m0, s16
	s_nop 0
	global_load_lds_dwordx4 v[198:199], off
	v_lshl_add_u64 v[198:199], v[230:231], 0, s[42:43]
	s_add_i32 m0, s16, 0x2000
	s_nop 0
	global_load_lds_dwordx4 v[198:199], off
	v_lshl_add_u64 v[198:199], v[232:233], 0, s[42:43]
	s_mov_b32 m0, s72
	s_nop 0
	global_load_lds_dwordx4 v[198:199], off
	v_lshl_add_u64 v[198:199], v[236:237], 0, s[42:43]
	s_mov_b32 m0, s73
	s_nop 0
	global_load_lds_dwordx4 v[198:199], off
	s_waitcnt vmcnt(8)
	s_waitcnt lgkmcnt(0)
	s_barrier
	s_waitcnt lgkmcnt(0)
	v_mfma_f32_16x16x32_bf16 v[60:63], v[128:131], v[190:193], v[60:63]
	v_mfma_f32_16x16x32_bf16 v[56:59], v[160:163], v[190:193], v[56:59]
	v_mfma_f32_16x16x32_bf16 v[44:47], v[128:131], v[202:205], v[44:47]
	v_mfma_f32_16x16x32_bf16 v[40:43], v[160:163], v[202:205], v[40:43]
	v_mfma_f32_16x16x32_bf16 v[28:31], v[128:131], v[210:213], v[28:31]
	v_mfma_f32_16x16x32_bf16 v[24:27], v[160:163], v[210:213], v[24:27]
	v_mfma_f32_16x16x32_bf16 v[12:15], v[128:131], v[218:221], v[12:15]
	v_mfma_f32_16x16x32_bf16 v[8:11], v[160:163], v[218:221], v[8:11]
	v_mfma_f32_16x16x32_bf16 v[60:63], v[156:159], v[194:197], v[60:63]
	v_mfma_f32_16x16x32_bf16 v[56:59], v[170:173], v[194:197], v[56:59]
	v_mfma_f32_16x16x32_bf16 v[44:47], v[156:159], v[206:209], v[44:47]
	v_mfma_f32_16x16x32_bf16 v[40:43], v[170:173], v[206:209], v[40:43]
	v_mfma_f32_16x16x32_bf16 v[28:31], v[156:159], v[214:217], v[28:31]
	v_mfma_f32_16x16x32_bf16 v[24:27], v[170:173], v[214:217], v[24:27]
	v_mfma_f32_16x16x32_bf16 v[12:15], v[156:159], v[222:225], v[12:15]
	v_mfma_f32_16x16x32_bf16 v[8:11], v[170:173], v[222:225], v[8:11]
	v_mfma_f32_16x16x32_bf16 v[52:55], v[174:177], v[190:193], v[52:55]
	v_mfma_f32_16x16x32_bf16 v[48:51], v[182:185], v[190:193], v[48:51]
	v_mfma_f32_16x16x32_bf16 v[36:39], v[174:177], v[202:205], v[36:39]
	v_mfma_f32_16x16x32_bf16 v[32:35], v[182:185], v[202:205], v[32:35]
	v_mfma_f32_16x16x32_bf16 v[20:23], v[174:177], v[210:213], v[20:23]
	v_mfma_f32_16x16x32_bf16 v[16:19], v[182:185], v[210:213], v[16:19]
	v_mfma_f32_16x16x32_bf16 v[4:7], v[174:177], v[218:221], v[4:7]
	v_mfma_f32_16x16x32_bf16 v[0:3], v[182:185], v[218:221], v[0:3]
	v_mfma_f32_16x16x32_bf16 v[52:55], v[178:181], v[194:197], v[52:55]
	v_mfma_f32_16x16x32_bf16 v[48:51], v[186:189], v[194:197], v[48:51]
	v_mfma_f32_16x16x32_bf16 v[36:39], v[178:181], v[206:209], v[36:39]
	v_mfma_f32_16x16x32_bf16 v[32:35], v[186:189], v[206:209], v[32:35]
	v_mfma_f32_16x16x32_bf16 v[20:23], v[178:181], v[214:217], v[20:23]
	v_mfma_f32_16x16x32_bf16 v[16:19], v[186:189], v[214:217], v[16:19]
	v_mfma_f32_16x16x32_bf16 v[4:7], v[178:181], v[222:225], v[4:7]
	v_mfma_f32_16x16x32_bf16 v[0:3], v[186:189], v[222:225], v[0:3]
	s_barrier
	s_add_u32 s58, s58, 0x100
	s_addc_u32 s59, s59, 0
	s_add_u32 s95, s95, 0x100
	s_addc_u32 s96, s96, 0
	s_cmp_ge_i32 s97, s74
	s_mov_b32 s60, s97
	s_cbranch_scc1 .LBB0_536
.LBB0_535:
	ds_read_b128 v[128:131], v166
	ds_read_b128 v[156:159], v166 offset:1024
	ds_read_b128 v[160:163], v166 offset:2048
	ds_read_b128 v[170:173], v166 offset:3072
	ds_read_b128 v[174:177], v167
	ds_read_b128 v[178:181], v167 offset:1024
	ds_read_b128 v[182:185], v167 offset:2048
	ds_read_b128 v[186:189], v167 offset:3072
	s_add_i32 s97, s60, 2
	s_add_u32 s16, s58, 0x80
	s_addc_u32 s17, s59, 0
	s_cmp_eq_u32 s76, s60
	s_cselect_b32 s60, s0, s16
	s_cselect_b32 s61, s1, s17
	s_cselect_b32 vcc_hi, s57, s96
	s_cselect_b32 vcc_lo, s56, s95
	v_lshl_add_u64 v[198:199], s[58:59], 0, v[148:149]
	s_add_i32 m0, s62, 0xc000
	ds_read_b128 v[190:193], v168
	ds_read_b128 v[194:197], v168 offset:1024
	ds_read_b128 v[202:205], v168 offset:2048
	ds_read_b128 v[206:209], v168 offset:3072
	ds_read_b128 v[210:213], v168 offset:4096
	ds_read_b128 v[214:217], v168 offset:5120
	ds_read_b128 v[218:221], v168 offset:6144
	ds_read_b128 v[222:225], v168 offset:7168
	global_load_lds_dwordx4 v[198:199], off
	v_lshl_add_u64 v[198:199], s[58:59], 0, v[150:151]
	s_add_i32 m0, s62, 0xe000
	s_nop 0
	global_load_lds_dwordx4 v[198:199], off
	s_waitcnt vmcnt(8)
	s_waitcnt lgkmcnt(0)
	s_barrier
; #define PG8_STAGE(bufoff, gbase, voff) do { _Pragma("unroll") for (int _i = 0; _i < 2; ++_i) \
;         __builtin_amdgcn_global_load_lds((const unsigned*)((const char*)(gbase) + (voff)[_i]), (PG8_LAS unsigned*)(lds + (bufoff) + ldsw + _i * 8192), 16, 0, 0); } while (0)
; #define PG8_LDA(dst, b, h) do { _Pragma("unroll") for (int m = 0; m < 4; ++m) _Pragma("unroll") for (int k = 0; k < 2; ++k) dst[m][k] = *(const PG8_LAS bf16x8*)(lds + PG8_SA(b, h) + aoff + m * 2048 + k * 1024); } while (0)
; #define PG8_LDB(dst, b, h) do { _Pragma("unroll") for (int n = 0; n < 2; ++n) _Pragma("unroll") for (int k = 0; k < 2; ++k) dst[n][k] = *(const PG8_LAS bf16x8*)(lds + PG8_SB(b, h) + boff + n * 2048 + k * 1024); } while (0)
; #define PG8_MMA(ai, bj, At, Bt) do { __builtin_amdgcn_s_setprio(1); _Pragma("unroll") for (int m = 0; m < 4; ++m) _Pragma("unroll") for (int n = 0; n < 2; ++n) _Pragma("unroll") for (int k = 0; k < 2; ++k) \
;         acc[ai][bj][m][n] = __builtin_amdgcn_mfma_f32_16x16x32_bf16(Bt[n][k], At[m][k], acc[ai][bj][m][n], 0, 0, 0); __builtin_amdgcn_s_setprio(0); } while (0)
; #define PG8_WAIT_V(n) asm volatile("s_waitcnt vmcnt(" #n ")" ::: "memory")
; #define PG8_WAIT_L(n) asm volatile("s_waitcnt lgkmcnt(" #n ")" ::: "memory")
; #define PG8_BAR __builtin_amdgcn_s_barrier()
; #define PG8_SCHED __builtin_amdgcn_sched_barrier(0)
; template <class Epi, class Sched, bool ALIGN_EPI = false, bool SP2 = false>
; __device__ __forceinline__ void gemm_phase(PG8_LAS unsigned char* lds, const Gemm g, const Sched& S, const Epi& E) {
;     ...
;             if constexpr (SP2) {
;             PG8_LDB(B0, 0, 0); PG8_LDB(B1, 0, 1); PG8_SCHED; PG8_LDA(At, 0, 0); PG8_STAGE(PG8_SA(1, 1), a1 + hstep, voffA);
;             PG8_WAIT_V(8); PG8_WAIT_L(0); PG8_BAR; PG8_MMA(0, 0, At, B0); PG8_MMA(0, 1, At, B1); PG8_BAR; PG8_SCHED;
;             PG8_LDA(At, 0, 1); PG8_STAGE(PG8_SB(0, 0), b2, voffB); PG8_STAGE(PG8_SB(0, 1), b2 + hstep, voffB); PG8_STAGE(PG8_SA(0, 0), a2, voffA);
;             PG8_WAIT_V(8); PG8_WAIT_L(0); PG8_BAR; PG8_MMA(1, 0, At, B0); PG8_MMA(1, 1, At, B1); PG8_BAR; PG8_SCHED;
	s_waitcnt lgkmcnt(0)
	v_mfma_f32_16x16x32_bf16 v[120:123], v[128:131], v[190:193], v[120:123]
	v_mfma_f32_16x16x32_bf16 v[124:127], v[160:163], v[190:193], v[124:127]
	v_mfma_f32_16x16x32_bf16 v[108:111], v[128:131], v[202:205], v[108:111]
	v_mfma_f32_16x16x32_bf16 v[104:107], v[160:163], v[202:205], v[104:107]
	v_mfma_f32_16x16x32_bf16 v[92:95], v[128:131], v[210:213], v[92:95]
	v_mfma_f32_16x16x32_bf16 v[88:91], v[160:163], v[210:213], v[88:91]
	v_mfma_f32_16x16x32_bf16 v[76:79], v[128:131], v[218:221], v[76:79]
	v_mfma_f32_16x16x32_bf16 v[72:75], v[160:163], v[218:221], v[72:75]
	v_mfma_f32_16x16x32_bf16 v[120:123], v[156:159], v[194:197], v[120:123]
	v_mfma_f32_16x16x32_bf16 v[124:127], v[170:173], v[194:197], v[124:127]
	v_mfma_f32_16x16x32_bf16 v[108:111], v[156:159], v[206:209], v[108:111]
	v_mfma_f32_16x16x32_bf16 v[104:107], v[170:173], v[206:209], v[104:107]
	v_mfma_f32_16x16x32_bf16 v[92:95], v[156:159], v[214:217], v[92:95]
	v_mfma_f32_16x16x32_bf16 v[88:91], v[170:173], v[214:217], v[88:91]
	v_mfma_f32_16x16x32_bf16 v[76:79], v[156:159], v[222:225], v[76:79]
	v_mfma_f32_16x16x32_bf16 v[72:75], v[170:173], v[222:225], v[72:75]
	v_mfma_f32_16x16x32_bf16 v[116:119], v[174:177], v[190:193], v[116:119]
	v_mfma_f32_16x16x32_bf16 v[112:115], v[182:185], v[190:193], v[112:115]
	v_mfma_f32_16x16x32_bf16 v[100:103], v[174:177], v[202:205], v[100:103]
	v_mfma_f32_16x16x32_bf16 v[96:99], v[182:185], v[202:205], v[96:99]
	v_mfma_f32_16x16x32_bf16 v[84:87], v[174:177], v[210:213], v[84:87]
	v_mfma_f32_16x16x32_bf16 v[80:83], v[182:185], v[210:213], v[80:83]
	v_mfma_f32_16x16x32_bf16 v[68:71], v[174:177], v[218:221], v[68:71]
	v_mfma_f32_16x16x32_bf16 v[64:67], v[182:185], v[218:221], v[64:67]
	v_mfma_f32_16x16x32_bf16 v[116:119], v[178:181], v[194:197], v[116:119]
	v_mfma_f32_16x16x32_bf16 v[112:115], v[186:189], v[194:197], v[112:115]
	v_mfma_f32_16x16x32_bf16 v[100:103], v[178:181], v[206:209], v[100:103]
	v_mfma_f32_16x16x32_bf16 v[96:99], v[186:189], v[206:209], v[96:99]
	v_mfma_f32_16x16x32_bf16 v[84:87], v[178:181], v[214:217], v[84:87]
	v_mfma_f32_16x16x32_bf16 v[80:83], v[186:189], v[214:217], v[80:83]
	v_mfma_f32_16x16x32_bf16 v[68:71], v[178:181], v[222:225], v[68:71]
	v_mfma_f32_16x16x32_bf16 v[64:67], v[186:189], v[222:225], v[64:67]
	s_barrier
	s_add_i32 s16, s79, s49
	v_lshl_add_u64 v[198:199], vcc, 0, v[134:135]
	s_mov_b32 m0, s16
	ds_read_b128 v[190:193], v168 offset:16384
	ds_read_b128 v[194:197], v168 offset:17408
	ds_read_b128 v[202:205], v168 offset:18432
	ds_read_b128 v[206:209], v168 offset:19456
	ds_read_b128 v[210:213], v168 offset:20480
	ds_read_b128 v[214:217], v168 offset:21504
	ds_read_b128 v[218:221], v168 offset:22528
	ds_read_b128 v[222:225], v168 offset:23552
	global_load_lds_dwordx4 v[198:199], off
	s_add_i32 m0, s16, 0x2000
	v_lshl_add_u64 v[226:227], vcc, 0, v[138:139]
	s_add_u32 vcc_lo, vcc_lo, s8
	s_addc_u32 vcc_hi, vcc_hi, s9
	s_add_i32 s16, s80, s49
	global_load_lds_dwordx4 v[226:227], off
	v_lshl_add_u64 v[228:229], vcc, 0, v[134:135]
	s_mov_b32 m0, s16
	v_lshl_add_u64 v[230:231], vcc, 0, v[138:139]
	global_load_lds_dwordx4 v[228:229], off
	s_add_i32 m0, s16, 0x2000
	v_lshl_add_u64 v[232:233], s[60:61], 0, v[132:133]
	global_load_lds_dwordx4 v[230:231], off
	s_mov_b32 m0, s62
	v_lshl_add_u64 v[236:237], s[60:61], 0, v[136:137]
	global_load_lds_dwordx4 v[232:233], off
	s_mov_b32 m0, s63
	s_nop 0
	global_load_lds_dwordx4 v[236:237], off
	s_waitcnt vmcnt(8)
	s_waitcnt lgkmcnt(0)
	s_barrier
	s_waitcnt lgkmcnt(0)
	v_mfma_f32_16x16x32_bf16 v[60:63], v[128:131], v[190:193], v[60:63]
	v_mfma_f32_16x16x32_bf16 v[56:59], v[160:163], v[190:193], v[56:59]
	v_mfma_f32_16x16x32_bf16 v[44:47], v[128:131], v[202:205], v[44:47]
	v_mfma_f32_16x16x32_bf16 v[40:43], v[160:163], v[202:205], v[40:43]
	v_mfma_f32_16x16x32_bf16 v[28:31], v[128:131], v[210:213], v[28:31]
	v_mfma_f32_16x16x32_bf16 v[24:27], v[160:163], v[210:213], v[24:27]
	v_mfma_f32_16x16x32_bf16 v[12:15], v[128:131], v[218:221], v[12:15]
	v_mfma_f32_16x16x32_bf16 v[8:11], v[160:163], v[218:221], v[8:11]
	v_mfma_f32_16x16x32_bf16 v[60:63], v[156:159], v[194:197], v[60:63]
	v_mfma_f32_16x16x32_bf16 v[56:59], v[170:173], v[194:197], v[56:59]
	v_mfma_f32_16x16x32_bf16 v[44:47], v[156:159], v[206:209], v[44:47]
	v_mfma_f32_16x16x32_bf16 v[40:43], v[170:173], v[206:209], v[40:43]
	v_mfma_f32_16x16x32_bf16 v[28:31], v[156:159], v[214:217], v[28:31]
	v_mfma_f32_16x16x32_bf16 v[24:27], v[170:173], v[214:217], v[24:27]
	v_mfma_f32_16x16x32_bf16 v[12:15], v[156:159], v[222:225], v[12:15]
	v_mfma_f32_16x16x32_bf16 v[8:11], v[170:173], v[222:225], v[8:11]
	v_mfma_f32_16x16x32_bf16 v[52:55], v[174:177], v[190:193], v[52:55]
	v_mfma_f32_16x16x32_bf16 v[48:51], v[182:185], v[190:193], v[48:51]
	v_mfma_f32_16x16x32_bf16 v[36:39], v[174:177], v[202:205], v[36:39]
	v_mfma_f32_16x16x32_bf16 v[32:35], v[182:185], v[202:205], v[32:35]
	v_mfma_f32_16x16x32_bf16 v[20:23], v[174:177], v[210:213], v[20:23]
	v_mfma_f32_16x16x32_bf16 v[16:19], v[182:185], v[210:213], v[16:19]
	v_mfma_f32_16x16x32_bf16 v[4:7], v[174:177], v[218:221], v[4:7]
	v_mfma_f32_16x16x32_bf16 v[0:3], v[182:185], v[218:221], v[0:3]
	v_mfma_f32_16x16x32_bf16 v[52:55], v[178:181], v[194:197], v[52:55]
	v_mfma_f32_16x16x32_bf16 v[48:51], v[186:189], v[194:197], v[48:51]
	v_mfma_f32_16x16x32_bf16 v[36:39], v[178:181], v[206:209], v[36:39]
	v_mfma_f32_16x16x32_bf16 v[32:35], v[186:189], v[206:209], v[32:35]
	v_mfma_f32_16x16x32_bf16 v[20:23], v[178:181], v[214:217], v[20:23]
	v_mfma_f32_16x16x32_bf16 v[16:19], v[186:189], v[214:217], v[16:19]
	v_mfma_f32_16x16x32_bf16 v[4:7], v[178:181], v[222:225], v[4:7]
	v_mfma_f32_16x16x32_bf16 v[0:3], v[186:189], v[222:225], v[0:3]
	s_barrier
; #define PG8_STAGE(bufoff, gbase, voff) do { _Pragma("unroll") for (int _i = 0; _i < 2; ++_i) \
;         __builtin_amdgcn_global_load_lds((const unsigned*)((const char*)(gbase) + (voff)[_i]), (PG8_LAS unsigned*)(lds + (bufoff) + ldsw + _i * 8192), 16, 0, 0); } while (0)
; #define PG8_LDA(dst, b, h) do { _Pragma("unroll") for (int m = 0; m < 4; ++m) _Pragma("unroll") for (int k = 0; k < 2; ++k) dst[m][k] = *(const PG8_LAS bf16x8*)(lds + PG8_SA(b, h) + aoff + m * 2048 + k * 1024); } while (0)
; #define PG8_LDB(dst, b, h) do { _Pragma("unroll") for (int n = 0; n < 2; ++n) _Pragma("unroll") for (int k = 0; k < 2; ++k) dst[n][k] = *(const PG8_LAS bf16x8*)(lds + PG8_SB(b, h) + boff + n * 2048 + k * 1024); } while (0)
; #define PG8_MMA(ai, bj, At, Bt) do { __builtin_amdgcn_s_setprio(1); _Pragma("unroll") for (int m = 0; m < 4; ++m) _Pragma("unroll") for (int n = 0; n < 2; ++n) _Pragma("unroll") for (int k = 0; k < 2; ++k) \
;         acc[ai][bj][m][n] = __builtin_amdgcn_mfma_f32_16x16x32_bf16(Bt[n][k], At[m][k], acc[ai][bj][m][n], 0, 0, 0); __builtin_amdgcn_s_setprio(0); } while (0)
; #define PG8_WAIT_V(n) asm volatile("s_waitcnt vmcnt(" #n ")" ::: "memory")
; #define PG8_WAIT_L(n) asm volatile("s_waitcnt lgkmcnt(" #n ")" ::: "memory")
; #define PG8_BAR __builtin_amdgcn_s_barrier()
; #define PG8_SCHED __builtin_amdgcn_sched_barrier(0)
; template <class Epi, class Sched, bool ALIGN_EPI = false, bool SP2 = false>
; __device__ __forceinline__ void gemm_phase(PG8_LAS unsigned char* lds, const Gemm g, const Sched& S, const Epi& E) {
;     ...
;             PG8_WAIT_V(8); PG8_WAIT_L(0); PG8_BAR; PG8_MMA(1, 0, At, B0); PG8_MMA(1, 1, At, B1); PG8_BAR; PG8_SCHED;
;             PG8_LDB(B0, 1, 0); PG8_LDB(B1, 1, 1); PG8_SCHED; PG8_LDA(At, 1, 0); PG8_STAGE(PG8_SA(0, 1), a2 + hstep, voffA);
;             PG8_WAIT_V(8); PG8_WAIT_L(0); PG8_BAR; PG8_MMA(0, 0, At, B0); PG8_MMA(0, 1, At, B1); PG8_BAR; PG8_SCHED;
;             PG8_LDA(At, 1, 1); PG8_STAGE(PG8_SB(1, 0), b3, voffB); PG8_STAGE(PG8_SB(1, 1), b3 + hstep, voffB); PG8_STAGE(PG8_SA(1, 0), a3, voffA);
;             PG8_WAIT_V(8); PG8_WAIT_L(0); PG8_BAR; PG8_MMA(1, 0, At, B0); PG8_MMA(1, 1, At, B1); PG8_BAR; PG8_SCHED;
	s_add_i32 s16, 0, 0x18000
	v_add_u32_e32 v140, s16, v165
	s_add_i32 s17, 0, 0x1c000
	ds_read_b128 v[128:131], v140
	ds_read_b128 v[156:159], v140 offset:1024
	ds_read_b128 v[160:163], v140 offset:2048
	ds_read_b128 v[170:173], v140 offset:3072
	v_add_u32_e32 v140, s17, v165
	ds_read_b128 v[174:177], v140
	ds_read_b128 v[178:181], v140 offset:1024
	ds_read_b128 v[182:185], v140 offset:2048
	ds_read_b128 v[186:189], v140 offset:3072
	s_add_u32 s60, s60, s8
	s_addc_u32 s61, s61, s9
	s_mov_b32 m0, s70
	v_lshl_add_u64 v[238:239], s[60:61], 0, v[132:133]
	ds_read_b128 v[190:193], v168 offset:32768
	ds_read_b128 v[194:197], v168 offset:33792
	ds_read_b128 v[202:205], v168 offset:34816
	ds_read_b128 v[206:209], v168 offset:35840
	ds_read_b128 v[210:213], v168 offset:36864
	ds_read_b128 v[214:217], v168 offset:37888
	ds_read_b128 v[218:221], v168 offset:38912
	ds_read_b128 v[222:225], v168 offset:39936
	global_load_lds_dwordx4 v[238:239], off
	v_lshl_add_u64 v[238:239], s[60:61], 0, v[136:137]
	s_mov_b32 m0, s71
	s_nop 0
	global_load_lds_dwordx4 v[238:239], off
	s_waitcnt vmcnt(8)
	s_waitcnt lgkmcnt(0)
	s_barrier
	s_waitcnt lgkmcnt(0)
	v_mfma_f32_16x16x32_bf16 v[120:123], v[128:131], v[190:193], v[120:123]
	v_mfma_f32_16x16x32_bf16 v[124:127], v[160:163], v[190:193], v[124:127]
	v_mfma_f32_16x16x32_bf16 v[108:111], v[128:131], v[202:205], v[108:111]
	v_mfma_f32_16x16x32_bf16 v[104:107], v[160:163], v[202:205], v[104:107]
	v_mfma_f32_16x16x32_bf16 v[92:95], v[128:131], v[210:213], v[92:95]
	v_mfma_f32_16x16x32_bf16 v[88:91], v[160:163], v[210:213], v[88:91]
	v_mfma_f32_16x16x32_bf16 v[76:79], v[128:131], v[218:221], v[76:79]
	v_mfma_f32_16x16x32_bf16 v[72:75], v[160:163], v[218:221], v[72:75]
	v_mfma_f32_16x16x32_bf16 v[120:123], v[156:159], v[194:197], v[120:123]
	v_mfma_f32_16x16x32_bf16 v[124:127], v[170:173], v[194:197], v[124:127]
	v_mfma_f32_16x16x32_bf16 v[108:111], v[156:159], v[206:209], v[108:111]
	v_mfma_f32_16x16x32_bf16 v[104:107], v[170:173], v[206:209], v[104:107]
	v_mfma_f32_16x16x32_bf16 v[92:95], v[156:159], v[214:217], v[92:95]
	v_mfma_f32_16x16x32_bf16 v[88:91], v[170:173], v[214:217], v[88:91]
	v_mfma_f32_16x16x32_bf16 v[76:79], v[156:159], v[222:225], v[76:79]
	v_mfma_f32_16x16x32_bf16 v[72:75], v[170:173], v[222:225], v[72:75]
	v_mfma_f32_16x16x32_bf16 v[116:119], v[174:177], v[190:193], v[116:119]
	v_mfma_f32_16x16x32_bf16 v[112:115], v[182:185], v[190:193], v[112:115]
	v_mfma_f32_16x16x32_bf16 v[100:103], v[174:177], v[202:205], v[100:103]
	v_mfma_f32_16x16x32_bf16 v[96:99], v[182:185], v[202:205], v[96:99]
	v_mfma_f32_16x16x32_bf16 v[84:87], v[174:177], v[210:213], v[84:87]
	v_mfma_f32_16x16x32_bf16 v[80:83], v[182:185], v[210:213], v[80:83]
	v_mfma_f32_16x16x32_bf16 v[68:71], v[174:177], v[218:221], v[68:71]
	v_mfma_f32_16x16x32_bf16 v[64:67], v[182:185], v[218:221], v[64:67]
	v_mfma_f32_16x16x32_bf16 v[116:119], v[178:181], v[194:197], v[116:119]
	v_mfma_f32_16x16x32_bf16 v[112:115], v[186:189], v[194:197], v[112:115]
	v_mfma_f32_16x16x32_bf16 v[100:103], v[178:181], v[206:209], v[100:103]
	v_mfma_f32_16x16x32_bf16 v[96:99], v[186:189], v[206:209], v[96:99]
	v_mfma_f32_16x16x32_bf16 v[84:87], v[178:181], v[214:217], v[84:87]
	v_mfma_f32_16x16x32_bf16 v[80:83], v[186:189], v[214:217], v[80:83]
	v_mfma_f32_16x16x32_bf16 v[68:71], v[178:181], v[222:225], v[68:71]
	v_mfma_f32_16x16x32_bf16 v[64:67], v[186:189], v[222:225], v[64:67]
	s_barrier
	s_add_i32 s16, s16, s49
	v_lshl_add_u64 v[198:199], v[198:199], 0, s[42:43]
	s_mov_b32 m0, s16
	ds_read_b128 v[190:193], v168 offset:49152
	ds_read_b128 v[194:197], v168 offset:50176
	ds_read_b128 v[202:205], v168 offset:51200
	ds_read_b128 v[206:209], v168 offset:52224
	ds_read_b128 v[210:213], v168 offset:53248
	ds_read_b128 v[214:217], v168 offset:54272
	ds_read_b128 v[218:221], v168 offset:55296
	ds_read_b128 v[222:225], v168 offset:56320
	global_load_lds_dwordx4 v[198:199], off
	v_lshl_add_u64 v[198:199], v[226:227], 0, s[42:43]
	s_add_i32 m0, s16, 0x2000
	s_add_i32 s16, s17, s49
	global_load_lds_dwordx4 v[198:199], off
	v_lshl_add_u64 v[198:199], v[228:229], 0, s[42:43]
	s_mov_b32 m0, s16
	s_nop 0
	global_load_lds_dwordx4 v[198:199], off
	v_lshl_add_u64 v[198:199], v[230:231], 0, s[42:43]
	s_add_i32 m0, s16, 0x2000
	s_nop 0
	global_load_lds_dwordx4 v[198:199], off
	v_lshl_add_u64 v[198:199], v[232:233], 0, s[42:43]
	s_mov_b32 m0, s72
	s_nop 0
	global_load_lds_dwordx4 v[198:199], off
	v_lshl_add_u64 v[198:199], v[236:237], 0, s[42:43]
	s_mov_b32 m0, s73
	s_nop 0
	global_load_lds_dwordx4 v[198:199], off
	s_waitcnt vmcnt(8)
	s_waitcnt lgkmcnt(0)
	s_barrier
	s_waitcnt lgkmcnt(0)
	v_mfma_f32_16x16x32_bf16 v[60:63], v[128:131], v[190:193], v[60:63]
	v_mfma_f32_16x16x32_bf16 v[56:59], v[160:163], v[190:193], v[56:59]
	v_mfma_f32_16x16x32_bf16 v[44:47], v[128:131], v[202:205], v[44:47]
	v_mfma_f32_16x16x32_bf16 v[40:43], v[160:163], v[202:205], v[40:43]
	v_mfma_f32_16x16x32_bf16 v[28:31], v[128:131], v[210:213], v[28:31]
	v_mfma_f32_16x16x32_bf16 v[24:27], v[160:163], v[210:213], v[24:27]
	v_mfma_f32_16x16x32_bf16 v[12:15], v[128:131], v[218:221], v[12:15]
	v_mfma_f32_16x16x32_bf16 v[8:11], v[160:163], v[218:221], v[8:11]
	v_mfma_f32_16x16x32_bf16 v[60:63], v[156:159], v[194:197], v[60:63]
	v_mfma_f32_16x16x32_bf16 v[56:59], v[170:173], v[194:197], v[56:59]
	v_mfma_f32_16x16x32_bf16 v[44:47], v[156:159], v[206:209], v[44:47]
	v_mfma_f32_16x16x32_bf16 v[40:43], v[170:173], v[206:209], v[40:43]
	v_mfma_f32_16x16x32_bf16 v[28:31], v[156:159], v[214:217], v[28:31]
	v_mfma_f32_16x16x32_bf16 v[24:27], v[170:173], v[214:217], v[24:27]
	v_mfma_f32_16x16x32_bf16 v[12:15], v[156:159], v[222:225], v[12:15]
	v_mfma_f32_16x16x32_bf16 v[8:11], v[170:173], v[222:225], v[8:11]
	v_mfma_f32_16x16x32_bf16 v[52:55], v[174:177], v[190:193], v[52:55]
	v_mfma_f32_16x16x32_bf16 v[48:51], v[182:185], v[190:193], v[48:51]
	v_mfma_f32_16x16x32_bf16 v[36:39], v[174:177], v[202:205], v[36:39]
	v_mfma_f32_16x16x32_bf16 v[32:35], v[182:185], v[202:205], v[32:35]
	v_mfma_f32_16x16x32_bf16 v[20:23], v[174:177], v[210:213], v[20:23]
	v_mfma_f32_16x16x32_bf16 v[16:19], v[182:185], v[210:213], v[16:19]
	v_mfma_f32_16x16x32_bf16 v[4:7], v[174:177], v[218:221], v[4:7]
	v_mfma_f32_16x16x32_bf16 v[0:3], v[182:185], v[218:221], v[0:3]
	v_mfma_f32_16x16x32_bf16 v[52:55], v[178:181], v[194:197], v[52:55]
	v_mfma_f32_16x16x32_bf16 v[48:51], v[186:189], v[194:197], v[48:51]
	v_mfma_f32_16x16x32_bf16 v[36:39], v[178:181], v[206:209], v[36:39]
	v_mfma_f32_16x16x32_bf16 v[32:35], v[186:189], v[206:209], v[32:35]
	v_mfma_f32_16x16x32_bf16 v[20:23], v[178:181], v[214:217], v[20:23]
	v_mfma_f32_16x16x32_bf16 v[16:19], v[186:189], v[214:217], v[16:19]
	v_mfma_f32_16x16x32_bf16 v[4:7], v[178:181], v[222:225], v[4:7]
	v_mfma_f32_16x16x32_bf16 v[0:3], v[186:189], v[222:225], v[0:3]
	s_barrier
	s_add_u32 s58, s58, 0x100
	s_addc_u32 s59, s59, 0
	s_add_u32 s95, s95, 0x100
	s_addc_u32 s96, s96, 0
	s_cmp_ge_i32 s97, s74
	s_mov_b32 s60, s97
	s_cbranch_scc0 .LBB0_535

; #define PG8_WAIT_V(n) asm volatile("s_waitcnt vmcnt(" #n ")" ::: "memory")
; #define PG8_BAR __builtin_amdgcn_s_barrier()
; template <class Epi, class Sched, bool ALIGN_EPI = false, bool SP2 = false>
; __device__ __forceinline__ void gemm_phase(PG8_LAS unsigned char* lds, const Gemm g, const Sched& S, const Epi& E) {
;     ...
;     PG8_WAIT_V(0);
;     if constexpr (!ALIGN_EPI) { if (wr == 0) PG8_BAR; }
;     PG8_BAR;
; __device__ __forceinline__ void xcd_barrier(const XcdBarrier& b) {
;     asm volatile("s_waitcnt vmcnt(0)" ::: "memory");
;     __syncthreads();
;     if (threadIdx.x == 0) {
;         unsigned* bar = b.bar;
;         __builtin_amdgcn_s_waitcnt(0);
;         unsigned nloc = b.st[0], nx = b.st[1];
;         if (nloc == 0u) { xcd_barrier_complete(bar, b.x, nloc, nx); b.st[0] = nloc; b.st[1] = nx; }
.LBB0_578:
	s_waitcnt vmcnt(0)
	s_waitcnt vmcnt(0) lgkmcnt(0)
	s_barrier
	s_setprio 0
	s_and_saveexec_b64 s[0:1], s[92:93]
	s_cbranch_execz .LBB0_630
	s_add_i32 s3, 0, 0x20400
	v_mov_b32_e32 v0, s3
	s_waitcnt vmcnt(0) expcnt(0) lgkmcnt(0)
	ds_read_b32 v2, v0
	s_add_i32 s3, 0, 0x20404
	v_mov_b32_e32 v0, s3
	ds_read_b32 v0, v0
	s_waitcnt lgkmcnt(1)
	v_cmp_ne_u32_e32 vcc, 0, v2
	s_cbranch_vccnz .LBB0_594
	s_add_u32 s4, s28, 0x180200
	s_addc_u32 s5, s29, 0
	s_add_u32 s8, s28, 0x180400
	s_addc_u32 s9, s29, 0
	s_add_u32 s10, s28, 0x180500
	s_addc_u32 s11, s29, 0
	s_add_u32 s12, s28, 0x180600
	s_addc_u32 s13, s29, 0
	s_add_u32 s14, s28, 0x180700
	s_addc_u32 s15, s29, 0
	s_add_u32 s42, s28, 0x180800
	s_addc_u32 s43, s29, 0
	s_add_u32 s44, s28, 0x180900
	s_addc_u32 s45, s29, 0
	s_add_u32 s46, s28, 0x180a00
	s_addc_u32 s47, s29, 0
	s_add_u32 s50, s28, 0x180b00
	s_addc_u32 s51, s29, 0
	s_add_u32 s52, s28, 0x180c00
	s_addc_u32 s53, s29, 0
	s_add_u32 s54, s28, 0x180d00
	s_addc_u32 s55, s29, 0
	s_add_u32 s56, s28, 0x180e00
	s_addc_u32 s57, s29, 0
	s_add_u32 s58, s28, 0x180f00
	s_addc_u32 s59, s29, 0
	s_add_u32 s60, s28, 0x181000
	s_addc_u32 s61, s29, 0
	s_add_u32 s62, s28, 0x181100
	s_addc_u32 s63, s29, 0
	s_add_u32 s68, s28, 0x181200
	v_readlane_b32 s3, v253, 0
	s_addc_u32 s69, s29, 0
	s_mul_i32 s3, s31, s3
	s_add_u32 s70, s28, 0x181300
	s_mul_i32 s3, s3, s30
	s_addc_u32 s71, s29, 0
	s_mov_b32 s48, 1
	v_mov_b32_e32 v16, 0
	s_branch .LBB0_582

;     __host__ __device__ bool next(int i, Unit& u) const {
;         const long L = (long)i * G + c; if (L >= nwg) return false;
;         int wgid = (int)L; { const int q = nwg / NXCD, r = nwg % NXCD, xcd = wgid % NXCD, off = wgid / NXCD; wgid = (xcd < r ? xcd * (q + 1) : r * (q + 1) + (xcd - r) * q) + off; }
;         const int nig = WGM * nN, gid = wgid / nig, fm = gid * WGM, gsz = (nM - fm) < WGM ? (nM - fm) : WGM;
;         u.pm = fm + ((wgid % nig) % gsz); u.pn = (wgid % nig) / gsz; u.sel = 0; return true;
;     __device__ bool next(int i, Unit& u) const { if (!so.next(i >> 1, u)) return false; u.sel = i & 1; return true; }
.Lprio5_skip:
	v_mov_b32_e32 v12, v201
	s_cmpk_lt_i32 s2, 0x400
	s_waitcnt lgkmcnt(0)
	s_barrier
	s_movk_i32 s0, 0x400
	v_readfirstlane_b32 s48, v12
	s_cselect_b64 s[4:5], -1, 0
	s_cmpk_gt_i32 s2, 0x3ff
	s_cbranch_scc1 .LBB0_710
	s_ashr_i32 s1, s2, 31
	s_lshr_b32 s1, s1, 29
	s_add_i32 s1, s2, s1
	s_and_b32 s3, s1, -8
	s_sub_i32 s3, s2, s3
	s_cmp_gt_i32 s3, -1
	s_cbranch_scc0 .LBB0_707
	s_lshl_b32 s8, s3, 7
	s_cbranch_execz .LBB0_708
	s_branch .LBB0_709

; #define PG8_STAGE(bufoff, gbase, voff) do { _Pragma("unroll") for (int _i = 0; _i < 2; ++_i) \
;         __builtin_amdgcn_global_load_lds((const unsigned*)((const char*)(gbase) + (voff)[_i]), (PG8_LAS unsigned*)(lds + (bufoff) + ldsw + _i * 8192), 16, 0, 0); } while (0)
; #define PG8_LDA(dst, b, h) do { _Pragma("unroll") for (int m = 0; m < 4; ++m) _Pragma("unroll") for (int k = 0; k < 2; ++k) dst[m][k] = *(const PG8_LAS bf16x8*)(lds + PG8_SA(b, h) + aoff + m * 2048 + k * 1024); } while (0)
; #define PG8_LDB(dst, b, h) do { _Pragma("unroll") for (int n = 0; n < 2; ++n) _Pragma("unroll") for (int k = 0; k < 2; ++k) dst[n][k] = *(const PG8_LAS bf16x8*)(lds + PG8_SB(b, h) + boff + n * 2048 + k * 1024); } while (0)
; #define PG8_MMA(ai, bj, At, Bt) do { __builtin_amdgcn_s_setprio(1); _Pragma("unroll") for (int m = 0; m < 4; ++m) _Pragma("unroll") for (int n = 0; n < 2; ++n) _Pragma("unroll") for (int k = 0; k < 2; ++k) \
;         acc[ai][bj][m][n] = __builtin_amdgcn_mfma_f32_16x16x32_bf16(Bt[n][k], At[m][k], acc[ai][bj][m][n], 0, 0, 0); __builtin_amdgcn_s_setprio(0); } while (0)
; #define PG8_WAIT_V(n) asm volatile("s_waitcnt vmcnt(" #n ")" ::: "memory")
; #define PG8_BAR __builtin_amdgcn_s_barrier()
; template <class Epi, class Sched, bool ALIGN_EPI = false, bool SP2 = false>
; __device__ __forceinline__ void gemm_phase(PG8_LAS unsigned char* lds, const Gemm g, const Sched& S, const Epi& E) {
;     ...
;         for (int t = 0; t < nt; t += 2) {
;             const bool last = (t == nt - 2);
;             const char* a1 = cA + (size_t)(t + 1) * kstep;
;             const char* a2 = last ? nA : cA + (size_t)(t + 2) * kstep; const char* b2 = last ? nB : cB + (size_t)(t + 2) * kstep;
;             const char* a3 = a2 + kstep; const char* b3 = b2 + kstep;
;             if (last && has_next) S.a_ready(nxt);
;             if constexpr (SP2) {
;             PG8_LDB(B0, 0, 0); PG8_LDB(B1, 0, 1); PG8_SCHED; PG8_LDA(At, 0, 0); PG8_STAGE(PG8_SA(1, 1), a1 + hstep, voffA);
;             PG8_WAIT_V(8); PG8_WAIT_L(0); PG8_BAR; PG8_MMA(0, 0, At, B0); PG8_MMA(0, 1, At, B1); PG8_BAR; PG8_SCHED;
;             PG8_LDA(At, 0, 1); PG8_STAGE(PG8_SB(0, 0), b2, voffB); PG8_STAGE(PG8_SB(0, 1), b2 + hstep, voffB); PG8_STAGE(PG8_SA(0, 0), a2, voffA);
;             PG8_WAIT_V(8); PG8_WAIT_L(0); PG8_BAR; PG8_MMA(1, 0, At, B0); PG8_MMA(1, 1, At, B1); PG8_BAR; PG8_SCHED;
.Lcz_go_728:
	s_add_u32 s6, s6, 0x80
	s_addc_u32 s7, s7, 0
	s_add_u32 s79, s52, 0x100
	s_addc_u32 s80, s53, 0
	s_mov_b32 s52, 0
	ds_read_b128 v[128:131], v169
	ds_read_b128 v[148:151], v169 offset:1024
	ds_read_b128 v[152:155], v169 offset:2048
	ds_read_b128 v[156:159], v169 offset:3072
	ds_read_b128 v[160:163], v170
	ds_read_b128 v[172:175], v170 offset:1024
	ds_read_b128 v[176:179], v170 offset:2048
	ds_read_b128 v[180:183], v170 offset:3072
	s_add_i32 s81, s52, 2
	s_add_u32 s16, s6, 0x80
	s_addc_u32 s17, s7, 0
	s_cmp_eq_u32 s69, s52
	s_cselect_b32 s52, s0, s16
	s_cselect_b32 s53, s1, s17
	s_cselect_b32 s83, s51, s80
	s_cselect_b32 s82, s50, s79
	v_lshl_add_u64 v[164:165], s[6:7], 0, v[140:141]
	s_add_i32 m0, s56, 0xc000
	ds_read_b128 v[184:187], v171
	ds_read_b128 v[188:191], v171 offset:1024
	ds_read_b128 v[192:195], v171 offset:2048
	ds_read_b128 v[196:199], v171 offset:3072
	ds_read_b128 v[202:205], v171 offset:4096
	ds_read_b128 v[206:209], v171 offset:5120
	ds_read_b128 v[210:213], v171 offset:6144
	ds_read_b128 v[214:217], v171 offset:7168
	global_load_lds_dwordx4 v[164:165], off
	v_lshl_add_u64 v[164:165], s[6:7], 0, v[142:143]
	s_add_i32 m0, s56, 0xe000
	s_nop 0
	global_load_lds_dwordx4 v[164:165], off
	s_waitcnt vmcnt(8)
	s_waitcnt lgkmcnt(0)
	s_barrier
	s_waitcnt lgkmcnt(0)
	v_mfma_f32_16x16x32_bf16 v[120:123], v[128:131], v[184:187], 0
	v_mfma_f32_16x16x32_bf16 v[124:127], v[152:155], v[184:187], 0
	v_mfma_f32_16x16x32_bf16 v[108:111], v[128:131], v[192:195], 0
	v_mfma_f32_16x16x32_bf16 v[104:107], v[152:155], v[192:195], 0
	v_mfma_f32_16x16x32_bf16 v[92:95], v[128:131], v[202:205], 0
	v_mfma_f32_16x16x32_bf16 v[88:91], v[152:155], v[202:205], 0
	v_mfma_f32_16x16x32_bf16 v[76:79], v[128:131], v[210:213], 0
	v_mfma_f32_16x16x32_bf16 v[72:75], v[152:155], v[210:213], 0
	v_mfma_f32_16x16x32_bf16 v[120:123], v[148:151], v[188:191], v[120:123]
	v_mfma_f32_16x16x32_bf16 v[124:127], v[156:159], v[188:191], v[124:127]
	v_mfma_f32_16x16x32_bf16 v[108:111], v[148:151], v[196:199], v[108:111]
	v_mfma_f32_16x16x32_bf16 v[104:107], v[156:159], v[196:199], v[104:107]
	v_mfma_f32_16x16x32_bf16 v[92:95], v[148:151], v[206:209], v[92:95]
	v_mfma_f32_16x16x32_bf16 v[88:91], v[156:159], v[206:209], v[88:91]
	v_mfma_f32_16x16x32_bf16 v[76:79], v[148:151], v[214:217], v[76:79]
	v_mfma_f32_16x16x32_bf16 v[72:75], v[156:159], v[214:217], v[72:75]
	v_mfma_f32_16x16x32_bf16 v[116:119], v[160:163], v[184:187], 0
	v_mfma_f32_16x16x32_bf16 v[112:115], v[176:179], v[184:187], 0
	v_mfma_f32_16x16x32_bf16 v[100:103], v[160:163], v[192:195], 0
	v_mfma_f32_16x16x32_bf16 v[96:99], v[176:179], v[192:195], 0
	v_mfma_f32_16x16x32_bf16 v[84:87], v[160:163], v[202:205], 0
	v_mfma_f32_16x16x32_bf16 v[80:83], v[176:179], v[202:205], 0
	v_mfma_f32_16x16x32_bf16 v[68:71], v[160:163], v[210:213], 0
	v_mfma_f32_16x16x32_bf16 v[64:67], v[176:179], v[210:213], 0
	v_mfma_f32_16x16x32_bf16 v[116:119], v[172:175], v[188:191], v[116:119]
	v_mfma_f32_16x16x32_bf16 v[112:115], v[180:183], v[188:191], v[112:115]
	v_mfma_f32_16x16x32_bf16 v[100:103], v[172:175], v[196:199], v[100:103]
	v_mfma_f32_16x16x32_bf16 v[96:99], v[180:183], v[196:199], v[96:99]
	v_mfma_f32_16x16x32_bf16 v[84:87], v[172:175], v[206:209], v[84:87]
	v_mfma_f32_16x16x32_bf16 v[80:83], v[180:183], v[206:209], v[80:83]
	v_mfma_f32_16x16x32_bf16 v[68:71], v[172:175], v[214:217], v[68:71]
	v_mfma_f32_16x16x32_bf16 v[64:67], v[180:183], v[214:217], v[64:67]
	s_barrier
	s_add_i32 s16, s71, s55
	v_lshl_add_u64 v[164:165], s[82:83], 0, v[134:135]
	s_mov_b32 m0, s16
	ds_read_b128 v[184:187], v171 offset:16384
	ds_read_b128 v[188:191], v171 offset:17408
	ds_read_b128 v[192:195], v171 offset:18432
	ds_read_b128 v[196:199], v171 offset:19456
	ds_read_b128 v[202:205], v171 offset:20480
	ds_read_b128 v[206:209], v171 offset:21504
	ds_read_b128 v[210:213], v171 offset:22528
	ds_read_b128 v[214:217], v171 offset:23552
	global_load_lds_dwordx4 v[164:165], off
	s_add_i32 m0, s16, 0x2000
	v_lshl_add_u64 v[218:219], s[82:83], 0, v[138:139]
	s_add_u32 s82, s82, s10
	s_addc_u32 s83, s83, s11
	s_add_i32 s16, s72, s55
	global_load_lds_dwordx4 v[218:219], off
	v_lshl_add_u64 v[220:221], s[82:83], 0, v[134:135]
	s_mov_b32 m0, s16
	v_lshl_add_u64 v[222:223], s[82:83], 0, v[138:139]
	global_load_lds_dwordx4 v[220:221], off
	s_add_i32 m0, s16, 0x2000
	v_lshl_add_u64 v[224:225], s[52:53], 0, v[132:133]
	global_load_lds_dwordx4 v[222:223], off
	s_mov_b32 m0, s56
	v_lshl_add_u64 v[226:227], s[52:53], 0, v[136:137]
	global_load_lds_dwordx4 v[224:225], off
	s_mov_b32 m0, s57
	s_nop 0
	global_load_lds_dwordx4 v[226:227], off
	s_waitcnt vmcnt(8)
	s_waitcnt lgkmcnt(0)
	s_barrier
; #define PG8_STAGE(bufoff, gbase, voff) do { _Pragma("unroll") for (int _i = 0; _i < 2; ++_i) \
;         __builtin_amdgcn_global_load_lds((const unsigned*)((const char*)(gbase) + (voff)[_i]), (PG8_LAS unsigned*)(lds + (bufoff) + ldsw + _i * 8192), 16, 0, 0); } while (0)
; #define PG8_LDA(dst, b, h) do { _Pragma("unroll") for (int m = 0; m < 4; ++m) _Pragma("unroll") for (int k = 0; k < 2; ++k) dst[m][k] = *(const PG8_LAS bf16x8*)(lds + PG8_SA(b, h) + aoff + m * 2048 + k * 1024); } while (0)
; #define PG8_LDB(dst, b, h) do { _Pragma("unroll") for (int n = 0; n < 2; ++n) _Pragma("unroll") for (int k = 0; k < 2; ++k) dst[n][k] = *(const PG8_LAS bf16x8*)(lds + PG8_SB(b, h) + boff + n * 2048 + k * 1024); } while (0)
; #define PG8_MMA(ai, bj, At, Bt) do { __builtin_amdgcn_s_setprio(1); _Pragma("unroll") for (int m = 0; m < 4; ++m) _Pragma("unroll") for (int n = 0; n < 2; ++n) _Pragma("unroll") for (int k = 0; k < 2; ++k) \
;         acc[ai][bj][m][n] = __builtin_amdgcn_mfma_f32_16x16x32_bf16(Bt[n][k], At[m][k], acc[ai][bj][m][n], 0, 0, 0); __builtin_amdgcn_s_setprio(0); } while (0)
; #define PG8_WAIT_V(n) asm volatile("s_waitcnt vmcnt(" #n ")" ::: "memory")
; #define PG8_WAIT_L(n) asm volatile("s_waitcnt lgkmcnt(" #n ")" ::: "memory")
; #define PG8_BAR __builtin_amdgcn_s_barrier()
; #define PG8_SCHED __builtin_amdgcn_sched_barrier(0)
; template <class Epi, class Sched, bool ALIGN_EPI = false, bool SP2 = false>
; __device__ __forceinline__ void gemm_phase(PG8_LAS unsigned char* lds, const Gemm g, const Sched& S, const Epi& E) {
;     ...
;             if constexpr (SP2) {
;             PG8_LDB(B0, 0, 0); PG8_LDB(B1, 0, 1); PG8_SCHED; PG8_LDA(At, 0, 0); PG8_STAGE(PG8_SA(1, 1), a1 + hstep, voffA);
;             PG8_WAIT_V(8); PG8_WAIT_L(0); PG8_BAR; PG8_MMA(0, 0, At, B0); PG8_MMA(0, 1, At, B1); PG8_BAR; PG8_SCHED;
;             PG8_LDA(At, 0, 1); PG8_STAGE(PG8_SB(0, 0), b2, voffB); PG8_STAGE(PG8_SB(0, 1), b2 + hstep, voffB); PG8_STAGE(PG8_SA(0, 0), a2, voffA);
;             PG8_WAIT_V(8); PG8_WAIT_L(0); PG8_BAR; PG8_MMA(1, 0, At, B0); PG8_MMA(1, 1, At, B1); PG8_BAR; PG8_SCHED;
;             PG8_LDB(B0, 1, 0); PG8_LDB(B1, 1, 1); PG8_SCHED; PG8_LDA(At, 1, 0); PG8_STAGE(PG8_SA(0, 1), a2 + hstep, voffA);
;             PG8_WAIT_V(8); PG8_WAIT_L(0); PG8_BAR; PG8_MMA(0, 0, At, B0); PG8_MMA(0, 1, At, B1); PG8_BAR; PG8_SCHED;
	s_waitcnt lgkmcnt(0)
	v_mfma_f32_16x16x32_bf16 v[60:63], v[128:131], v[184:187], 0
	v_mfma_f32_16x16x32_bf16 v[56:59], v[152:155], v[184:187], 0
	v_mfma_f32_16x16x32_bf16 v[44:47], v[128:131], v[192:195], 0
	v_mfma_f32_16x16x32_bf16 v[40:43], v[152:155], v[192:195], 0
	v_mfma_f32_16x16x32_bf16 v[28:31], v[128:131], v[202:205], 0
	v_mfma_f32_16x16x32_bf16 v[24:27], v[152:155], v[202:205], 0
	v_mfma_f32_16x16x32_bf16 v[12:15], v[128:131], v[210:213], 0
	v_mfma_f32_16x16x32_bf16 v[8:11], v[152:155], v[210:213], 0
	v_mfma_f32_16x16x32_bf16 v[60:63], v[148:151], v[188:191], v[60:63]
	v_mfma_f32_16x16x32_bf16 v[56:59], v[156:159], v[188:191], v[56:59]
	v_mfma_f32_16x16x32_bf16 v[44:47], v[148:151], v[196:199], v[44:47]
	v_mfma_f32_16x16x32_bf16 v[40:43], v[156:159], v[196:199], v[40:43]
	v_mfma_f32_16x16x32_bf16 v[28:31], v[148:151], v[206:209], v[28:31]
	v_mfma_f32_16x16x32_bf16 v[24:27], v[156:159], v[206:209], v[24:27]
	v_mfma_f32_16x16x32_bf16 v[12:15], v[148:151], v[214:217], v[12:15]
	v_mfma_f32_16x16x32_bf16 v[8:11], v[156:159], v[214:217], v[8:11]
	v_mfma_f32_16x16x32_bf16 v[52:55], v[160:163], v[184:187], 0
	v_mfma_f32_16x16x32_bf16 v[48:51], v[176:179], v[184:187], 0
	v_mfma_f32_16x16x32_bf16 v[36:39], v[160:163], v[192:195], 0
	v_mfma_f32_16x16x32_bf16 v[32:35], v[176:179], v[192:195], 0
	v_mfma_f32_16x16x32_bf16 v[20:23], v[160:163], v[202:205], 0
	v_mfma_f32_16x16x32_bf16 v[16:19], v[176:179], v[202:205], 0
	v_mfma_f32_16x16x32_bf16 v[4:7], v[160:163], v[210:213], 0
	v_mfma_f32_16x16x32_bf16 v[0:3], v[176:179], v[210:213], 0
	v_mfma_f32_16x16x32_bf16 v[52:55], v[172:175], v[188:191], v[52:55]
	v_mfma_f32_16x16x32_bf16 v[48:51], v[180:183], v[188:191], v[48:51]
	v_mfma_f32_16x16x32_bf16 v[36:39], v[172:175], v[196:199], v[36:39]
	v_mfma_f32_16x16x32_bf16 v[32:35], v[180:183], v[196:199], v[32:35]
	v_mfma_f32_16x16x32_bf16 v[20:23], v[172:175], v[206:209], v[20:23]
	v_mfma_f32_16x16x32_bf16 v[16:19], v[180:183], v[206:209], v[16:19]
	v_mfma_f32_16x16x32_bf16 v[4:7], v[172:175], v[214:217], v[4:7]
	v_mfma_f32_16x16x32_bf16 v[0:3], v[180:183], v[214:217], v[0:3]
	s_barrier
	s_add_i32 s16, 0, 0x18000
	s_add_i32 s17, 0, 0x1c000
	v_add_u32_e32 v156, s16, v167
	v_add_u32_e32 v180, s17, v167
	ds_read_b128 v[128:131], v156
	ds_read_b128 v[148:151], v156 offset:1024
	ds_read_b128 v[152:155], v156 offset:2048
	ds_read_b128 v[156:159], v156 offset:3072
	ds_read_b128 v[160:163], v180
	ds_read_b128 v[172:175], v180 offset:1024
	ds_read_b128 v[176:179], v180 offset:2048
	ds_read_b128 v[180:183], v180 offset:3072
	s_add_u32 s52, s52, s10
	s_addc_u32 s53, s53, s11
	s_mov_b32 m0, s58
	v_lshl_add_u64 v[228:229], s[52:53], 0, v[132:133]
	ds_read_b128 v[184:187], v171 offset:32768
	ds_read_b128 v[188:191], v171 offset:33792
	ds_read_b128 v[192:195], v171 offset:34816
	ds_read_b128 v[196:199], v171 offset:35840
	ds_read_b128 v[202:205], v171 offset:36864
	ds_read_b128 v[206:209], v171 offset:37888
	ds_read_b128 v[210:213], v171 offset:38912
	ds_read_b128 v[214:217], v171 offset:39936
	global_load_lds_dwordx4 v[228:229], off
	v_lshl_add_u64 v[228:229], s[52:53], 0, v[136:137]
	s_mov_b32 m0, s59
	s_nop 0
	global_load_lds_dwordx4 v[228:229], off
	s_waitcnt vmcnt(8)
	s_waitcnt lgkmcnt(0)
	s_barrier
	s_waitcnt lgkmcnt(0)
	v_mfma_f32_16x16x32_bf16 v[120:123], v[128:131], v[184:187], v[120:123]
	v_mfma_f32_16x16x32_bf16 v[124:127], v[152:155], v[184:187], v[124:127]
	v_mfma_f32_16x16x32_bf16 v[108:111], v[128:131], v[192:195], v[108:111]
	v_mfma_f32_16x16x32_bf16 v[104:107], v[152:155], v[192:195], v[104:107]
	v_mfma_f32_16x16x32_bf16 v[92:95], v[128:131], v[202:205], v[92:95]
	v_mfma_f32_16x16x32_bf16 v[88:91], v[152:155], v[202:205], v[88:91]
	v_mfma_f32_16x16x32_bf16 v[76:79], v[128:131], v[210:213], v[76:79]
	v_mfma_f32_16x16x32_bf16 v[72:75], v[152:155], v[210:213], v[72:75]
	v_mfma_f32_16x16x32_bf16 v[120:123], v[148:151], v[188:191], v[120:123]
	v_mfma_f32_16x16x32_bf16 v[124:127], v[156:159], v[188:191], v[124:127]
	v_mfma_f32_16x16x32_bf16 v[108:111], v[148:151], v[196:199], v[108:111]
	v_mfma_f32_16x16x32_bf16 v[104:107], v[156:159], v[196:199], v[104:107]
	v_mfma_f32_16x16x32_bf16 v[92:95], v[148:151], v[206:209], v[92:95]
	v_mfma_f32_16x16x32_bf16 v[88:91], v[156:159], v[206:209], v[88:91]
	v_mfma_f32_16x16x32_bf16 v[76:79], v[148:151], v[214:217], v[76:79]
	v_mfma_f32_16x16x32_bf16 v[72:75], v[156:159], v[214:217], v[72:75]
	v_mfma_f32_16x16x32_bf16 v[116:119], v[160:163], v[184:187], v[116:119]
	v_mfma_f32_16x16x32_bf16 v[112:115], v[176:179], v[184:187], v[112:115]
	v_mfma_f32_16x16x32_bf16 v[100:103], v[160:163], v[192:195], v[100:103]
	v_mfma_f32_16x16x32_bf16 v[96:99], v[176:179], v[192:195], v[96:99]
	v_mfma_f32_16x16x32_bf16 v[84:87], v[160:163], v[202:205], v[84:87]
	v_mfma_f32_16x16x32_bf16 v[80:83], v[176:179], v[202:205], v[80:83]
	v_mfma_f32_16x16x32_bf16 v[68:71], v[160:163], v[210:213], v[68:71]
	v_mfma_f32_16x16x32_bf16 v[64:67], v[176:179], v[210:213], v[64:67]
	v_mfma_f32_16x16x32_bf16 v[116:119], v[172:175], v[188:191], v[116:119]
	v_mfma_f32_16x16x32_bf16 v[112:115], v[180:183], v[188:191], v[112:115]
	v_mfma_f32_16x16x32_bf16 v[100:103], v[172:175], v[196:199], v[100:103]
	v_mfma_f32_16x16x32_bf16 v[96:99], v[180:183], v[196:199], v[96:99]
	v_mfma_f32_16x16x32_bf16 v[84:87], v[172:175], v[206:209], v[84:87]
	v_mfma_f32_16x16x32_bf16 v[80:83], v[180:183], v[206:209], v[80:83]
	v_mfma_f32_16x16x32_bf16 v[68:71], v[172:175], v[214:217], v[68:71]
	v_mfma_f32_16x16x32_bf16 v[64:67], v[180:183], v[214:217], v[64:67]
	s_barrier
; #define PG8_STAGE(bufoff, gbase, voff) do { _Pragma("unroll") for (int _i = 0; _i < 2; ++_i) \
;         __builtin_amdgcn_global_load_lds((const unsigned*)((const char*)(gbase) + (voff)[_i]), (PG8_LAS unsigned*)(lds + (bufoff) + ldsw + _i * 8192), 16, 0, 0); } while (0)
; #define PG8_LDA(dst, b, h) do { _Pragma("unroll") for (int m = 0; m < 4; ++m) _Pragma("unroll") for (int k = 0; k < 2; ++k) dst[m][k] = *(const PG8_LAS bf16x8*)(lds + PG8_SA(b, h) + aoff + m * 2048 + k * 1024); } while (0)
; #define PG8_LDB(dst, b, h) do { _Pragma("unroll") for (int n = 0; n < 2; ++n) _Pragma("unroll") for (int k = 0; k < 2; ++k) dst[n][k] = *(const PG8_LAS bf16x8*)(lds + PG8_SB(b, h) + boff + n * 2048 + k * 1024); } while (0)
; template <class Epi, class Sched, bool ALIGN_EPI = false, bool SP2 = false>
; __device__ __forceinline__ void gemm_phase(PG8_LAS unsigned char* lds, const Gemm g, const Sched& S, const Epi& E) {
;     ...
;         for (int t = 0; t < nt; t += 2) {
;             const bool last = (t == nt - 2);
;             const char* a1 = cA + (size_t)(t + 1) * kstep;
;             const char* a2 = last ? nA : cA + (size_t)(t + 2) * kstep; const char* b2 = last ? nB : cB + (size_t)(t + 2) * kstep;
;             const char* a3 = a2 + kstep; const char* b3 = b2 + kstep;
;             if (last && has_next) S.a_ready(nxt);
;             if constexpr (SP2) {
;             PG8_LDB(B0, 0, 0); PG8_LDB(B1, 0, 1); PG8_SCHED; PG8_LDA(At, 0, 0); PG8_STAGE(PG8_SA(1, 1), a1 + hstep, voffA);
;             PG8_WAIT_V(8); PG8_WAIT_L(0); PG8_BAR; PG8_MMA(0, 0, At, B0); PG8_MMA(0, 1, At, B1); PG8_BAR; PG8_SCHED;
;             PG8_LDA(At, 0, 1); PG8_STAGE(PG8_SB(0, 0), b2, voffB); PG8_STAGE(PG8_SB(0, 1), b2 + hstep, voffB); PG8_STAGE(PG8_SA(0, 0), a2, voffA);
;             PG8_WAIT_V(8); PG8_WAIT_L(0); PG8_BAR; PG8_MMA(1, 0, At, B0); PG8_MMA(1, 1, At, B1); PG8_BAR; PG8_SCHED;
;             PG8_LDB(B0, 1, 0); PG8_LDB(B1, 1, 1); PG8_SCHED; PG8_LDA(At, 1, 0); PG8_STAGE(PG8_SA(0, 1), a2 + hstep, voffA);
;             PG8_WAIT_V(8); PG8_WAIT_L(0); PG8_BAR; PG8_MMA(0, 0, At, B0); PG8_MMA(0, 1, At, B1); PG8_BAR; PG8_SCHED;
;             PG8_LDA(At, 1, 1); PG8_STAGE(PG8_SB(1, 0), b3, voffB); PG8_STAGE(PG8_SB(1, 1), b3 + hstep, voffB); PG8_STAGE(PG8_SA(1, 0), a3, voffA);
;             PG8_WAIT_V(8); PG8_WAIT_L(0); PG8_BAR; PG8_MMA(1, 0, At, B0); PG8_MMA(1, 1, At, B1); PG8_BAR; PG8_SCHED;
	s_add_i32 s16, s16, s55
	v_lshl_add_u64 v[164:165], v[164:165], 0, s[44:45]
	s_mov_b32 m0, s16
	ds_read_b128 v[184:187], v171 offset:49152
	ds_read_b128 v[188:191], v171 offset:50176
	ds_read_b128 v[192:195], v171 offset:51200
	ds_read_b128 v[196:199], v171 offset:52224
	ds_read_b128 v[202:205], v171 offset:53248
	ds_read_b128 v[206:209], v171 offset:54272
	ds_read_b128 v[210:213], v171 offset:55296
	ds_read_b128 v[214:217], v171 offset:56320
	global_load_lds_dwordx4 v[164:165], off
	v_lshl_add_u64 v[164:165], v[218:219], 0, s[44:45]
	s_add_i32 m0, s16, 0x2000
	s_add_i32 s16, s17, s55
	global_load_lds_dwordx4 v[164:165], off
	v_lshl_add_u64 v[164:165], v[220:221], 0, s[44:45]
	s_mov_b32 m0, s16
	s_nop 0
	global_load_lds_dwordx4 v[164:165], off
	v_lshl_add_u64 v[164:165], v[222:223], 0, s[44:45]
	s_add_i32 m0, s16, 0x2000
	s_nop 0
	global_load_lds_dwordx4 v[164:165], off
	v_lshl_add_u64 v[164:165], v[224:225], 0, s[44:45]
	s_mov_b32 m0, s62
	s_nop 0
	global_load_lds_dwordx4 v[164:165], off
	v_lshl_add_u64 v[164:165], v[226:227], 0, s[44:45]
	s_mov_b32 m0, s63
	s_nop 0
	global_load_lds_dwordx4 v[164:165], off
	s_waitcnt vmcnt(8)
	s_waitcnt lgkmcnt(0)
	s_barrier
	s_waitcnt lgkmcnt(0)
	v_mfma_f32_16x16x32_bf16 v[60:63], v[128:131], v[184:187], v[60:63]
	v_mfma_f32_16x16x32_bf16 v[56:59], v[152:155], v[184:187], v[56:59]
	v_mfma_f32_16x16x32_bf16 v[44:47], v[128:131], v[192:195], v[44:47]
	v_mfma_f32_16x16x32_bf16 v[40:43], v[152:155], v[192:195], v[40:43]
	v_mfma_f32_16x16x32_bf16 v[28:31], v[128:131], v[202:205], v[28:31]
	v_mfma_f32_16x16x32_bf16 v[24:27], v[152:155], v[202:205], v[24:27]
	v_mfma_f32_16x16x32_bf16 v[12:15], v[128:131], v[210:213], v[12:15]
	v_mfma_f32_16x16x32_bf16 v[8:11], v[152:155], v[210:213], v[8:11]
	v_mfma_f32_16x16x32_bf16 v[60:63], v[148:151], v[188:191], v[60:63]
	v_mfma_f32_16x16x32_bf16 v[56:59], v[156:159], v[188:191], v[56:59]
	v_mfma_f32_16x16x32_bf16 v[44:47], v[148:151], v[196:199], v[44:47]
	v_mfma_f32_16x16x32_bf16 v[40:43], v[156:159], v[196:199], v[40:43]
	v_mfma_f32_16x16x32_bf16 v[28:31], v[148:151], v[206:209], v[28:31]
	v_mfma_f32_16x16x32_bf16 v[24:27], v[156:159], v[206:209], v[24:27]
	v_mfma_f32_16x16x32_bf16 v[12:15], v[148:151], v[214:217], v[12:15]
	v_mfma_f32_16x16x32_bf16 v[8:11], v[156:159], v[214:217], v[8:11]
	v_mfma_f32_16x16x32_bf16 v[52:55], v[160:163], v[184:187], v[52:55]
	v_mfma_f32_16x16x32_bf16 v[48:51], v[176:179], v[184:187], v[48:51]
	v_mfma_f32_16x16x32_bf16 v[36:39], v[160:163], v[192:195], v[36:39]
	v_mfma_f32_16x16x32_bf16 v[32:35], v[176:179], v[192:195], v[32:35]
	v_mfma_f32_16x16x32_bf16 v[20:23], v[160:163], v[202:205], v[20:23]
	v_mfma_f32_16x16x32_bf16 v[16:19], v[176:179], v[202:205], v[16:19]
	v_mfma_f32_16x16x32_bf16 v[4:7], v[160:163], v[210:213], v[4:7]
	v_mfma_f32_16x16x32_bf16 v[0:3], v[176:179], v[210:213], v[0:3]
	v_mfma_f32_16x16x32_bf16 v[52:55], v[172:175], v[188:191], v[52:55]
	v_mfma_f32_16x16x32_bf16 v[48:51], v[180:183], v[188:191], v[48:51]
	v_mfma_f32_16x16x32_bf16 v[36:39], v[172:175], v[196:199], v[36:39]
	v_mfma_f32_16x16x32_bf16 v[32:35], v[180:183], v[196:199], v[32:35]
	v_mfma_f32_16x16x32_bf16 v[20:23], v[172:175], v[206:209], v[20:23]
	v_mfma_f32_16x16x32_bf16 v[16:19], v[180:183], v[206:209], v[16:19]
	v_mfma_f32_16x16x32_bf16 v[4:7], v[172:175], v[214:217], v[4:7]
	v_mfma_f32_16x16x32_bf16 v[0:3], v[180:183], v[214:217], v[0:3]
	s_barrier
	s_add_u32 s6, s6, 0x100
	s_addc_u32 s7, s7, 0
	s_add_u32 s79, s79, 0x100
	s_addc_u32 s80, s80, 0
	s_cmp_ge_i32 s81, s68
	s_mov_b32 s52, s81
	s_cbranch_scc1 .LBB0_729
.LBB0_728:
	ds_read_b128 v[128:131], v169
	ds_read_b128 v[148:151], v169 offset:1024
	ds_read_b128 v[152:155], v169 offset:2048
	ds_read_b128 v[156:159], v169 offset:3072
	ds_read_b128 v[160:163], v170
	ds_read_b128 v[172:175], v170 offset:1024
	ds_read_b128 v[176:179], v170 offset:2048
	ds_read_b128 v[180:183], v170 offset:3072
	s_add_i32 s81, s52, 2
	s_add_u32 s16, s6, 0x80
	s_addc_u32 s17, s7, 0
	s_cmp_eq_u32 s69, s52
	s_cselect_b32 s52, s0, s16
	s_cselect_b32 s53, s1, s17
	s_cselect_b32 s83, s51, s80
	s_cselect_b32 s82, s50, s79
	v_lshl_add_u64 v[164:165], s[6:7], 0, v[140:141]
	s_add_i32 m0, s56, 0xc000
	ds_read_b128 v[184:187], v171
	ds_read_b128 v[188:191], v171 offset:1024
	ds_read_b128 v[192:195], v171 offset:2048
	ds_read_b128 v[196:199], v171 offset:3072
	ds_read_b128 v[202:205], v171 offset:4096
	ds_read_b128 v[206:209], v171 offset:5120
	ds_read_b128 v[210:213], v171 offset:6144
	ds_read_b128 v[214:217], v171 offset:7168
	global_load_lds_dwordx4 v[164:165], off
	v_lshl_add_u64 v[164:165], s[6:7], 0, v[142:143]
	s_add_i32 m0, s56, 0xe000
	s_nop 0
	global_load_lds_dwordx4 v[164:165], off
	s_waitcnt vmcnt(8)
	s_waitcnt lgkmcnt(0)
	s_barrier
; #define PG8_STAGE(bufoff, gbase, voff) do { _Pragma("unroll") for (int _i = 0; _i < 2; ++_i) \
;         __builtin_amdgcn_global_load_lds((const unsigned*)((const char*)(gbase) + (voff)[_i]), (PG8_LAS unsigned*)(lds + (bufoff) + ldsw + _i * 8192), 16, 0, 0); } while (0)
; #define PG8_LDA(dst, b, h) do { _Pragma("unroll") for (int m = 0; m < 4; ++m) _Pragma("unroll") for (int k = 0; k < 2; ++k) dst[m][k] = *(const PG8_LAS bf16x8*)(lds + PG8_SA(b, h) + aoff + m * 2048 + k * 1024); } while (0)
; #define PG8_LDB(dst, b, h) do { _Pragma("unroll") for (int n = 0; n < 2; ++n) _Pragma("unroll") for (int k = 0; k < 2; ++k) dst[n][k] = *(const PG8_LAS bf16x8*)(lds + PG8_SB(b, h) + boff + n * 2048 + k * 1024); } while (0)
; #define PG8_MMA(ai, bj, At, Bt) do { __builtin_amdgcn_s_setprio(1); _Pragma("unroll") for (int m = 0; m < 4; ++m) _Pragma("unroll") for (int n = 0; n < 2; ++n) _Pragma("unroll") for (int k = 0; k < 2; ++k) \
;         acc[ai][bj][m][n] = __builtin_amdgcn_mfma_f32_16x16x32_bf16(Bt[n][k], At[m][k], acc[ai][bj][m][n], 0, 0, 0); __builtin_amdgcn_s_setprio(0); } while (0)
; #define PG8_WAIT_V(n) asm volatile("s_waitcnt vmcnt(" #n ")" ::: "memory")
; #define PG8_WAIT_L(n) asm volatile("s_waitcnt lgkmcnt(" #n ")" ::: "memory")
; #define PG8_BAR __builtin_amdgcn_s_barrier()
; #define PG8_SCHED __builtin_amdgcn_sched_barrier(0)
; template <class Epi, class Sched, bool ALIGN_EPI = false, bool SP2 = false>
; __device__ __forceinline__ void gemm_phase(PG8_LAS unsigned char* lds, const Gemm g, const Sched& S, const Epi& E) {
;     ...
;             if constexpr (SP2) {
;             PG8_LDB(B0, 0, 0); PG8_LDB(B1, 0, 1); PG8_SCHED; PG8_LDA(At, 0, 0); PG8_STAGE(PG8_SA(1, 1), a1 + hstep, voffA);
;             PG8_WAIT_V(8); PG8_WAIT_L(0); PG8_BAR; PG8_MMA(0, 0, At, B0); PG8_MMA(0, 1, At, B1); PG8_BAR; PG8_SCHED;
;             PG8_LDA(At, 0, 1); PG8_STAGE(PG8_SB(0, 0), b2, voffB); PG8_STAGE(PG8_SB(0, 1), b2 + hstep, voffB); PG8_STAGE(PG8_SA(0, 0), a2, voffA);
;             PG8_WAIT_V(8); PG8_WAIT_L(0); PG8_BAR; PG8_MMA(1, 0, At, B0); PG8_MMA(1, 1, At, B1); PG8_BAR; PG8_SCHED;
	s_waitcnt lgkmcnt(0)
	v_mfma_f32_16x16x32_bf16 v[120:123], v[128:131], v[184:187], v[120:123]
	v_mfma_f32_16x16x32_bf16 v[124:127], v[152:155], v[184:187], v[124:127]
	v_mfma_f32_16x16x32_bf16 v[108:111], v[128:131], v[192:195], v[108:111]
	v_mfma_f32_16x16x32_bf16 v[104:107], v[152:155], v[192:195], v[104:107]
	v_mfma_f32_16x16x32_bf16 v[92:95], v[128:131], v[202:205], v[92:95]
	v_mfma_f32_16x16x32_bf16 v[88:91], v[152:155], v[202:205], v[88:91]
	v_mfma_f32_16x16x32_bf16 v[76:79], v[128:131], v[210:213], v[76:79]
	v_mfma_f32_16x16x32_bf16 v[72:75], v[152:155], v[210:213], v[72:75]
	v_mfma_f32_16x16x32_bf16 v[120:123], v[148:151], v[188:191], v[120:123]
	v_mfma_f32_16x16x32_bf16 v[124:127], v[156:159], v[188:191], v[124:127]
	v_mfma_f32_16x16x32_bf16 v[108:111], v[148:151], v[196:199], v[108:111]
	v_mfma_f32_16x16x32_bf16 v[104:107], v[156:159], v[196:199], v[104:107]
	v_mfma_f32_16x16x32_bf16 v[92:95], v[148:151], v[206:209], v[92:95]
	v_mfma_f32_16x16x32_bf16 v[88:91], v[156:159], v[206:209], v[88:91]
	v_mfma_f32_16x16x32_bf16 v[76:79], v[148:151], v[214:217], v[76:79]
	v_mfma_f32_16x16x32_bf16 v[72:75], v[156:159], v[214:217], v[72:75]
	v_mfma_f32_16x16x32_bf16 v[116:119], v[160:163], v[184:187], v[116:119]
	v_mfma_f32_16x16x32_bf16 v[112:115], v[176:179], v[184:187], v[112:115]
	v_mfma_f32_16x16x32_bf16 v[100:103], v[160:163], v[192:195], v[100:103]
	v_mfma_f32_16x16x32_bf16 v[96:99], v[176:179], v[192:195], v[96:99]
	v_mfma_f32_16x16x32_bf16 v[84:87], v[160:163], v[202:205], v[84:87]
	v_mfma_f32_16x16x32_bf16 v[80:83], v[176:179], v[202:205], v[80:83]
	v_mfma_f32_16x16x32_bf16 v[68:71], v[160:163], v[210:213], v[68:71]
	v_mfma_f32_16x16x32_bf16 v[64:67], v[176:179], v[210:213], v[64:67]
	v_mfma_f32_16x16x32_bf16 v[116:119], v[172:175], v[188:191], v[116:119]
	v_mfma_f32_16x16x32_bf16 v[112:115], v[180:183], v[188:191], v[112:115]
	v_mfma_f32_16x16x32_bf16 v[100:103], v[172:175], v[196:199], v[100:103]
	v_mfma_f32_16x16x32_bf16 v[96:99], v[180:183], v[196:199], v[96:99]
	v_mfma_f32_16x16x32_bf16 v[84:87], v[172:175], v[206:209], v[84:87]
	v_mfma_f32_16x16x32_bf16 v[80:83], v[180:183], v[206:209], v[80:83]
	v_mfma_f32_16x16x32_bf16 v[68:71], v[172:175], v[214:217], v[68:71]
	v_mfma_f32_16x16x32_bf16 v[64:67], v[180:183], v[214:217], v[64:67]
	s_barrier
	s_add_i32 s16, s71, s55
	v_lshl_add_u64 v[164:165], s[82:83], 0, v[134:135]
	s_mov_b32 m0, s16
	ds_read_b128 v[184:187], v171 offset:16384
	ds_read_b128 v[188:191], v171 offset:17408
	ds_read_b128 v[192:195], v171 offset:18432
	ds_read_b128 v[196:199], v171 offset:19456
	ds_read_b128 v[202:205], v171 offset:20480
	ds_read_b128 v[206:209], v171 offset:21504
	ds_read_b128 v[210:213], v171 offset:22528
	ds_read_b128 v[214:217], v171 offset:23552
	global_load_lds_dwordx4 v[164:165], off
	s_add_i32 m0, s16, 0x2000
	v_lshl_add_u64 v[218:219], s[82:83], 0, v[138:139]
	s_add_u32 s82, s82, s10
	s_addc_u32 s83, s83, s11
	s_add_i32 s16, s72, s55
	global_load_lds_dwordx4 v[218:219], off
	v_lshl_add_u64 v[220:221], s[82:83], 0, v[134:135]
	s_mov_b32 m0, s16
	v_lshl_add_u64 v[222:223], s[82:83], 0, v[138:139]
	global_load_lds_dwordx4 v[220:221], off
	s_add_i32 m0, s16, 0x2000
	v_lshl_add_u64 v[224:225], s[52:53], 0, v[132:133]
	global_load_lds_dwordx4 v[222:223], off
	s_mov_b32 m0, s56
	v_lshl_add_u64 v[226:227], s[52:53], 0, v[136:137]
	global_load_lds_dwordx4 v[224:225], off
	s_mov_b32 m0, s57
	s_nop 0
	global_load_lds_dwordx4 v[226:227], off
	s_waitcnt vmcnt(8)
	s_waitcnt lgkmcnt(0)
	s_barrier
	s_waitcnt lgkmcnt(0)
	v_mfma_f32_16x16x32_bf16 v[60:63], v[128:131], v[184:187], v[60:63]
	v_mfma_f32_16x16x32_bf16 v[56:59], v[152:155], v[184:187], v[56:59]
	v_mfma_f32_16x16x32_bf16 v[44:47], v[128:131], v[192:195], v[44:47]
	v_mfma_f32_16x16x32_bf16 v[40:43], v[152:155], v[192:195], v[40:43]
	v_mfma_f32_16x16x32_bf16 v[28:31], v[128:131], v[202:205], v[28:31]
	v_mfma_f32_16x16x32_bf16 v[24:27], v[152:155], v[202:205], v[24:27]
	v_mfma_f32_16x16x32_bf16 v[12:15], v[128:131], v[210:213], v[12:15]
	v_mfma_f32_16x16x32_bf16 v[8:11], v[152:155], v[210:213], v[8:11]
	v_mfma_f32_16x16x32_bf16 v[60:63], v[148:151], v[188:191], v[60:63]
	v_mfma_f32_16x16x32_bf16 v[56:59], v[156:159], v[188:191], v[56:59]
	v_mfma_f32_16x16x32_bf16 v[44:47], v[148:151], v[196:199], v[44:47]
	v_mfma_f32_16x16x32_bf16 v[40:43], v[156:159], v[196:199], v[40:43]
	v_mfma_f32_16x16x32_bf16 v[28:31], v[148:151], v[206:209], v[28:31]
	v_mfma_f32_16x16x32_bf16 v[24:27], v[156:159], v[206:209], v[24:27]
	v_mfma_f32_16x16x32_bf16 v[12:15], v[148:151], v[214:217], v[12:15]
	v_mfma_f32_16x16x32_bf16 v[8:11], v[156:159], v[214:217], v[8:11]
	v_mfma_f32_16x16x32_bf16 v[52:55], v[160:163], v[184:187], v[52:55]
	v_mfma_f32_16x16x32_bf16 v[48:51], v[176:179], v[184:187], v[48:51]
	v_mfma_f32_16x16x32_bf16 v[36:39], v[160:163], v[192:195], v[36:39]
	v_mfma_f32_16x16x32_bf16 v[32:35], v[176:179], v[192:195], v[32:35]
	v_mfma_f32_16x16x32_bf16 v[20:23], v[160:163], v[202:205], v[20:23]
	v_mfma_f32_16x16x32_bf16 v[16:19], v[176:179], v[202:205], v[16:19]
	v_mfma_f32_16x16x32_bf16 v[4:7], v[160:163], v[210:213], v[4:7]
	v_mfma_f32_16x16x32_bf16 v[0:3], v[176:179], v[210:213], v[0:3]
	v_mfma_f32_16x16x32_bf16 v[52:55], v[172:175], v[188:191], v[52:55]
	v_mfma_f32_16x16x32_bf16 v[48:51], v[180:183], v[188:191], v[48:51]
	v_mfma_f32_16x16x32_bf16 v[36:39], v[172:175], v[196:199], v[36:39]
	v_mfma_f32_16x16x32_bf16 v[32:35], v[180:183], v[196:199], v[32:35]
	v_mfma_f32_16x16x32_bf16 v[20:23], v[172:175], v[206:209], v[20:23]
	v_mfma_f32_16x16x32_bf16 v[16:19], v[180:183], v[206:209], v[16:19]
	v_mfma_f32_16x16x32_bf16 v[4:7], v[172:175], v[214:217], v[4:7]
	v_mfma_f32_16x16x32_bf16 v[0:3], v[180:183], v[214:217], v[0:3]
	s_barrier
; #define PG8_STAGE(bufoff, gbase, voff) do { _Pragma("unroll") for (int _i = 0; _i < 2; ++_i) \
;         __builtin_amdgcn_global_load_lds((const unsigned*)((const char*)(gbase) + (voff)[_i]), (PG8_LAS unsigned*)(lds + (bufoff) + ldsw + _i * 8192), 16, 0, 0); } while (0)
; #define PG8_LDA(dst, b, h) do { _Pragma("unroll") for (int m = 0; m < 4; ++m) _Pragma("unroll") for (int k = 0; k < 2; ++k) dst[m][k] = *(const PG8_LAS bf16x8*)(lds + PG8_SA(b, h) + aoff + m * 2048 + k * 1024); } while (0)
; #define PG8_LDB(dst, b, h) do { _Pragma("unroll") for (int n = 0; n < 2; ++n) _Pragma("unroll") for (int k = 0; k < 2; ++k) dst[n][k] = *(const PG8_LAS bf16x8*)(lds + PG8_SB(b, h) + boff + n * 2048 + k * 1024); } while (0)
; #define PG8_MMA(ai, bj, At, Bt) do { __builtin_amdgcn_s_setprio(1); _Pragma("unroll") for (int m = 0; m < 4; ++m) _Pragma("unroll") for (int n = 0; n < 2; ++n) _Pragma("unroll") for (int k = 0; k < 2; ++k) \
;         acc[ai][bj][m][n] = __builtin_amdgcn_mfma_f32_16x16x32_bf16(Bt[n][k], At[m][k], acc[ai][bj][m][n], 0, 0, 0); __builtin_amdgcn_s_setprio(0); } while (0)
; #define PG8_WAIT_V(n) asm volatile("s_waitcnt vmcnt(" #n ")" ::: "memory")
; #define PG8_WAIT_L(n) asm volatile("s_waitcnt lgkmcnt(" #n ")" ::: "memory")
; #define PG8_BAR __builtin_amdgcn_s_barrier()
; #define PG8_SCHED __builtin_amdgcn_sched_barrier(0)
; template <class Epi, class Sched, bool ALIGN_EPI = false, bool SP2 = false>
; __device__ __forceinline__ void gemm_phase(PG8_LAS unsigned char* lds, const Gemm g, const Sched& S, const Epi& E) {
;     ...
;             PG8_WAIT_V(8); PG8_WAIT_L(0); PG8_BAR; PG8_MMA(1, 0, At, B0); PG8_MMA(1, 1, At, B1); PG8_BAR; PG8_SCHED;
;             PG8_LDB(B0, 1, 0); PG8_LDB(B1, 1, 1); PG8_SCHED; PG8_LDA(At, 1, 0); PG8_STAGE(PG8_SA(0, 1), a2 + hstep, voffA);
;             PG8_WAIT_V(8); PG8_WAIT_L(0); PG8_BAR; PG8_MMA(0, 0, At, B0); PG8_MMA(0, 1, At, B1); PG8_BAR; PG8_SCHED;
;             PG8_LDA(At, 1, 1); PG8_STAGE(PG8_SB(1, 0), b3, voffB); PG8_STAGE(PG8_SB(1, 1), b3 + hstep, voffB); PG8_STAGE(PG8_SA(1, 0), a3, voffA);
;             PG8_WAIT_V(8); PG8_WAIT_L(0); PG8_BAR; PG8_MMA(1, 0, At, B0); PG8_MMA(1, 1, At, B1); PG8_BAR; PG8_SCHED;
	s_add_i32 s16, 0, 0x18000
	s_add_i32 s17, 0, 0x1c000
	v_add_u32_e32 v156, s16, v167
	v_add_u32_e32 v180, s17, v167
	ds_read_b128 v[128:131], v156
	ds_read_b128 v[148:151], v156 offset:1024
	ds_read_b128 v[152:155], v156 offset:2048
	ds_read_b128 v[156:159], v156 offset:3072
	ds_read_b128 v[160:163], v180
	ds_read_b128 v[172:175], v180 offset:1024
	ds_read_b128 v[176:179], v180 offset:2048
	ds_read_b128 v[180:183], v180 offset:3072
	s_add_u32 s52, s52, s10
	s_addc_u32 s53, s53, s11
	s_mov_b32 m0, s58
	v_lshl_add_u64 v[228:229], s[52:53], 0, v[132:133]
	ds_read_b128 v[184:187], v171 offset:32768
	ds_read_b128 v[188:191], v171 offset:33792
	ds_read_b128 v[192:195], v171 offset:34816
	ds_read_b128 v[196:199], v171 offset:35840
	ds_read_b128 v[202:205], v171 offset:36864
	ds_read_b128 v[206:209], v171 offset:37888
	ds_read_b128 v[210:213], v171 offset:38912
	ds_read_b128 v[214:217], v171 offset:39936
	global_load_lds_dwordx4 v[228:229], off
	v_lshl_add_u64 v[228:229], s[52:53], 0, v[136:137]
	s_mov_b32 m0, s59
	s_nop 0
	global_load_lds_dwordx4 v[228:229], off
	s_waitcnt vmcnt(8)
	s_waitcnt lgkmcnt(0)
	s_barrier
	s_waitcnt lgkmcnt(0)
	v_mfma_f32_16x16x32_bf16 v[120:123], v[128:131], v[184:187], v[120:123]
	v_mfma_f32_16x16x32_bf16 v[124:127], v[152:155], v[184:187], v[124:127]
	v_mfma_f32_16x16x32_bf16 v[108:111], v[128:131], v[192:195], v[108:111]
	v_mfma_f32_16x16x32_bf16 v[104:107], v[152:155], v[192:195], v[104:107]
	v_mfma_f32_16x16x32_bf16 v[92:95], v[128:131], v[202:205], v[92:95]
	v_mfma_f32_16x16x32_bf16 v[88:91], v[152:155], v[202:205], v[88:91]
	v_mfma_f32_16x16x32_bf16 v[76:79], v[128:131], v[210:213], v[76:79]
	v_mfma_f32_16x16x32_bf16 v[72:75], v[152:155], v[210:213], v[72:75]
	v_mfma_f32_16x16x32_bf16 v[120:123], v[148:151], v[188:191], v[120:123]
	v_mfma_f32_16x16x32_bf16 v[124:127], v[156:159], v[188:191], v[124:127]
	v_mfma_f32_16x16x32_bf16 v[108:111], v[148:151], v[196:199], v[108:111]
	v_mfma_f32_16x16x32_bf16 v[104:107], v[156:159], v[196:199], v[104:107]
	v_mfma_f32_16x16x32_bf16 v[92:95], v[148:151], v[206:209], v[92:95]
	v_mfma_f32_16x16x32_bf16 v[88:91], v[156:159], v[206:209], v[88:91]
	v_mfma_f32_16x16x32_bf16 v[76:79], v[148:151], v[214:217], v[76:79]
	v_mfma_f32_16x16x32_bf16 v[72:75], v[156:159], v[214:217], v[72:75]
	v_mfma_f32_16x16x32_bf16 v[116:119], v[160:163], v[184:187], v[116:119]
	v_mfma_f32_16x16x32_bf16 v[112:115], v[176:179], v[184:187], v[112:115]
	v_mfma_f32_16x16x32_bf16 v[100:103], v[160:163], v[192:195], v[100:103]
	v_mfma_f32_16x16x32_bf16 v[96:99], v[176:179], v[192:195], v[96:99]
	v_mfma_f32_16x16x32_bf16 v[84:87], v[160:163], v[202:205], v[84:87]
	v_mfma_f32_16x16x32_bf16 v[80:83], v[176:179], v[202:205], v[80:83]
	v_mfma_f32_16x16x32_bf16 v[68:71], v[160:163], v[210:213], v[68:71]
	v_mfma_f32_16x16x32_bf16 v[64:67], v[176:179], v[210:213], v[64:67]
	v_mfma_f32_16x16x32_bf16 v[116:119], v[172:175], v[188:191], v[116:119]
	v_mfma_f32_16x16x32_bf16 v[112:115], v[180:183], v[188:191], v[112:115]
	v_mfma_f32_16x16x32_bf16 v[100:103], v[172:175], v[196:199], v[100:103]
	v_mfma_f32_16x16x32_bf16 v[96:99], v[180:183], v[196:199], v[96:99]
	v_mfma_f32_16x16x32_bf16 v[84:87], v[172:175], v[206:209], v[84:87]
	v_mfma_f32_16x16x32_bf16 v[80:83], v[180:183], v[206:209], v[80:83]
	v_mfma_f32_16x16x32_bf16 v[68:71], v[172:175], v[214:217], v[68:71]
	v_mfma_f32_16x16x32_bf16 v[64:67], v[180:183], v[214:217], v[64:67]
	s_barrier
	s_add_i32 s16, s16, s55
	v_lshl_add_u64 v[164:165], v[164:165], 0, s[44:45]
	s_mov_b32 m0, s16
	ds_read_b128 v[184:187], v171 offset:49152
	ds_read_b128 v[188:191], v171 offset:50176
	ds_read_b128 v[192:195], v171 offset:51200
	ds_read_b128 v[196:199], v171 offset:52224
	ds_read_b128 v[202:205], v171 offset:53248
	ds_read_b128 v[206:209], v171 offset:54272
	ds_read_b128 v[210:213], v171 offset:55296
	ds_read_b128 v[214:217], v171 offset:56320
	global_load_lds_dwordx4 v[164:165], off
	v_lshl_add_u64 v[164:165], v[218:219], 0, s[44:45]
	s_add_i32 m0, s16, 0x2000
	s_add_i32 s16, s17, s55
	global_load_lds_dwordx4 v[164:165], off
	v_lshl_add_u64 v[164:165], v[220:221], 0, s[44:45]
	s_mov_b32 m0, s16
	s_nop 0
	global_load_lds_dwordx4 v[164:165], off
	v_lshl_add_u64 v[164:165], v[222:223], 0, s[44:45]
	s_add_i32 m0, s16, 0x2000
	s_nop 0
	global_load_lds_dwordx4 v[164:165], off
	v_lshl_add_u64 v[164:165], v[224:225], 0, s[44:45]
	s_mov_b32 m0, s62
	s_nop 0
	global_load_lds_dwordx4 v[164:165], off
	v_lshl_add_u64 v[164:165], v[226:227], 0, s[44:45]
	s_mov_b32 m0, s63
	s_nop 0
	global_load_lds_dwordx4 v[164:165], off
	s_waitcnt vmcnt(8)
	s_waitcnt lgkmcnt(0)
	s_barrier
	s_waitcnt lgkmcnt(0)
	v_mfma_f32_16x16x32_bf16 v[60:63], v[128:131], v[184:187], v[60:63]
	v_mfma_f32_16x16x32_bf16 v[56:59], v[152:155], v[184:187], v[56:59]
	v_mfma_f32_16x16x32_bf16 v[44:47], v[128:131], v[192:195], v[44:47]
	v_mfma_f32_16x16x32_bf16 v[40:43], v[152:155], v[192:195], v[40:43]
	v_mfma_f32_16x16x32_bf16 v[28:31], v[128:131], v[202:205], v[28:31]
	v_mfma_f32_16x16x32_bf16 v[24:27], v[152:155], v[202:205], v[24:27]
	v_mfma_f32_16x16x32_bf16 v[12:15], v[128:131], v[210:213], v[12:15]
	v_mfma_f32_16x16x32_bf16 v[8:11], v[152:155], v[210:213], v[8:11]
	v_mfma_f32_16x16x32_bf16 v[60:63], v[148:151], v[188:191], v[60:63]
	v_mfma_f32_16x16x32_bf16 v[56:59], v[156:159], v[188:191], v[56:59]
	v_mfma_f32_16x16x32_bf16 v[44:47], v[148:151], v[196:199], v[44:47]
	v_mfma_f32_16x16x32_bf16 v[40:43], v[156:159], v[196:199], v[40:43]
	v_mfma_f32_16x16x32_bf16 v[28:31], v[148:151], v[206:209], v[28:31]
	v_mfma_f32_16x16x32_bf16 v[24:27], v[156:159], v[206:209], v[24:27]
	v_mfma_f32_16x16x32_bf16 v[12:15], v[148:151], v[214:217], v[12:15]
	v_mfma_f32_16x16x32_bf16 v[8:11], v[156:159], v[214:217], v[8:11]
	v_mfma_f32_16x16x32_bf16 v[52:55], v[160:163], v[184:187], v[52:55]
	v_mfma_f32_16x16x32_bf16 v[48:51], v[176:179], v[184:187], v[48:51]
	v_mfma_f32_16x16x32_bf16 v[36:39], v[160:163], v[192:195], v[36:39]
	v_mfma_f32_16x16x32_bf16 v[32:35], v[176:179], v[192:195], v[32:35]
	v_mfma_f32_16x16x32_bf16 v[20:23], v[160:163], v[202:205], v[20:23]
	v_mfma_f32_16x16x32_bf16 v[16:19], v[176:179], v[202:205], v[16:19]
	v_mfma_f32_16x16x32_bf16 v[4:7], v[160:163], v[210:213], v[4:7]
	v_mfma_f32_16x16x32_bf16 v[0:3], v[176:179], v[210:213], v[0:3]
	v_mfma_f32_16x16x32_bf16 v[52:55], v[172:175], v[188:191], v[52:55]
	v_mfma_f32_16x16x32_bf16 v[48:51], v[180:183], v[188:191], v[48:51]
	v_mfma_f32_16x16x32_bf16 v[36:39], v[172:175], v[196:199], v[36:39]
	v_mfma_f32_16x16x32_bf16 v[32:35], v[180:183], v[196:199], v[32:35]
	v_mfma_f32_16x16x32_bf16 v[20:23], v[172:175], v[206:209], v[20:23]
	v_mfma_f32_16x16x32_bf16 v[16:19], v[180:183], v[206:209], v[16:19]
	v_mfma_f32_16x16x32_bf16 v[4:7], v[172:175], v[214:217], v[4:7]
	v_mfma_f32_16x16x32_bf16 v[0:3], v[180:183], v[214:217], v[0:3]
	s_barrier
	s_add_u32 s6, s6, 0x100
	s_addc_u32 s7, s7, 0
	s_add_u32 s79, s79, 0x100
	s_addc_u32 s80, s80, 0
	s_cmp_ge_i32 s81, s68
	s_mov_b32 s52, s81
	s_cbranch_scc0 .LBB0_728

; #define PG8_WAIT_V(n) asm volatile("s_waitcnt vmcnt(" #n ")" ::: "memory")
; #define PG8_BAR __builtin_amdgcn_s_barrier()
; template <class Epi, class Sched, bool ALIGN_EPI = false, bool SP2 = false>
; __device__ __forceinline__ void gemm_phase(PG8_LAS unsigned char* lds, const Gemm g, const Sched& S, const Epi& E) {
;     ...
;     PG8_WAIT_V(0);
;     if constexpr (!ALIGN_EPI) { if (wr == 0) PG8_BAR; }
;     PG8_BAR;
; __device__ __forceinline__ void xcd_barrier(const XcdBarrier& b) {
;     asm volatile("s_waitcnt vmcnt(0)" ::: "memory");
;     __syncthreads();
;     if (threadIdx.x == 0) {
;         unsigned* bar = b.bar;
;         __builtin_amdgcn_s_waitcnt(0);
;         unsigned nloc = b.st[0], nx = b.st[1];
;         if (nloc == 0u) { xcd_barrier_complete(bar, b.x, nloc, nx); b.st[0] = nloc; b.st[1] = nx; }
.LBB0_799:
	s_waitcnt vmcnt(0)
	s_waitcnt lgkmcnt(0)
	s_barrier
	s_setprio 0
	s_and_saveexec_b64 s[0:1], s[92:93]
	s_cbranch_execz .LBB0_851
	s_add_i32 s3, 0, 0x20400
	v_mov_b32_e32 v0, s3
	s_waitcnt vmcnt(0) expcnt(0) lgkmcnt(0)
	ds_read_b32 v2, v0
	s_add_i32 s3, 0, 0x20404
	v_mov_b32_e32 v0, s3
	ds_read_b32 v0, v0
	s_waitcnt lgkmcnt(1)
	v_cmp_ne_u32_e32 vcc, 0, v2
	s_cbranch_vccnz .LBB0_815
	s_add_u32 s4, s28, 0x180200
	s_addc_u32 s5, s29, 0
	s_add_u32 s6, s28, 0x180400
	s_addc_u32 s7, s29, 0
	s_add_u32 s10, s28, 0x180500
	s_addc_u32 s11, s29, 0
	s_add_u32 s12, s28, 0x180600
	s_addc_u32 s13, s29, 0
	s_add_u32 s14, s28, 0x180700
	s_addc_u32 s15, s29, 0
	s_add_u32 s38, s28, 0x180800
	s_addc_u32 s39, s29, 0
	s_add_u32 s40, s28, 0x180900
	s_addc_u32 s41, s29, 0
	s_add_u32 s42, s28, 0x180a00
	s_addc_u32 s43, s29, 0
	s_add_u32 s44, s28, 0x180b00
	s_addc_u32 s45, s29, 0
	s_add_u32 s46, s28, 0x180c00
	s_addc_u32 s47, s29, 0
	s_add_u32 s48, s28, 0x180d00
	s_addc_u32 s49, s29, 0
	s_add_u32 s50, s28, 0x180e00
	s_addc_u32 s51, s29, 0
	s_add_u32 s52, s28, 0x180f00
	s_addc_u32 s53, s29, 0
	s_add_u32 s54, s28, 0x181000
	s_addc_u32 s55, s29, 0
	s_add_u32 s56, s28, 0x181100
	s_addc_u32 s57, s29, 0
	s_add_u32 s58, s28, 0x181200
	v_readlane_b32 s3, v253, 0
	s_addc_u32 s59, s29, 0
	s_mul_i32 s3, s31, s3
	s_add_u32 s60, s28, 0x181300
	s_mul_i32 s3, s3, s30
	s_addc_u32 s61, s29, 0
	s_mov_b32 s72, 1
	v_mov_b32_e32 v16, 0
	s_branch .LBB0_803

; #define PG8_LAS __attribute__((address_space(3)))
;     __device__ bool next(int i, Unit& u) const { if (!so.next(i >> 1, u)) return false; u.sel = i & 1; return true; }
;     __host__ __device__ bool next(int i, Unit& u) const {
;         const long L = (long)i * G + c; if (L >= nwg) return false;
;         int wgid = (int)L; { const int q = nwg / NXCD, r = nwg % NXCD, xcd = wgid % NXCD, off = wgid / NXCD; wgid = (xcd < r ? xcd * (q + 1) : r * (q + 1) + (xcd - r) * q) + off; }
;         const int nig = WGM * nN, gid = wgid / nig, fm = gid * WGM, gsz = (nM - fm) < WGM ? (nM - fm) : WGM;
;         u.pm = fm + ((wgid % nig) % gsz); u.pn = (wgid % nig) / gsz; u.sel = 0; return true;
; template <class Epi, class Sched, bool ALIGN_EPI = false, bool SP2 = false>
; __device__ __forceinline__ void gemm_phase(PG8_LAS unsigned char* lds, const Gemm g, const Sched& S, const Epi& E) {
;     int tid_ = threadIdx.x; asm volatile("" : "+v"(tid_));
;     const int tid = tid_, wid = __builtin_amdgcn_readfirstlane(tid >> 6), lane = tid & 63, wr = wid >> 2, wc = wid & 3, fr = lane & 15, fq = lane >> 4;
;     int K_ = g.K; asm volatile("" : "+s"(K_));
;     const int K = K_, nt = K / BK;
;     unsigned voffA[2], voffB[2];
; #pragma unroll
;     for (int i = 0; i < 2; ++i) { int R, C; stage_rc(tid * 16 + i * 8192, R, C); const int Rb = Epi::PERM ? ((R & ~31) + perm32(R & 31)) : R;
;         voffA[i] = (unsigned)(R * K + C) * 2u; voffB[i] = (unsigned)(Rb * K + C) * 2u; }
;     const size_t kstep = (size_t)(BK * 2);
;     const size_t hstep = (size_t)HALF * K * 2;
;     const size_t tstep = 2 * hstep;
;     const unsigned ldsw = (unsigned)wid * 1024u;
;     const int aoff = lds_byte(wr * 64 + fr, fq * 8), boff = lds_byte(wc * 32 + fr, fq * 8);
;     ...
;     Unit cur, nxt; int ui = 0;
;     if (!S.next(0, cur)) return;
.Lprio6_skip:
	v_mov_b32_e32 v12, v201
	s_waitcnt lgkmcnt(0)
	s_barrier
	s_movk_i32 s0, 0x400
	v_readfirstlane_b32 s6, v12
	s_and_b64 vcc, exec, s[8:9]
	s_cbranch_vccnz .LBB0_857
	s_ashr_i32 s1, s2, 31
	s_lshr_b32 s1, s1, 29
	s_add_i32 s1, s2, s1
	s_and_b32 s3, s1, -8
	s_sub_i32 s3, s2, s3
	s_cmp_gt_i32 s3, -1
	s_cbranch_scc0 .LBB0_854
	s_lshl_b32 s7, s3, 7
	s_cbranch_execz .LBB0_855
	s_branch .LBB0_856

; #define PG8_STAGE(bufoff, gbase, voff) do { _Pragma("unroll") for (int _i = 0; _i < 2; ++_i) \
;         __builtin_amdgcn_global_load_lds((const unsigned*)((const char*)(gbase) + (voff)[_i]), (PG8_LAS unsigned*)(lds + (bufoff) + ldsw + _i * 8192), 16, 0, 0); } while (0)
; #define PG8_LDA(dst, b, h) do { _Pragma("unroll") for (int m = 0; m < 4; ++m) _Pragma("unroll") for (int k = 0; k < 2; ++k) dst[m][k] = *(const PG8_LAS bf16x8*)(lds + PG8_SA(b, h) + aoff + m * 2048 + k * 1024); } while (0)
; #define PG8_LDB(dst, b, h) do { _Pragma("unroll") for (int n = 0; n < 2; ++n) _Pragma("unroll") for (int k = 0; k < 2; ++k) dst[n][k] = *(const PG8_LAS bf16x8*)(lds + PG8_SB(b, h) + boff + n * 2048 + k * 1024); } while (0)
; #define PG8_MMA(ai, bj, At, Bt) do { __builtin_amdgcn_s_setprio(1); _Pragma("unroll") for (int m = 0; m < 4; ++m) _Pragma("unroll") for (int n = 0; n < 2; ++n) _Pragma("unroll") for (int k = 0; k < 2; ++k) \
;         acc[ai][bj][m][n] = __builtin_amdgcn_mfma_f32_16x16x32_bf16(Bt[n][k], At[m][k], acc[ai][bj][m][n], 0, 0, 0); __builtin_amdgcn_s_setprio(0); } while (0)
; #define PG8_WAIT_V(n) asm volatile("s_waitcnt vmcnt(" #n ")" ::: "memory")
; #define PG8_BAR __builtin_amdgcn_s_barrier()
; template <class Epi, class Sched, bool ALIGN_EPI = false, bool SP2 = false>
; __device__ __forceinline__ void gemm_phase(PG8_LAS unsigned char* lds, const Gemm g, const Sched& S, const Epi& E) {
;     ...
;         for (int t = 0; t < nt; t += 2) {
;             const bool last = (t == nt - 2);
;             const char* a1 = cA + (size_t)(t + 1) * kstep;
;             const char* a2 = last ? nA : cA + (size_t)(t + 2) * kstep; const char* b2 = last ? nB : cB + (size_t)(t + 2) * kstep;
;             const char* a3 = a2 + kstep; const char* b3 = b2 + kstep;
;             if (last && has_next) S.a_ready(nxt);
;             if constexpr (SP2) {
;             PG8_LDB(B0, 0, 0); PG8_LDB(B1, 0, 1); PG8_SCHED; PG8_LDA(At, 0, 0); PG8_STAGE(PG8_SA(1, 1), a1 + hstep, voffA);
;             PG8_WAIT_V(8); PG8_WAIT_L(0); PG8_BAR; PG8_MMA(0, 0, At, B0); PG8_MMA(0, 1, At, B1); PG8_BAR; PG8_SCHED;
;             PG8_LDA(At, 0, 1); PG8_STAGE(PG8_SB(0, 0), b2, voffB); PG8_STAGE(PG8_SB(0, 1), b2 + hstep, voffB); PG8_STAGE(PG8_SA(0, 0), a2, voffA);
;             PG8_WAIT_V(8); PG8_WAIT_L(0); PG8_BAR; PG8_MMA(1, 0, At, B0); PG8_MMA(1, 1, At, B1); PG8_BAR; PG8_SCHED;
.Lcz_go_875:
	s_add_u32 s50, s50, 0x80
	s_addc_u32 s51, s51, 0
	s_add_u32 s78, s52, 0x100
	s_addc_u32 s79, s53, 0
	s_mov_b32 s52, 0
	ds_read_b128 v[144:147], v151
	ds_read_b128 v[156:159], v151 offset:1024
	ds_read_b128 v[160:163], v151 offset:2048
	ds_read_b128 v[164:167], v151 offset:3072
	ds_read_b128 v[168:171], v152
	ds_read_b128 v[172:175], v152 offset:1024
	ds_read_b128 v[176:179], v152 offset:2048
	ds_read_b128 v[180:183], v152 offset:3072
	s_add_i32 s80, s52, 2
	s_add_u32 s16, s50, 0x80
	s_addc_u32 s17, s51, 0
	s_cmp_eq_u32 s68, s52
	s_cselect_b32 s52, s0, s16
	s_cselect_b32 s53, s1, s17
	s_cselect_b32 s83, s49, s79
	s_cselect_b32 s82, s48, s78
	v_lshl_add_u64 v[218:219], s[50:51], 0, v[136:137]
	s_add_i32 m0, s56, 0xc000
	ds_read_b128 v[184:187], v153
	ds_read_b128 v[188:191], v153 offset:1024
	ds_read_b128 v[192:195], v153 offset:2048
	ds_read_b128 v[196:199], v153 offset:3072
	ds_read_b128 v[202:205], v153 offset:4096
	ds_read_b128 v[206:209], v153 offset:5120
	ds_read_b128 v[210:213], v153 offset:6144
	ds_read_b128 v[214:217], v153 offset:7168
	global_load_lds_dwordx4 v[218:219], off
	v_lshl_add_u64 v[218:219], s[50:51], 0, v[138:139]
	s_add_i32 m0, s56, 0xe000
	s_nop 0
	global_load_lds_dwordx4 v[218:219], off
	s_waitcnt vmcnt(8)
	s_waitcnt lgkmcnt(0)
	s_barrier
	s_waitcnt lgkmcnt(0)
	v_mfma_f32_16x16x32_bf16 v[124:127], v[144:147], v[184:187], 0
	v_mfma_f32_16x16x32_bf16 v[120:123], v[160:163], v[184:187], 0
	v_mfma_f32_16x16x32_bf16 v[108:111], v[144:147], v[192:195], 0
	v_mfma_f32_16x16x32_bf16 v[104:107], v[160:163], v[192:195], 0
	v_mfma_f32_16x16x32_bf16 v[92:95], v[144:147], v[202:205], 0
	v_mfma_f32_16x16x32_bf16 v[88:91], v[160:163], v[202:205], 0
	v_mfma_f32_16x16x32_bf16 v[76:79], v[144:147], v[210:213], 0
	v_mfma_f32_16x16x32_bf16 v[72:75], v[160:163], v[210:213], 0
	v_mfma_f32_16x16x32_bf16 v[124:127], v[156:159], v[188:191], v[124:127]
	v_mfma_f32_16x16x32_bf16 v[120:123], v[164:167], v[188:191], v[120:123]
	v_mfma_f32_16x16x32_bf16 v[108:111], v[156:159], v[196:199], v[108:111]
	v_mfma_f32_16x16x32_bf16 v[104:107], v[164:167], v[196:199], v[104:107]
	v_mfma_f32_16x16x32_bf16 v[92:95], v[156:159], v[206:209], v[92:95]
	v_mfma_f32_16x16x32_bf16 v[88:91], v[164:167], v[206:209], v[88:91]
	v_mfma_f32_16x16x32_bf16 v[76:79], v[156:159], v[214:217], v[76:79]
	v_mfma_f32_16x16x32_bf16 v[72:75], v[164:167], v[214:217], v[72:75]
	v_mfma_f32_16x16x32_bf16 v[116:119], v[168:171], v[184:187], 0
	v_mfma_f32_16x16x32_bf16 v[112:115], v[176:179], v[184:187], 0
	v_mfma_f32_16x16x32_bf16 v[100:103], v[168:171], v[192:195], 0
	v_mfma_f32_16x16x32_bf16 v[96:99], v[176:179], v[192:195], 0
	v_mfma_f32_16x16x32_bf16 v[84:87], v[168:171], v[202:205], 0
	v_mfma_f32_16x16x32_bf16 v[80:83], v[176:179], v[202:205], 0
	v_mfma_f32_16x16x32_bf16 v[68:71], v[168:171], v[210:213], 0
	v_mfma_f32_16x16x32_bf16 v[64:67], v[176:179], v[210:213], 0
	v_mfma_f32_16x16x32_bf16 v[116:119], v[172:175], v[188:191], v[116:119]
	v_mfma_f32_16x16x32_bf16 v[112:115], v[180:183], v[188:191], v[112:115]
	v_mfma_f32_16x16x32_bf16 v[100:103], v[172:175], v[196:199], v[100:103]
	v_mfma_f32_16x16x32_bf16 v[96:99], v[180:183], v[196:199], v[96:99]
	v_mfma_f32_16x16x32_bf16 v[84:87], v[172:175], v[206:209], v[84:87]
	v_mfma_f32_16x16x32_bf16 v[80:83], v[180:183], v[206:209], v[80:83]
	v_mfma_f32_16x16x32_bf16 v[68:71], v[172:175], v[214:217], v[68:71]
	v_mfma_f32_16x16x32_bf16 v[64:67], v[180:183], v[214:217], v[64:67]
	s_barrier
	s_add_i32 s16, s72, s55
	v_lshl_add_u64 v[218:219], s[82:83], 0, v[130:131]
	s_mov_b32 m0, s16
	ds_read_b128 v[184:187], v153 offset:16384
	ds_read_b128 v[188:191], v153 offset:17408
	ds_read_b128 v[192:195], v153 offset:18432
	ds_read_b128 v[196:199], v153 offset:19456
	ds_read_b128 v[202:205], v153 offset:20480
	ds_read_b128 v[206:209], v153 offset:21504
	ds_read_b128 v[210:213], v153 offset:22528
	ds_read_b128 v[214:217], v153 offset:23552
	global_load_lds_dwordx4 v[218:219], off
	s_add_i32 m0, s16, 0x2000
	v_lshl_add_u64 v[220:221], s[82:83], 0, v[134:135]
	s_add_u32 s82, s82, s12
	s_addc_u32 s83, s83, s13
	s_add_i32 s16, s73, s55
	global_load_lds_dwordx4 v[220:221], off
	v_lshl_add_u64 v[222:223], s[82:83], 0, v[130:131]
	s_mov_b32 m0, s16
	v_lshl_add_u64 v[224:225], s[82:83], 0, v[134:135]
	global_load_lds_dwordx4 v[222:223], off
	s_add_i32 m0, s16, 0x2000
	v_lshl_add_u64 v[226:227], s[52:53], 0, v[128:129]
	global_load_lds_dwordx4 v[224:225], off
	s_mov_b32 m0, s56
	v_lshl_add_u64 v[228:229], s[52:53], 0, v[132:133]
	global_load_lds_dwordx4 v[226:227], off
	s_mov_b32 m0, s57
	s_nop 0
	global_load_lds_dwordx4 v[228:229], off
	s_waitcnt vmcnt(8)
	s_waitcnt lgkmcnt(0)
	s_barrier
; #define PG8_STAGE(bufoff, gbase, voff) do { _Pragma("unroll") for (int _i = 0; _i < 2; ++_i) \
;         __builtin_amdgcn_global_load_lds((const unsigned*)((const char*)(gbase) + (voff)[_i]), (PG8_LAS unsigned*)(lds + (bufoff) + ldsw + _i * 8192), 16, 0, 0); } while (0)
; #define PG8_LDA(dst, b, h) do { _Pragma("unroll") for (int m = 0; m < 4; ++m) _Pragma("unroll") for (int k = 0; k < 2; ++k) dst[m][k] = *(const PG8_LAS bf16x8*)(lds + PG8_SA(b, h) + aoff + m * 2048 + k * 1024); } while (0)
; #define PG8_LDB(dst, b, h) do { _Pragma("unroll") for (int n = 0; n < 2; ++n) _Pragma("unroll") for (int k = 0; k < 2; ++k) dst[n][k] = *(const PG8_LAS bf16x8*)(lds + PG8_SB(b, h) + boff + n * 2048 + k * 1024); } while (0)
; #define PG8_MMA(ai, bj, At, Bt) do { __builtin_amdgcn_s_setprio(1); _Pragma("unroll") for (int m = 0; m < 4; ++m) _Pragma("unroll") for (int n = 0; n < 2; ++n) _Pragma("unroll") for (int k = 0; k < 2; ++k) \
;         acc[ai][bj][m][n] = __builtin_amdgcn_mfma_f32_16x16x32_bf16(Bt[n][k], At[m][k], acc[ai][bj][m][n], 0, 0, 0); __builtin_amdgcn_s_setprio(0); } while (0)
; #define PG8_WAIT_V(n) asm volatile("s_waitcnt vmcnt(" #n ")" ::: "memory")
; #define PG8_WAIT_L(n) asm volatile("s_waitcnt lgkmcnt(" #n ")" ::: "memory")
; #define PG8_BAR __builtin_amdgcn_s_barrier()
; #define PG8_SCHED __builtin_amdgcn_sched_barrier(0)
; template <class Epi, class Sched, bool ALIGN_EPI = false, bool SP2 = false>
; __device__ __forceinline__ void gemm_phase(PG8_LAS unsigned char* lds, const Gemm g, const Sched& S, const Epi& E) {
;     ...
;             if constexpr (SP2) {
;             PG8_LDB(B0, 0, 0); PG8_LDB(B1, 0, 1); PG8_SCHED; PG8_LDA(At, 0, 0); PG8_STAGE(PG8_SA(1, 1), a1 + hstep, voffA);
;             PG8_WAIT_V(8); PG8_WAIT_L(0); PG8_BAR; PG8_MMA(0, 0, At, B0); PG8_MMA(0, 1, At, B1); PG8_BAR; PG8_SCHED;
;             PG8_LDA(At, 0, 1); PG8_STAGE(PG8_SB(0, 0), b2, voffB); PG8_STAGE(PG8_SB(0, 1), b2 + hstep, voffB); PG8_STAGE(PG8_SA(0, 0), a2, voffA);
;             PG8_WAIT_V(8); PG8_WAIT_L(0); PG8_BAR; PG8_MMA(1, 0, At, B0); PG8_MMA(1, 1, At, B1); PG8_BAR; PG8_SCHED;
;             PG8_LDB(B0, 1, 0); PG8_LDB(B1, 1, 1); PG8_SCHED; PG8_LDA(At, 1, 0); PG8_STAGE(PG8_SA(0, 1), a2 + hstep, voffA);
;             PG8_WAIT_V(8); PG8_WAIT_L(0); PG8_BAR; PG8_MMA(0, 0, At, B0); PG8_MMA(0, 1, At, B1); PG8_BAR; PG8_SCHED;
	s_waitcnt lgkmcnt(0)
	v_mfma_f32_16x16x32_bf16 v[60:63], v[144:147], v[184:187], 0
	v_mfma_f32_16x16x32_bf16 v[56:59], v[160:163], v[184:187], 0
	v_mfma_f32_16x16x32_bf16 v[44:47], v[144:147], v[192:195], 0
	v_mfma_f32_16x16x32_bf16 v[40:43], v[160:163], v[192:195], 0
	v_mfma_f32_16x16x32_bf16 v[28:31], v[144:147], v[202:205], 0
	v_mfma_f32_16x16x32_bf16 v[24:27], v[160:163], v[202:205], 0
	v_mfma_f32_16x16x32_bf16 v[12:15], v[144:147], v[210:213], 0
	v_mfma_f32_16x16x32_bf16 v[8:11], v[160:163], v[210:213], 0
	v_mfma_f32_16x16x32_bf16 v[60:63], v[156:159], v[188:191], v[60:63]
	v_mfma_f32_16x16x32_bf16 v[56:59], v[164:167], v[188:191], v[56:59]
	v_mfma_f32_16x16x32_bf16 v[44:47], v[156:159], v[196:199], v[44:47]
	v_mfma_f32_16x16x32_bf16 v[40:43], v[164:167], v[196:199], v[40:43]
	v_mfma_f32_16x16x32_bf16 v[28:31], v[156:159], v[206:209], v[28:31]
	v_mfma_f32_16x16x32_bf16 v[24:27], v[164:167], v[206:209], v[24:27]
	v_mfma_f32_16x16x32_bf16 v[12:15], v[156:159], v[214:217], v[12:15]
	v_mfma_f32_16x16x32_bf16 v[8:11], v[164:167], v[214:217], v[8:11]
	v_mfma_f32_16x16x32_bf16 v[52:55], v[168:171], v[184:187], 0
	v_mfma_f32_16x16x32_bf16 v[48:51], v[176:179], v[184:187], 0
	v_mfma_f32_16x16x32_bf16 v[36:39], v[168:171], v[192:195], 0
	v_mfma_f32_16x16x32_bf16 v[32:35], v[176:179], v[192:195], 0
	v_mfma_f32_16x16x32_bf16 v[20:23], v[168:171], v[202:205], 0
	v_mfma_f32_16x16x32_bf16 v[16:19], v[176:179], v[202:205], 0
	v_mfma_f32_16x16x32_bf16 v[4:7], v[168:171], v[210:213], 0
	v_mfma_f32_16x16x32_bf16 v[0:3], v[176:179], v[210:213], 0
	v_mfma_f32_16x16x32_bf16 v[52:55], v[172:175], v[188:191], v[52:55]
	v_mfma_f32_16x16x32_bf16 v[48:51], v[180:183], v[188:191], v[48:51]
	v_mfma_f32_16x16x32_bf16 v[36:39], v[172:175], v[196:199], v[36:39]
	v_mfma_f32_16x16x32_bf16 v[32:35], v[180:183], v[196:199], v[32:35]
	v_mfma_f32_16x16x32_bf16 v[20:23], v[172:175], v[206:209], v[20:23]
	v_mfma_f32_16x16x32_bf16 v[16:19], v[180:183], v[206:209], v[16:19]
	v_mfma_f32_16x16x32_bf16 v[4:7], v[172:175], v[214:217], v[4:7]
	v_mfma_f32_16x16x32_bf16 v[0:3], v[180:183], v[214:217], v[0:3]
	s_barrier
	s_add_i32 s16, 0, 0x18000
	v_add_u32_e32 v155, s16, v149
	s_add_i32 s17, 0, 0x1c000
	ds_read_b128 v[144:147], v155
	ds_read_b128 v[156:159], v155 offset:1024
	ds_read_b128 v[160:163], v155 offset:2048
	ds_read_b128 v[164:167], v155 offset:3072
	v_add_u32_e32 v155, s17, v149
	ds_read_b128 v[168:171], v155
	ds_read_b128 v[172:175], v155 offset:1024
	ds_read_b128 v[176:179], v155 offset:2048
	ds_read_b128 v[180:183], v155 offset:3072
	s_add_u32 s52, s52, s12
	s_addc_u32 s53, s53, s13
	s_mov_b32 m0, s58
	v_lshl_add_u64 v[230:231], s[52:53], 0, v[128:129]
	ds_read_b128 v[184:187], v153 offset:32768
	ds_read_b128 v[188:191], v153 offset:33792
	ds_read_b128 v[192:195], v153 offset:34816
	ds_read_b128 v[196:199], v153 offset:35840
	ds_read_b128 v[202:205], v153 offset:36864
	ds_read_b128 v[206:209], v153 offset:37888
	ds_read_b128 v[210:213], v153 offset:38912
	ds_read_b128 v[214:217], v153 offset:39936
	global_load_lds_dwordx4 v[230:231], off
	v_lshl_add_u64 v[230:231], s[52:53], 0, v[132:133]
	s_mov_b32 m0, s59
	s_nop 0
	global_load_lds_dwordx4 v[230:231], off
	s_waitcnt vmcnt(8)
	s_waitcnt lgkmcnt(0)
	s_barrier
	s_waitcnt lgkmcnt(0)
	v_mfma_f32_16x16x32_bf16 v[124:127], v[144:147], v[184:187], v[124:127]
	v_mfma_f32_16x16x32_bf16 v[120:123], v[160:163], v[184:187], v[120:123]
	v_mfma_f32_16x16x32_bf16 v[108:111], v[144:147], v[192:195], v[108:111]
	v_mfma_f32_16x16x32_bf16 v[104:107], v[160:163], v[192:195], v[104:107]
	v_mfma_f32_16x16x32_bf16 v[92:95], v[144:147], v[202:205], v[92:95]
	v_mfma_f32_16x16x32_bf16 v[88:91], v[160:163], v[202:205], v[88:91]
	v_mfma_f32_16x16x32_bf16 v[76:79], v[144:147], v[210:213], v[76:79]
	v_mfma_f32_16x16x32_bf16 v[72:75], v[160:163], v[210:213], v[72:75]
	v_mfma_f32_16x16x32_bf16 v[124:127], v[156:159], v[188:191], v[124:127]
	v_mfma_f32_16x16x32_bf16 v[120:123], v[164:167], v[188:191], v[120:123]
	v_mfma_f32_16x16x32_bf16 v[108:111], v[156:159], v[196:199], v[108:111]
	v_mfma_f32_16x16x32_bf16 v[104:107], v[164:167], v[196:199], v[104:107]
	v_mfma_f32_16x16x32_bf16 v[92:95], v[156:159], v[206:209], v[92:95]
	v_mfma_f32_16x16x32_bf16 v[88:91], v[164:167], v[206:209], v[88:91]
	v_mfma_f32_16x16x32_bf16 v[76:79], v[156:159], v[214:217], v[76:79]
	v_mfma_f32_16x16x32_bf16 v[72:75], v[164:167], v[214:217], v[72:75]
	v_mfma_f32_16x16x32_bf16 v[116:119], v[168:171], v[184:187], v[116:119]
	v_mfma_f32_16x16x32_bf16 v[112:115], v[176:179], v[184:187], v[112:115]
	v_mfma_f32_16x16x32_bf16 v[100:103], v[168:171], v[192:195], v[100:103]
	v_mfma_f32_16x16x32_bf16 v[96:99], v[176:179], v[192:195], v[96:99]
	v_mfma_f32_16x16x32_bf16 v[84:87], v[168:171], v[202:205], v[84:87]
	v_mfma_f32_16x16x32_bf16 v[80:83], v[176:179], v[202:205], v[80:83]
	v_mfma_f32_16x16x32_bf16 v[68:71], v[168:171], v[210:213], v[68:71]
	v_mfma_f32_16x16x32_bf16 v[64:67], v[176:179], v[210:213], v[64:67]
	v_mfma_f32_16x16x32_bf16 v[116:119], v[172:175], v[188:191], v[116:119]
	v_mfma_f32_16x16x32_bf16 v[112:115], v[180:183], v[188:191], v[112:115]
	v_mfma_f32_16x16x32_bf16 v[100:103], v[172:175], v[196:199], v[100:103]
	v_mfma_f32_16x16x32_bf16 v[96:99], v[180:183], v[196:199], v[96:99]
	v_mfma_f32_16x16x32_bf16 v[84:87], v[172:175], v[206:209], v[84:87]
	v_mfma_f32_16x16x32_bf16 v[80:83], v[180:183], v[206:209], v[80:83]
	v_mfma_f32_16x16x32_bf16 v[68:71], v[172:175], v[214:217], v[68:71]
	v_mfma_f32_16x16x32_bf16 v[64:67], v[180:183], v[214:217], v[64:67]
	s_barrier
; #define PG8_STAGE(bufoff, gbase, voff) do { _Pragma("unroll") for (int _i = 0; _i < 2; ++_i) \
;         __builtin_amdgcn_global_load_lds((const unsigned*)((const char*)(gbase) + (voff)[_i]), (PG8_LAS unsigned*)(lds + (bufoff) + ldsw + _i * 8192), 16, 0, 0); } while (0)
; #define PG8_LDA(dst, b, h) do { _Pragma("unroll") for (int m = 0; m < 4; ++m) _Pragma("unroll") for (int k = 0; k < 2; ++k) dst[m][k] = *(const PG8_LAS bf16x8*)(lds + PG8_SA(b, h) + aoff + m * 2048 + k * 1024); } while (0)
; #define PG8_LDB(dst, b, h) do { _Pragma("unroll") for (int n = 0; n < 2; ++n) _Pragma("unroll") for (int k = 0; k < 2; ++k) dst[n][k] = *(const PG8_LAS bf16x8*)(lds + PG8_SB(b, h) + boff + n * 2048 + k * 1024); } while (0)
; template <class Epi, class Sched, bool ALIGN_EPI = false, bool SP2 = false>
; __device__ __forceinline__ void gemm_phase(PG8_LAS unsigned char* lds, const Gemm g, const Sched& S, const Epi& E) {
;     ...
;         for (int t = 0; t < nt; t += 2) {
;             const bool last = (t == nt - 2);
;             const char* a1 = cA + (size_t)(t + 1) * kstep;
;             const char* a2 = last ? nA : cA + (size_t)(t + 2) * kstep; const char* b2 = last ? nB : cB + (size_t)(t + 2) * kstep;
;             const char* a3 = a2 + kstep; const char* b3 = b2 + kstep;
;             if (last && has_next) S.a_ready(nxt);
;             if constexpr (SP2) {
;             PG8_LDB(B0, 0, 0); PG8_LDB(B1, 0, 1); PG8_SCHED; PG8_LDA(At, 0, 0); PG8_STAGE(PG8_SA(1, 1), a1 + hstep, voffA);
;             PG8_WAIT_V(8); PG8_WAIT_L(0); PG8_BAR; PG8_MMA(0, 0, At, B0); PG8_MMA(0, 1, At, B1); PG8_BAR; PG8_SCHED;
;             PG8_LDA(At, 0, 1); PG8_STAGE(PG8_SB(0, 0), b2, voffB); PG8_STAGE(PG8_SB(0, 1), b2 + hstep, voffB); PG8_STAGE(PG8_SA(0, 0), a2, voffA);
;             PG8_WAIT_V(8); PG8_WAIT_L(0); PG8_BAR; PG8_MMA(1, 0, At, B0); PG8_MMA(1, 1, At, B1); PG8_BAR; PG8_SCHED;
;             PG8_LDB(B0, 1, 0); PG8_LDB(B1, 1, 1); PG8_SCHED; PG8_LDA(At, 1, 0); PG8_STAGE(PG8_SA(0, 1), a2 + hstep, voffA);
;             PG8_WAIT_V(8); PG8_WAIT_L(0); PG8_BAR; PG8_MMA(0, 0, At, B0); PG8_MMA(0, 1, At, B1); PG8_BAR; PG8_SCHED;
;             PG8_LDA(At, 1, 1); PG8_STAGE(PG8_SB(1, 0), b3, voffB); PG8_STAGE(PG8_SB(1, 1), b3 + hstep, voffB); PG8_STAGE(PG8_SA(1, 0), a3, voffA);
;             PG8_WAIT_V(8); PG8_WAIT_L(0); PG8_BAR; PG8_MMA(1, 0, At, B0); PG8_MMA(1, 1, At, B1); PG8_BAR; PG8_SCHED;
	s_add_i32 s16, s16, s55
	v_lshl_add_u64 v[218:219], v[218:219], 0, s[42:43]
	s_mov_b32 m0, s16
	ds_read_b128 v[184:187], v153 offset:49152
	ds_read_b128 v[188:191], v153 offset:50176
	ds_read_b128 v[192:195], v153 offset:51200
	ds_read_b128 v[196:199], v153 offset:52224
	ds_read_b128 v[202:205], v153 offset:53248
	ds_read_b128 v[206:209], v153 offset:54272
	ds_read_b128 v[210:213], v153 offset:55296
	ds_read_b128 v[214:217], v153 offset:56320
	global_load_lds_dwordx4 v[218:219], off
	v_lshl_add_u64 v[218:219], v[220:221], 0, s[42:43]
	s_add_i32 m0, s16, 0x2000
	s_add_i32 s16, s17, s55
	global_load_lds_dwordx4 v[218:219], off
	v_lshl_add_u64 v[218:219], v[222:223], 0, s[42:43]
	s_mov_b32 m0, s16
	s_nop 0
	global_load_lds_dwordx4 v[218:219], off
	v_lshl_add_u64 v[218:219], v[224:225], 0, s[42:43]
	s_add_i32 m0, s16, 0x2000
	s_nop 0
	global_load_lds_dwordx4 v[218:219], off
	v_lshl_add_u64 v[218:219], v[226:227], 0, s[42:43]
	s_mov_b32 m0, s60
	s_nop 0
	global_load_lds_dwordx4 v[218:219], off
	v_lshl_add_u64 v[218:219], v[228:229], 0, s[42:43]
	s_mov_b32 m0, s61
	s_nop 0
	global_load_lds_dwordx4 v[218:219], off
	s_waitcnt vmcnt(8)
	s_waitcnt lgkmcnt(0)
	s_barrier
	s_waitcnt lgkmcnt(0)
	v_mfma_f32_16x16x32_bf16 v[60:63], v[144:147], v[184:187], v[60:63]
	v_mfma_f32_16x16x32_bf16 v[56:59], v[160:163], v[184:187], v[56:59]
	v_mfma_f32_16x16x32_bf16 v[44:47], v[144:147], v[192:195], v[44:47]
	v_mfma_f32_16x16x32_bf16 v[40:43], v[160:163], v[192:195], v[40:43]
	v_mfma_f32_16x16x32_bf16 v[28:31], v[144:147], v[202:205], v[28:31]
	v_mfma_f32_16x16x32_bf16 v[24:27], v[160:163], v[202:205], v[24:27]
	v_mfma_f32_16x16x32_bf16 v[12:15], v[144:147], v[210:213], v[12:15]
	v_mfma_f32_16x16x32_bf16 v[8:11], v[160:163], v[210:213], v[8:11]
	v_mfma_f32_16x16x32_bf16 v[60:63], v[156:159], v[188:191], v[60:63]
	v_mfma_f32_16x16x32_bf16 v[56:59], v[164:167], v[188:191], v[56:59]
	v_mfma_f32_16x16x32_bf16 v[44:47], v[156:159], v[196:199], v[44:47]
	v_mfma_f32_16x16x32_bf16 v[40:43], v[164:167], v[196:199], v[40:43]
	v_mfma_f32_16x16x32_bf16 v[28:31], v[156:159], v[206:209], v[28:31]
	v_mfma_f32_16x16x32_bf16 v[24:27], v[164:167], v[206:209], v[24:27]
	v_mfma_f32_16x16x32_bf16 v[12:15], v[156:159], v[214:217], v[12:15]
	v_mfma_f32_16x16x32_bf16 v[8:11], v[164:167], v[214:217], v[8:11]
	v_mfma_f32_16x16x32_bf16 v[52:55], v[168:171], v[184:187], v[52:55]
	v_mfma_f32_16x16x32_bf16 v[48:51], v[176:179], v[184:187], v[48:51]
	v_mfma_f32_16x16x32_bf16 v[36:39], v[168:171], v[192:195], v[36:39]
	v_mfma_f32_16x16x32_bf16 v[32:35], v[176:179], v[192:195], v[32:35]
	v_mfma_f32_16x16x32_bf16 v[20:23], v[168:171], v[202:205], v[20:23]
	v_mfma_f32_16x16x32_bf16 v[16:19], v[176:179], v[202:205], v[16:19]
	v_mfma_f32_16x16x32_bf16 v[4:7], v[168:171], v[210:213], v[4:7]
	v_mfma_f32_16x16x32_bf16 v[0:3], v[176:179], v[210:213], v[0:3]
	v_mfma_f32_16x16x32_bf16 v[52:55], v[172:175], v[188:191], v[52:55]
	v_mfma_f32_16x16x32_bf16 v[48:51], v[180:183], v[188:191], v[48:51]
	v_mfma_f32_16x16x32_bf16 v[36:39], v[172:175], v[196:199], v[36:39]
	v_mfma_f32_16x16x32_bf16 v[32:35], v[180:183], v[196:199], v[32:35]
	v_mfma_f32_16x16x32_bf16 v[20:23], v[172:175], v[206:209], v[20:23]
	v_mfma_f32_16x16x32_bf16 v[16:19], v[180:183], v[206:209], v[16:19]
	v_mfma_f32_16x16x32_bf16 v[4:7], v[172:175], v[214:217], v[4:7]
	v_mfma_f32_16x16x32_bf16 v[0:3], v[180:183], v[214:217], v[0:3]
	s_barrier
	s_add_u32 s50, s50, 0x100
	s_addc_u32 s51, s51, 0
	s_add_u32 s78, s78, 0x100
	s_addc_u32 s79, s79, 0
	s_cmp_ge_i32 s80, s63
	s_mov_b32 s52, s80
	s_cbranch_scc1 .LBB0_876
.LBB0_875:
	ds_read_b128 v[144:147], v151
	ds_read_b128 v[156:159], v151 offset:1024
	ds_read_b128 v[160:163], v151 offset:2048
	ds_read_b128 v[164:167], v151 offset:3072
	ds_read_b128 v[168:171], v152
	ds_read_b128 v[172:175], v152 offset:1024
	ds_read_b128 v[176:179], v152 offset:2048
	ds_read_b128 v[180:183], v152 offset:3072
	s_add_i32 s80, s52, 2
	s_add_u32 s16, s50, 0x80
	s_addc_u32 s17, s51, 0
	s_cmp_eq_u32 s68, s52
	s_cselect_b32 s52, s0, s16
	s_cselect_b32 s53, s1, s17
	s_cselect_b32 s83, s49, s79
	s_cselect_b32 s82, s48, s78
	v_lshl_add_u64 v[218:219], s[50:51], 0, v[136:137]
	s_add_i32 m0, s56, 0xc000
	ds_read_b128 v[184:187], v153
	ds_read_b128 v[188:191], v153 offset:1024
	ds_read_b128 v[192:195], v153 offset:2048
	ds_read_b128 v[196:199], v153 offset:3072
	ds_read_b128 v[202:205], v153 offset:4096
	ds_read_b128 v[206:209], v153 offset:5120
	ds_read_b128 v[210:213], v153 offset:6144
	ds_read_b128 v[214:217], v153 offset:7168
	global_load_lds_dwordx4 v[218:219], off
	v_lshl_add_u64 v[218:219], s[50:51], 0, v[138:139]
	s_add_i32 m0, s56, 0xe000
	s_nop 0
	global_load_lds_dwordx4 v[218:219], off
	s_waitcnt vmcnt(8)
	s_waitcnt lgkmcnt(0)
	s_barrier
; #define PG8_STAGE(bufoff, gbase, voff) do { _Pragma("unroll") for (int _i = 0; _i < 2; ++_i) \
;         __builtin_amdgcn_global_load_lds((const unsigned*)((const char*)(gbase) + (voff)[_i]), (PG8_LAS unsigned*)(lds + (bufoff) + ldsw + _i * 8192), 16, 0, 0); } while (0)
; #define PG8_LDA(dst, b, h) do { _Pragma("unroll") for (int m = 0; m < 4; ++m) _Pragma("unroll") for (int k = 0; k < 2; ++k) dst[m][k] = *(const PG8_LAS bf16x8*)(lds + PG8_SA(b, h) + aoff + m * 2048 + k * 1024); } while (0)
; #define PG8_LDB(dst, b, h) do { _Pragma("unroll") for (int n = 0; n < 2; ++n) _Pragma("unroll") for (int k = 0; k < 2; ++k) dst[n][k] = *(const PG8_LAS bf16x8*)(lds + PG8_SB(b, h) + boff + n * 2048 + k * 1024); } while (0)
; #define PG8_MMA(ai, bj, At, Bt) do { __builtin_amdgcn_s_setprio(1); _Pragma("unroll") for (int m = 0; m < 4; ++m) _Pragma("unroll") for (int n = 0; n < 2; ++n) _Pragma("unroll") for (int k = 0; k < 2; ++k) \
;         acc[ai][bj][m][n] = __builtin_amdgcn_mfma_f32_16x16x32_bf16(Bt[n][k], At[m][k], acc[ai][bj][m][n], 0, 0, 0); __builtin_amdgcn_s_setprio(0); } while (0)
; #define PG8_WAIT_V(n) asm volatile("s_waitcnt vmcnt(" #n ")" ::: "memory")
; #define PG8_WAIT_L(n) asm volatile("s_waitcnt lgkmcnt(" #n ")" ::: "memory")
; #define PG8_BAR __builtin_amdgcn_s_barrier()
; #define PG8_SCHED __builtin_amdgcn_sched_barrier(0)
; template <class Epi, class Sched, bool ALIGN_EPI = false, bool SP2 = false>
; __device__ __forceinline__ void gemm_phase(PG8_LAS unsigned char* lds, const Gemm g, const Sched& S, const Epi& E) {
;     ...
;             if constexpr (SP2) {
;             PG8_LDB(B0, 0, 0); PG8_LDB(B1, 0, 1); PG8_SCHED; PG8_LDA(At, 0, 0); PG8_STAGE(PG8_SA(1, 1), a1 + hstep, voffA);
;             PG8_WAIT_V(8); PG8_WAIT_L(0); PG8_BAR; PG8_MMA(0, 0, At, B0); PG8_MMA(0, 1, At, B1); PG8_BAR; PG8_SCHED;
;             PG8_LDA(At, 0, 1); PG8_STAGE(PG8_SB(0, 0), b2, voffB); PG8_STAGE(PG8_SB(0, 1), b2 + hstep, voffB); PG8_STAGE(PG8_SA(0, 0), a2, voffA);
;             PG8_WAIT_V(8); PG8_WAIT_L(0); PG8_BAR; PG8_MMA(1, 0, At, B0); PG8_MMA(1, 1, At, B1); PG8_BAR; PG8_SCHED;
	s_waitcnt lgkmcnt(0)
	v_mfma_f32_16x16x32_bf16 v[124:127], v[144:147], v[184:187], v[124:127]
	v_mfma_f32_16x16x32_bf16 v[120:123], v[160:163], v[184:187], v[120:123]
	v_mfma_f32_16x16x32_bf16 v[108:111], v[144:147], v[192:195], v[108:111]
	v_mfma_f32_16x16x32_bf16 v[104:107], v[160:163], v[192:195], v[104:107]
	v_mfma_f32_16x16x32_bf16 v[92:95], v[144:147], v[202:205], v[92:95]
	v_mfma_f32_16x16x32_bf16 v[88:91], v[160:163], v[202:205], v[88:91]
	v_mfma_f32_16x16x32_bf16 v[76:79], v[144:147], v[210:213], v[76:79]
	v_mfma_f32_16x16x32_bf16 v[72:75], v[160:163], v[210:213], v[72:75]
	v_mfma_f32_16x16x32_bf16 v[124:127], v[156:159], v[188:191], v[124:127]
	v_mfma_f32_16x16x32_bf16 v[120:123], v[164:167], v[188:191], v[120:123]
	v_mfma_f32_16x16x32_bf16 v[108:111], v[156:159], v[196:199], v[108:111]
	v_mfma_f32_16x16x32_bf16 v[104:107], v[164:167], v[196:199], v[104:107]
	v_mfma_f32_16x16x32_bf16 v[92:95], v[156:159], v[206:209], v[92:95]
	v_mfma_f32_16x16x32_bf16 v[88:91], v[164:167], v[206:209], v[88:91]
	v_mfma_f32_16x16x32_bf16 v[76:79], v[156:159], v[214:217], v[76:79]
	v_mfma_f32_16x16x32_bf16 v[72:75], v[164:167], v[214:217], v[72:75]
	v_mfma_f32_16x16x32_bf16 v[116:119], v[168:171], v[184:187], v[116:119]
	v_mfma_f32_16x16x32_bf16 v[112:115], v[176:179], v[184:187], v[112:115]
	v_mfma_f32_16x16x32_bf16 v[100:103], v[168:171], v[192:195], v[100:103]
	v_mfma_f32_16x16x32_bf16 v[96:99], v[176:179], v[192:195], v[96:99]
	v_mfma_f32_16x16x32_bf16 v[84:87], v[168:171], v[202:205], v[84:87]
	v_mfma_f32_16x16x32_bf16 v[80:83], v[176:179], v[202:205], v[80:83]
	v_mfma_f32_16x16x32_bf16 v[68:71], v[168:171], v[210:213], v[68:71]
	v_mfma_f32_16x16x32_bf16 v[64:67], v[176:179], v[210:213], v[64:67]
	v_mfma_f32_16x16x32_bf16 v[116:119], v[172:175], v[188:191], v[116:119]
	v_mfma_f32_16x16x32_bf16 v[112:115], v[180:183], v[188:191], v[112:115]
	v_mfma_f32_16x16x32_bf16 v[100:103], v[172:175], v[196:199], v[100:103]
	v_mfma_f32_16x16x32_bf16 v[96:99], v[180:183], v[196:199], v[96:99]
	v_mfma_f32_16x16x32_bf16 v[84:87], v[172:175], v[206:209], v[84:87]
	v_mfma_f32_16x16x32_bf16 v[80:83], v[180:183], v[206:209], v[80:83]
	v_mfma_f32_16x16x32_bf16 v[68:71], v[172:175], v[214:217], v[68:71]
	v_mfma_f32_16x16x32_bf16 v[64:67], v[180:183], v[214:217], v[64:67]
	s_barrier
	s_add_i32 s16, s72, s55
	v_lshl_add_u64 v[218:219], s[82:83], 0, v[130:131]
	s_mov_b32 m0, s16
	ds_read_b128 v[184:187], v153 offset:16384
	ds_read_b128 v[188:191], v153 offset:17408
	ds_read_b128 v[192:195], v153 offset:18432
	ds_read_b128 v[196:199], v153 offset:19456
	ds_read_b128 v[202:205], v153 offset:20480
	ds_read_b128 v[206:209], v153 offset:21504
	ds_read_b128 v[210:213], v153 offset:22528
	ds_read_b128 v[214:217], v153 offset:23552
	global_load_lds_dwordx4 v[218:219], off
	s_add_i32 m0, s16, 0x2000
	v_lshl_add_u64 v[220:221], s[82:83], 0, v[134:135]
	s_add_u32 s82, s82, s12
	s_addc_u32 s83, s83, s13
	s_add_i32 s16, s73, s55
	global_load_lds_dwordx4 v[220:221], off
	v_lshl_add_u64 v[222:223], s[82:83], 0, v[130:131]
	s_mov_b32 m0, s16
	v_lshl_add_u64 v[224:225], s[82:83], 0, v[134:135]
	global_load_lds_dwordx4 v[222:223], off
	s_add_i32 m0, s16, 0x2000
	v_lshl_add_u64 v[226:227], s[52:53], 0, v[128:129]
	global_load_lds_dwordx4 v[224:225], off
	s_mov_b32 m0, s56
	v_lshl_add_u64 v[228:229], s[52:53], 0, v[132:133]
	global_load_lds_dwordx4 v[226:227], off
	s_mov_b32 m0, s57
	s_nop 0
	global_load_lds_dwordx4 v[228:229], off
	s_waitcnt vmcnt(8)
	s_waitcnt lgkmcnt(0)
	s_barrier
	s_waitcnt lgkmcnt(0)
	v_mfma_f32_16x16x32_bf16 v[60:63], v[144:147], v[184:187], v[60:63]
	v_mfma_f32_16x16x32_bf16 v[56:59], v[160:163], v[184:187], v[56:59]
	v_mfma_f32_16x16x32_bf16 v[44:47], v[144:147], v[192:195], v[44:47]
	v_mfma_f32_16x16x32_bf16 v[40:43], v[160:163], v[192:195], v[40:43]
	v_mfma_f32_16x16x32_bf16 v[28:31], v[144:147], v[202:205], v[28:31]
	v_mfma_f32_16x16x32_bf16 v[24:27], v[160:163], v[202:205], v[24:27]
	v_mfma_f32_16x16x32_bf16 v[12:15], v[144:147], v[210:213], v[12:15]
	v_mfma_f32_16x16x32_bf16 v[8:11], v[160:163], v[210:213], v[8:11]
	v_mfma_f32_16x16x32_bf16 v[60:63], v[156:159], v[188:191], v[60:63]
	v_mfma_f32_16x16x32_bf16 v[56:59], v[164:167], v[188:191], v[56:59]
	v_mfma_f32_16x16x32_bf16 v[44:47], v[156:159], v[196:199], v[44:47]
	v_mfma_f32_16x16x32_bf16 v[40:43], v[164:167], v[196:199], v[40:43]
	v_mfma_f32_16x16x32_bf16 v[28:31], v[156:159], v[206:209], v[28:31]
	v_mfma_f32_16x16x32_bf16 v[24:27], v[164:167], v[206:209], v[24:27]
	v_mfma_f32_16x16x32_bf16 v[12:15], v[156:159], v[214:217], v[12:15]
	v_mfma_f32_16x16x32_bf16 v[8:11], v[164:167], v[214:217], v[8:11]
	v_mfma_f32_16x16x32_bf16 v[52:55], v[168:171], v[184:187], v[52:55]
	v_mfma_f32_16x16x32_bf16 v[48:51], v[176:179], v[184:187], v[48:51]
	v_mfma_f32_16x16x32_bf16 v[36:39], v[168:171], v[192:195], v[36:39]
	v_mfma_f32_16x16x32_bf16 v[32:35], v[176:179], v[192:195], v[32:35]
	v_mfma_f32_16x16x32_bf16 v[20:23], v[168:171], v[202:205], v[20:23]
	v_mfma_f32_16x16x32_bf16 v[16:19], v[176:179], v[202:205], v[16:19]
	v_mfma_f32_16x16x32_bf16 v[4:7], v[168:171], v[210:213], v[4:7]
	v_mfma_f32_16x16x32_bf16 v[0:3], v[176:179], v[210:213], v[0:3]
	v_mfma_f32_16x16x32_bf16 v[52:55], v[172:175], v[188:191], v[52:55]
	v_mfma_f32_16x16x32_bf16 v[48:51], v[180:183], v[188:191], v[48:51]
	v_mfma_f32_16x16x32_bf16 v[36:39], v[172:175], v[196:199], v[36:39]
	v_mfma_f32_16x16x32_bf16 v[32:35], v[180:183], v[196:199], v[32:35]
	v_mfma_f32_16x16x32_bf16 v[20:23], v[172:175], v[206:209], v[20:23]
	v_mfma_f32_16x16x32_bf16 v[16:19], v[180:183], v[206:209], v[16:19]
	v_mfma_f32_16x16x32_bf16 v[4:7], v[172:175], v[214:217], v[4:7]
	v_mfma_f32_16x16x32_bf16 v[0:3], v[180:183], v[214:217], v[0:3]
	s_barrier
; #define PG8_STAGE(bufoff, gbase, voff) do { _Pragma("unroll") for (int _i = 0; _i < 2; ++_i) \
;         __builtin_amdgcn_global_load_lds((const unsigned*)((const char*)(gbase) + (voff)[_i]), (PG8_LAS unsigned*)(lds + (bufoff) + ldsw + _i * 8192), 16, 0, 0); } while (0)
; #define PG8_LDA(dst, b, h) do { _Pragma("unroll") for (int m = 0; m < 4; ++m) _Pragma("unroll") for (int k = 0; k < 2; ++k) dst[m][k] = *(const PG8_LAS bf16x8*)(lds + PG8_SA(b, h) + aoff + m * 2048 + k * 1024); } while (0)
; #define PG8_LDB(dst, b, h) do { _Pragma("unroll") for (int n = 0; n < 2; ++n) _Pragma("unroll") for (int k = 0; k < 2; ++k) dst[n][k] = *(const PG8_LAS bf16x8*)(lds + PG8_SB(b, h) + boff + n * 2048 + k * 1024); } while (0)
; #define PG8_MMA(ai, bj, At, Bt) do { __builtin_amdgcn_s_setprio(1); _Pragma("unroll") for (int m = 0; m < 4; ++m) _Pragma("unroll") for (int n = 0; n < 2; ++n) _Pragma("unroll") for (int k = 0; k < 2; ++k) \
;         acc[ai][bj][m][n] = __builtin_amdgcn_mfma_f32_16x16x32_bf16(Bt[n][k], At[m][k], acc[ai][bj][m][n], 0, 0, 0); __builtin_amdgcn_s_setprio(0); } while (0)
; #define PG8_WAIT_V(n) asm volatile("s_waitcnt vmcnt(" #n ")" ::: "memory")
; #define PG8_WAIT_L(n) asm volatile("s_waitcnt lgkmcnt(" #n ")" ::: "memory")
; #define PG8_BAR __builtin_amdgcn_s_barrier()
; #define PG8_SCHED __builtin_amdgcn_sched_barrier(0)
; template <class Epi, class Sched, bool ALIGN_EPI = false, bool SP2 = false>
; __device__ __forceinline__ void gemm_phase(PG8_LAS unsigned char* lds, const Gemm g, const Sched& S, const Epi& E) {
;     ...
;             PG8_LDB(B0, 1, 0); PG8_LDB(B1, 1, 1); PG8_SCHED; PG8_LDA(At, 1, 0); PG8_STAGE(PG8_SA(0, 1), a2 + hstep, voffA);
;             PG8_WAIT_V(8); PG8_WAIT_L(0); PG8_BAR; PG8_MMA(0, 0, At, B0); PG8_MMA(0, 1, At, B1); PG8_BAR; PG8_SCHED;
;             PG8_LDA(At, 1, 1); PG8_STAGE(PG8_SB(1, 0), b3, voffB); PG8_STAGE(PG8_SB(1, 1), b3 + hstep, voffB); PG8_STAGE(PG8_SA(1, 0), a3, voffA);
;             PG8_WAIT_V(8); PG8_WAIT_L(0); PG8_BAR; PG8_MMA(1, 0, At, B0); PG8_MMA(1, 1, At, B1); PG8_BAR; PG8_SCHED;
	s_add_i32 s16, 0, 0x18000
	v_add_u32_e32 v155, s16, v149
	s_add_i32 s17, 0, 0x1c000
	ds_read_b128 v[144:147], v155
	ds_read_b128 v[156:159], v155 offset:1024
	ds_read_b128 v[160:163], v155 offset:2048
	ds_read_b128 v[164:167], v155 offset:3072
	v_add_u32_e32 v155, s17, v149
	ds_read_b128 v[168:171], v155
	ds_read_b128 v[172:175], v155 offset:1024
	ds_read_b128 v[176:179], v155 offset:2048
	ds_read_b128 v[180:183], v155 offset:3072
	s_add_u32 s52, s52, s12
	s_addc_u32 s53, s53, s13
	s_mov_b32 m0, s58
	v_lshl_add_u64 v[230:231], s[52:53], 0, v[128:129]
	ds_read_b128 v[184:187], v153 offset:32768
	ds_read_b128 v[188:191], v153 offset:33792
	ds_read_b128 v[192:195], v153 offset:34816
	ds_read_b128 v[196:199], v153 offset:35840
	ds_read_b128 v[202:205], v153 offset:36864
	ds_read_b128 v[206:209], v153 offset:37888
	ds_read_b128 v[210:213], v153 offset:38912
	ds_read_b128 v[214:217], v153 offset:39936
	global_load_lds_dwordx4 v[230:231], off
	v_lshl_add_u64 v[230:231], s[52:53], 0, v[132:133]
	s_mov_b32 m0, s59
	s_nop 0
	global_load_lds_dwordx4 v[230:231], off
	s_waitcnt vmcnt(8)
	s_waitcnt lgkmcnt(0)
	s_barrier
	s_waitcnt lgkmcnt(0)
	v_mfma_f32_16x16x32_bf16 v[124:127], v[144:147], v[184:187], v[124:127]
	v_mfma_f32_16x16x32_bf16 v[120:123], v[160:163], v[184:187], v[120:123]
	v_mfma_f32_16x16x32_bf16 v[108:111], v[144:147], v[192:195], v[108:111]
	v_mfma_f32_16x16x32_bf16 v[104:107], v[160:163], v[192:195], v[104:107]
	v_mfma_f32_16x16x32_bf16 v[92:95], v[144:147], v[202:205], v[92:95]
	v_mfma_f32_16x16x32_bf16 v[88:91], v[160:163], v[202:205], v[88:91]
	v_mfma_f32_16x16x32_bf16 v[76:79], v[144:147], v[210:213], v[76:79]
	v_mfma_f32_16x16x32_bf16 v[72:75], v[160:163], v[210:213], v[72:75]
	v_mfma_f32_16x16x32_bf16 v[124:127], v[156:159], v[188:191], v[124:127]
	v_mfma_f32_16x16x32_bf16 v[120:123], v[164:167], v[188:191], v[120:123]
	v_mfma_f32_16x16x32_bf16 v[108:111], v[156:159], v[196:199], v[108:111]
	v_mfma_f32_16x16x32_bf16 v[104:107], v[164:167], v[196:199], v[104:107]
	v_mfma_f32_16x16x32_bf16 v[92:95], v[156:159], v[206:209], v[92:95]
	v_mfma_f32_16x16x32_bf16 v[88:91], v[164:167], v[206:209], v[88:91]
	v_mfma_f32_16x16x32_bf16 v[76:79], v[156:159], v[214:217], v[76:79]
	v_mfma_f32_16x16x32_bf16 v[72:75], v[164:167], v[214:217], v[72:75]
	v_mfma_f32_16x16x32_bf16 v[116:119], v[168:171], v[184:187], v[116:119]
	v_mfma_f32_16x16x32_bf16 v[112:115], v[176:179], v[184:187], v[112:115]
	v_mfma_f32_16x16x32_bf16 v[100:103], v[168:171], v[192:195], v[100:103]
	v_mfma_f32_16x16x32_bf16 v[96:99], v[176:179], v[192:195], v[96:99]
	v_mfma_f32_16x16x32_bf16 v[84:87], v[168:171], v[202:205], v[84:87]
	v_mfma_f32_16x16x32_bf16 v[80:83], v[176:179], v[202:205], v[80:83]
	v_mfma_f32_16x16x32_bf16 v[68:71], v[168:171], v[210:213], v[68:71]
	v_mfma_f32_16x16x32_bf16 v[64:67], v[176:179], v[210:213], v[64:67]
	v_mfma_f32_16x16x32_bf16 v[116:119], v[172:175], v[188:191], v[116:119]
	v_mfma_f32_16x16x32_bf16 v[112:115], v[180:183], v[188:191], v[112:115]
	v_mfma_f32_16x16x32_bf16 v[100:103], v[172:175], v[196:199], v[100:103]
	v_mfma_f32_16x16x32_bf16 v[96:99], v[180:183], v[196:199], v[96:99]
	v_mfma_f32_16x16x32_bf16 v[84:87], v[172:175], v[206:209], v[84:87]
	v_mfma_f32_16x16x32_bf16 v[80:83], v[180:183], v[206:209], v[80:83]
	v_mfma_f32_16x16x32_bf16 v[68:71], v[172:175], v[214:217], v[68:71]
	v_mfma_f32_16x16x32_bf16 v[64:67], v[180:183], v[214:217], v[64:67]
	s_barrier
	s_add_i32 s16, s16, s55
	v_lshl_add_u64 v[218:219], v[218:219], 0, s[42:43]
	s_mov_b32 m0, s16
	ds_read_b128 v[184:187], v153 offset:49152
	ds_read_b128 v[188:191], v153 offset:50176
	ds_read_b128 v[192:195], v153 offset:51200
	ds_read_b128 v[196:199], v153 offset:52224
	ds_read_b128 v[202:205], v153 offset:53248
	ds_read_b128 v[206:209], v153 offset:54272
	ds_read_b128 v[210:213], v153 offset:55296
	ds_read_b128 v[214:217], v153 offset:56320
	global_load_lds_dwordx4 v[218:219], off
	v_lshl_add_u64 v[218:219], v[220:221], 0, s[42:43]
	s_add_i32 m0, s16, 0x2000
	s_add_i32 s16, s17, s55
	global_load_lds_dwordx4 v[218:219], off
	v_lshl_add_u64 v[218:219], v[222:223], 0, s[42:43]
	s_mov_b32 m0, s16
	s_nop 0
	global_load_lds_dwordx4 v[218:219], off
	v_lshl_add_u64 v[218:219], v[224:225], 0, s[42:43]
	s_add_i32 m0, s16, 0x2000
	s_nop 0
	global_load_lds_dwordx4 v[218:219], off
	v_lshl_add_u64 v[218:219], v[226:227], 0, s[42:43]
	s_mov_b32 m0, s60
	s_nop 0
	global_load_lds_dwordx4 v[218:219], off
	v_lshl_add_u64 v[218:219], v[228:229], 0, s[42:43]
	s_mov_b32 m0, s61
	s_nop 0
	global_load_lds_dwordx4 v[218:219], off
	s_waitcnt vmcnt(8)
	s_waitcnt lgkmcnt(0)
	s_barrier
	s_waitcnt lgkmcnt(0)
	v_mfma_f32_16x16x32_bf16 v[60:63], v[144:147], v[184:187], v[60:63]
	v_mfma_f32_16x16x32_bf16 v[56:59], v[160:163], v[184:187], v[56:59]
	v_mfma_f32_16x16x32_bf16 v[44:47], v[144:147], v[192:195], v[44:47]
	v_mfma_f32_16x16x32_bf16 v[40:43], v[160:163], v[192:195], v[40:43]
	v_mfma_f32_16x16x32_bf16 v[28:31], v[144:147], v[202:205], v[28:31]
	v_mfma_f32_16x16x32_bf16 v[24:27], v[160:163], v[202:205], v[24:27]
	v_mfma_f32_16x16x32_bf16 v[12:15], v[144:147], v[210:213], v[12:15]
	v_mfma_f32_16x16x32_bf16 v[8:11], v[160:163], v[210:213], v[8:11]
	v_mfma_f32_16x16x32_bf16 v[60:63], v[156:159], v[188:191], v[60:63]
	v_mfma_f32_16x16x32_bf16 v[56:59], v[164:167], v[188:191], v[56:59]
	v_mfma_f32_16x16x32_bf16 v[44:47], v[156:159], v[196:199], v[44:47]
	v_mfma_f32_16x16x32_bf16 v[40:43], v[164:167], v[196:199], v[40:43]
	v_mfma_f32_16x16x32_bf16 v[28:31], v[156:159], v[206:209], v[28:31]
	v_mfma_f32_16x16x32_bf16 v[24:27], v[164:167], v[206:209], v[24:27]
	v_mfma_f32_16x16x32_bf16 v[12:15], v[156:159], v[214:217], v[12:15]
	v_mfma_f32_16x16x32_bf16 v[8:11], v[164:167], v[214:217], v[8:11]
	v_mfma_f32_16x16x32_bf16 v[52:55], v[168:171], v[184:187], v[52:55]
	v_mfma_f32_16x16x32_bf16 v[48:51], v[176:179], v[184:187], v[48:51]
	v_mfma_f32_16x16x32_bf16 v[36:39], v[168:171], v[192:195], v[36:39]
	v_mfma_f32_16x16x32_bf16 v[32:35], v[176:179], v[192:195], v[32:35]
	v_mfma_f32_16x16x32_bf16 v[20:23], v[168:171], v[202:205], v[20:23]
	v_mfma_f32_16x16x32_bf16 v[16:19], v[176:179], v[202:205], v[16:19]
	v_mfma_f32_16x16x32_bf16 v[4:7], v[168:171], v[210:213], v[4:7]
	v_mfma_f32_16x16x32_bf16 v[0:3], v[176:179], v[210:213], v[0:3]
	v_mfma_f32_16x16x32_bf16 v[52:55], v[172:175], v[188:191], v[52:55]
	v_mfma_f32_16x16x32_bf16 v[48:51], v[180:183], v[188:191], v[48:51]
	v_mfma_f32_16x16x32_bf16 v[36:39], v[172:175], v[196:199], v[36:39]
	v_mfma_f32_16x16x32_bf16 v[32:35], v[180:183], v[196:199], v[32:35]
	v_mfma_f32_16x16x32_bf16 v[20:23], v[172:175], v[206:209], v[20:23]
	v_mfma_f32_16x16x32_bf16 v[16:19], v[180:183], v[206:209], v[16:19]
	v_mfma_f32_16x16x32_bf16 v[4:7], v[172:175], v[214:217], v[4:7]
	v_mfma_f32_16x16x32_bf16 v[0:3], v[180:183], v[214:217], v[0:3]
	s_barrier
	s_add_u32 s50, s50, 0x100
	s_addc_u32 s51, s51, 0
	s_add_u32 s78, s78, 0x100
	s_addc_u32 s79, s79, 0
	s_cmp_ge_i32 s80, s63
	s_mov_b32 s52, s80
	s_cbranch_scc0 .LBB0_875

; #define PG8_WAIT_V(n) asm volatile("s_waitcnt vmcnt(" #n ")" ::: "memory")
; #define PG8_BAR __builtin_amdgcn_s_barrier()
; template <class Epi, class Sched, bool ALIGN_EPI = false, bool SP2 = false>
; __device__ __forceinline__ void gemm_phase(PG8_LAS unsigned char* lds, const Gemm g, const Sched& S, const Epi& E) {
;     ...
;     PG8_WAIT_V(0);
;     if constexpr (!ALIGN_EPI) { if (wr == 0) PG8_BAR; }
;     PG8_BAR;
; __device__ __forceinline__ void xcd_barrier(const XcdBarrier& b) {
;     asm volatile("s_waitcnt vmcnt(0)" ::: "memory");
;     __syncthreads();
;     if (threadIdx.x == 0) {
;         unsigned* bar = b.bar;
;         __builtin_amdgcn_s_waitcnt(0);
;         unsigned nloc = b.st[0], nx = b.st[1];
;         if (nloc == 0u) { xcd_barrier_complete(bar, b.x, nloc, nx); b.st[0] = nloc; b.st[1] = nx; }
.LBB0_898:
	s_waitcnt vmcnt(0)
	s_waitcnt vmcnt(0) lgkmcnt(0)
	s_barrier
	s_setprio 0
	s_and_saveexec_b64 s[0:1], s[92:93]
	v_readlane_b32 s75, v253, 1
	s_cbranch_execz .LBB0_950
	s_add_i32 s3, 0, 0x20400
	v_mov_b32_e32 v0, s3
	s_waitcnt vmcnt(0) expcnt(0) lgkmcnt(0)
	ds_read_b32 v2, v0
	s_add_i32 s3, 0, 0x20404
	v_mov_b32_e32 v0, s3
	ds_read_b32 v0, v0
	s_waitcnt lgkmcnt(1)
	v_cmp_ne_u32_e32 vcc, 0, v2
	s_cbranch_vccnz .LBB0_914
	s_add_u32 s4, s28, 0x180200
	s_addc_u32 s5, s29, 0
	s_add_u32 s6, s28, 0x180400
	s_addc_u32 s7, s29, 0
	s_add_u32 s12, s28, 0x180500
	s_addc_u32 s13, s29, 0
	s_add_u32 s14, s28, 0x180600
	s_addc_u32 s15, s29, 0
	s_add_u32 s38, s28, 0x180700
	s_addc_u32 s39, s29, 0
	s_add_u32 s40, s28, 0x180800
	s_addc_u32 s41, s29, 0
	s_add_u32 s42, s28, 0x180900
	s_addc_u32 s43, s29, 0
	s_add_u32 s44, s28, 0x180a00
	s_addc_u32 s45, s29, 0
	s_add_u32 s46, s28, 0x180b00
	s_addc_u32 s47, s29, 0
	s_add_u32 s48, s28, 0x180c00
	s_addc_u32 s49, s29, 0
	s_add_u32 s50, s28, 0x180d00
	s_addc_u32 s51, s29, 0
	s_add_u32 s52, s28, 0x180e00
	s_addc_u32 s53, s29, 0
	s_add_u32 s54, s28, 0x180f00
	s_addc_u32 s55, s29, 0
	s_add_u32 s56, s28, 0x181000
	s_addc_u32 s57, s29, 0
	s_add_u32 s58, s28, 0x181100
	s_addc_u32 s59, s29, 0
	s_add_u32 s60, s28, 0x181200
	v_readlane_b32 s3, v253, 0
	s_addc_u32 s61, s29, 0
	s_mul_i32 s3, s31, s3
	s_add_u32 s62, s28, 0x181300
	s_mul_i32 s3, s3, s30
	s_addc_u32 s63, s29, 0
	s_mov_b32 s74, 1
	v_mov_b32_e32 v16, 0
	s_branch .LBB0_902

;     __device__ bool next(int i, Unit& u) const { if (!so.next(i >> 1, u)) return false; u.sel = i & 1; return true; }
; #define PG8_WAIT_V(n) asm volatile("s_waitcnt vmcnt(" #n ")" ::: "memory")
; #define PG8_BAR __builtin_amdgcn_s_barrier()
; template <class Epi, class Sched, bool ALIGN_EPI = false, bool SP2 = false>
; __device__ __forceinline__ void gemm_phase(PG8_LAS unsigned char* lds, const Gemm g, const Sched& S, const Epi& E) {
;     int tid_ = threadIdx.x; asm volatile("" : "+v"(tid_));
;     const int tid = tid_, wid = __builtin_amdgcn_readfirstlane(tid >> 6), lane = tid & 63, wr = wid >> 2, wc = wid & 3, fr = lane & 15, fq = lane >> 4;
;     int K_ = g.K; asm volatile("" : "+s"(K_));
;     const int K = K_, nt = K / BK;
;     unsigned voffA[2], voffB[2];
; #pragma unroll
;     for (int i = 0; i < 2; ++i) { int R, C; stage_rc(tid * 16 + i * 8192, R, C); const int Rb = Epi::PERM ? ((R & ~31) + perm32(R & 31)) : R;
;         voffA[i] = (unsigned)(R * K + C) * 2u; voffB[i] = (unsigned)(Rb * K + C) * 2u; }
;     const size_t kstep = (size_t)(BK * 2);
;     const size_t hstep = (size_t)HALF * K * 2;
;     const size_t tstep = 2 * hstep;
;     const unsigned ldsw = (unsigned)wid * 1024u;
;     const int aoff = lds_byte(wr * 64 + fr, fq * 8), boff = lds_byte(wc * 32 + fr, fq * 8);
;     ...
;     Unit cur, nxt; int ui = 0;
;     if (!S.next(0, cur)) return;
;     f32x4 acc[2][2][4][2];
; #pragma unroll
;     for (int a = 0; a < 2; ++a)
; #pragma unroll
;         for (int b = 0; b < 2; ++b)
; #pragma unroll
;             for (int m = 0; m < 4; ++m)
; #pragma unroll
;                 for (int n = 0; n < 2; ++n) acc[a][b][m][n] = (f32x4){0.f, 0.f, 0.f, 0.f};
;     bf16x8 At[4][2], B0[2][2], B1[2][2];
;     const char* cA = (const char*)(cur.sel ? g.A2 : g.A) + (size_t)cur.pm * tstep; const char* cB = (const char*)(cur.sel ? g.Bt2 : g.Bt) + (size_t)cur.pn * tstep;
;     S.a_ready(cur);
;     if constexpr (SP2) {
;         PG8_STAGE(PG8_SB(0, 0), cB, voffB); PG8_STAGE(PG8_SB(0, 1), cB + hstep, voffB); PG8_STAGE(PG8_SA(0, 0), cA, voffA); PG8_STAGE(PG8_SA(0, 1), cA + hstep, voffA);
;         if (wr == 1) PG8_BAR;
;         PG8_WAIT_V(2); PG8_BAR;
;         PG8_STAGE(PG8_SB(1, 0), cB + kstep, voffB); PG8_STAGE(PG8_SA(1, 0), cA + kstep, voffA); PG8_STAGE(PG8_SB(1, 1), cB + hstep + kstep, voffB);
.Lprio8_skip:
	v_mov_b32_e32 v12, v201
	s_waitcnt lgkmcnt(0)
	s_barrier
	s_movk_i32 s0, 0x400
	v_readfirstlane_b32 s5, v12
	s_cmpk_gt_i32 s2, 0x15ff
	s_cbranch_scc1 .LBB0_1028
	v_lshlrev_b32_e32 v0, 4, v12
	v_add_u32_e32 v1, 0x2000, v0
	v_ashrrev_i32_e32 v2, 31, v1
	v_lshrrev_b32_e32 v2, 22, v2
	v_add_u32_e32 v2, v1, v2
	v_ashrrev_i32_e32 v2, 10, v2
	v_mul_i32_i24_e32 v3, 0x400, v2
	v_sub_u32_e32 v1, v1, v3
	v_lshrrev_b32_e32 v3, 4, v1
	v_bitop3_b32 v1, v3, v1, 32 bitop3:0x6c
	v_ashrrev_i32_e32 v3, 31, v1
	v_lshrrev_b32_e32 v3, 26, v3
	v_add_u32_e32 v3, v1, v3
	v_lshlrev_b32_e32 v5, 3, v2
	v_ashrrev_i32_e32 v4, 6, v3
	v_and_b32_e32 v5, -16, v5
	v_lshlrev_b32_e32 v2, 5, v2
	v_add_u32_e32 v5, v4, v5
	v_and_b32_e32 v13, 32, v2
	v_and_b32_e32 v2, 0xc0, v3
	v_and_b32_e32 v4, 3, v4
	s_mov_b32 s4, 0x7fffffe0
	v_lshrrev_b32_e32 v6, 2, v5
	v_lshlrev_b32_e32 v7, 1, v5
	v_sub_u32_e32 v1, v1, v2
	v_mov_b32_e32 v2, 1
	v_and_or_b32 v4, v5, s4, v4
	v_and_b32_e32 v6, 4, v6
	v_and_b32_e32 v7, 24, v7
	v_ashrrev_i16_sdwa v1, v2, sext(v1) dst_sel:DWORD dst_unused:UNUSED_PAD src0_sel:DWORD src1_sel:BYTE_0
	v_or3_b32 v4, v4, v6, v7
	v_bfe_i32 v14, v1, 0, 16
	v_mul_lo_u32 v4, v4, s0
	v_add_u32_e32 v1, v13, v14
	v_mul_lo_u32 v15, v5, s0
	v_add_lshl_u32 v128, v4, v1, 1
	v_add_lshl_u32 v130, v1, v15, 1
	v_bfe_i32 v1, v12, 27, 1
	v_lshrrev_b32_e32 v1, 22, v1
	v_add_u32_e32 v1, v0, v1
	v_and_b32_e32 v1, 0xfffffc00, v1
	v_sub_u32_e32 v0, v0, v1
	v_lshrrev_b32_e32 v1, 4, v0
	v_ashrrev_i32_e32 v4, 31, v12
	v_bitop3_b32 v0, v1, v0, 32 bitop3:0x6c
	v_lshrrev_b32_e32 v4, 26, v4
	v_ashrrev_i32_e32 v1, 31, v0
	v_add_u32_e32 v4, v12, v4
	v_lshrrev_b32_e32 v1, 26, v1
	v_ashrrev_i32_e32 v4, 6, v4
	v_add_u32_e32 v1, v0, v1
	v_lshlrev_b32_e32 v5, 3, v4
	s_add_u32 s3, s28, 0x1180000
	v_ashrrev_i32_e32 v3, 6, v1
	v_and_b32_e32 v5, -16, v5
	s_addc_u32 s46, s29, 0
	v_add_u32_e32 v5, v3, v5
	v_and_b32_e32 v3, 3, v3
	s_ashr_i32 s48, s2, 31
	v_and_or_b32 v3, v5, s4, v3
	s_lshr_b32 s4, s48, 29
	s_add_i32 s4, s2, s4
	s_ashr_i32 s6, s5, 6
	s_ashr_i32 s1, s0, 31
	s_ashr_i32 s14, s4, 3
	s_and_b32 s4, s4, -8
	s_ashr_i32 s7, s5, 8
	s_lshl_b64 s[10:11], s[0:1], 8
	s_lshl_b64 s[12:13], s[0:1], 9
	s_lshl_b32 s47, s6, 10
	s_sub_i32 s4, s2, s4
	s_cmp_lt_i32 s4, 0
	s_movk_i32 s49, 0x2c1
	s_cselect_b32 s15, s49, 0x2c0
	s_mul_i32 s4, s4, s15
	s_add_i32 s4, s4, s14
	s_mul_hi_i32 s14, s4, 0x2e8ba2e9
	s_lshr_b32 s15, s14, 31
	s_ashr_i32 s14, s14, 5
	s_add_i32 s14, s14, s15
	s_lshl_b32 s15, s14, 3
	s_mulk_i32 s14, 0xb0
	s_sub_i32 s14, s4, s14
	s_sext_i32_i16 s4, s14
	s_bfe_u32 s4, s4, 0x3001c
	s_add_i32 s16, s14, s4
	s_sext_i32_i16 s17, s16
	s_and_b32 s16, s16, 0xfff8
	s_sub_i32 s14, s14, s16
	s_sext_i32_i16 s14, s14
	s_add_i32 s66, s15, s14
	s_ashr_i32 s14, s66, 31
	s_mul_i32 s14, s12, s14
	s_mul_hi_u32 s15, s12, s66
	s_add_i32 s16, s15, s14
	s_lshr_b64 s[14:15], s[0:1], 23
	s_lshr_b32 s4, s17, 3
	s_mul_i32 s15, s14, s66
	s_add_i32 s16, s16, s15
	s_bfe_i64 s[36:37], s[4:5], 0x100000
	s_ashr_i32 s15, s17, 3
	v_and_b32_e32 v1, 0xc0, v1
	s_mul_hi_u32 s17, s12, s15
	s_mul_i32 s36, s12, s37
	v_lshrrev_b32_e32 v6, 2, v5
	v_lshlrev_b32_e32 v7, 1, v5
	v_sub_u32_e32 v0, v0, v1
	s_add_i32 s17, s17, s36
	s_mul_i32 s14, s14, s15
	v_and_b32_e32 v6, 4, v6
	v_and_b32_e32 v7, 24, v7
	v_lshlrev_b32_e32 v4, 5, v4
	v_ashrrev_i16_sdwa v0, v2, sext(v0) dst_sel:DWORD dst_unused:UNUSED_PAD src0_sel:DWORD src1_sel:BYTE_0
	s_add_i32 s17, s17, s14
	s_mul_i32 s14, s12, s15
	v_or3_b32 v3, v3, v6, v7
	v_and_b32_e32 v16, 32, v4
	v_bfe_i32 v17, v0, 0, 16
	s_add_u32 s44, s3, s14
	v_mul_lo_u32 v3, v3, s0
	v_add_u32_e32 v0, v16, v17
	s_addc_u32 s45, s46, s17
	s_add_i32 s50, s47, 0
	v_add_lshl_u32 v132, v3, v0, 1
	s_add_i32 m0, s50, 0x10000
	s_mul_i32 s38, s12, s66
	global_load_lds_dwordx4 v132, s[44:45]
	s_add_i32 m0, s50, 0x12000
	s_add_u32 s14, s44, s10
	global_load_lds_dwordx4 v128, s[44:45]
	s_addc_u32 s15, s45, s11
	s_add_i32 m0, s50, 0x14000
	v_mul_lo_u32 v18, v5, s0
	global_load_lds_dwordx4 v132, s[14:15]
	s_add_i32 m0, s50, 0x16000
	s_add_u32 s42, s34, s38
	s_addc_u32 s43, s35, s16
	s_add_i32 s51, s50, 0x2000
	v_add_lshl_u32 v134, v0, v18, 1
	global_load_lds_dwordx4 v128, s[14:15]
	s_mov_b32 m0, s50
	s_add_u32 s36, s42, s10
	global_load_lds_dwordx4 v134, s[42:43]
	s_mov_b32 m0, s51
	s_addc_u32 s37, s43, s11
	s_add_i32 s52, s50, 0x4000
	global_load_lds_dwordx4 v130, s[42:43]
	s_mov_b32 m0, s52
	s_add_i32 s53, s50, 0x6000
	global_load_lds_dwordx4 v134, s[36:37]
	s_mov_b32 m0, s53
	v_mov_b32_e32 v133, 0
	global_load_lds_dwordx4 v130, s[36:37]
	v_mov_b32_e32 v129, v133
	v_mov_b32_e32 v135, v133
	v_mov_b32_e32 v131, v133
	s_cmp_eq_u32 s7, 1
	s_mov_b32 s54, 0
	v_lshl_add_u64 v[8:9], s[44:45], 0, v[132:133]
	v_lshl_add_u64 v[4:5], s[44:45], 0, v[128:129]
	v_lshl_add_u64 v[2:3], s[14:15], 0, v[132:133]
	v_lshl_add_u64 v[0:1], s[14:15], 0, v[128:129]
	v_lshl_add_u64 v[6:7], s[42:43], 0, v[134:135]
	s_cselect_b64 s[14:15], -1, 0
	s_cmp_lg_u32 s7, 1
	v_lshl_add_u64 v[10:11], s[42:43], 0, v[130:131]
	s_cbranch_scc1 .LBB0_1010
	s_barrier

;     __device__ bool next(int i, Unit& u) const { if (!so.next(i >> 1, u)) return false; u.sel = i & 1; return true; }
; #define PG8_STAGE(bufoff, gbase, voff) do { _Pragma("unroll") for (int _i = 0; _i < 2; ++_i) \
;         __builtin_amdgcn_global_load_lds((const unsigned*)((const char*)(gbase) + (voff)[_i]), (PG8_LAS unsigned*)(lds + (bufoff) + ldsw + _i * 8192), 16, 0, 0); } while (0)
; #define PG8_LDA(dst, b, h) do { _Pragma("unroll") for (int m = 0; m < 4; ++m) _Pragma("unroll") for (int k = 0; k < 2; ++k) dst[m][k] = *(const PG8_LAS bf16x8*)(lds + PG8_SA(b, h) + aoff + m * 2048 + k * 1024); } while (0)
; #define PG8_LDB(dst, b, h) do { _Pragma("unroll") for (int n = 0; n < 2; ++n) _Pragma("unroll") for (int k = 0; k < 2; ++k) dst[n][k] = *(const PG8_LAS bf16x8*)(lds + PG8_SB(b, h) + boff + n * 2048 + k * 1024); } while (0)
; #define PG8_WAIT_V(n) asm volatile("s_waitcnt vmcnt(" #n ")" ::: "memory")
; #define PG8_BAR __builtin_amdgcn_s_barrier()
; template <class Epi, class Sched, bool ALIGN_EPI = false, bool SP2 = false>
; __device__ __forceinline__ void gemm_phase(PG8_LAS unsigned char* lds, const Gemm g, const Sched& S, const Epi& E) {
;     ...
;         const bool has_next = S.next(ui + 1, nxt);
;         const char* nA = has_next ? (const char*)(nxt.sel ? g.A2 : g.A) + (size_t)nxt.pm * tstep : cA; const char* nB = has_next ? (const char*)(nxt.sel ? g.Bt2 : g.Bt) + (size_t)nxt.pn * tstep : cB;
;         for (int t = 0; t < nt; t += 2) {
;             const bool last = (t == nt - 2);
;             const char* a1 = cA + (size_t)(t + 1) * kstep;
;             const char* a2 = last ? nA : cA + (size_t)(t + 2) * kstep; const char* b2 = last ? nB : cB + (size_t)(t + 2) * kstep;
;             const char* a3 = a2 + kstep; const char* b3 = b2 + kstep;
;             if (last && has_next) S.a_ready(nxt);
;             if constexpr (SP2) {
;             PG8_LDB(B0, 0, 0); PG8_LDB(B1, 0, 1); PG8_SCHED; PG8_LDA(At, 0, 0); PG8_STAGE(PG8_SA(1, 1), a1 + hstep, voffA);
;             PG8_WAIT_V(8); PG8_WAIT_L(0); PG8_BAR; PG8_MMA(0, 0, At, B0); PG8_MMA(0, 1, At, B1); PG8_BAR; PG8_SCHED;
;             PG8_LDA(At, 0, 1); PG8_STAGE(PG8_SB(0, 0), b2, voffB); PG8_STAGE(PG8_SB(0, 1), b2 + hstep, voffB); PG8_STAGE(PG8_SA(0, 0), a2, voffA);
;             PG8_WAIT_V(8); PG8_WAIT_L(0); PG8_BAR; PG8_MMA(1, 0, At, B0); PG8_MMA(1, 1, At, B1); PG8_BAR; PG8_SCHED;
.Lcz_go_1021:
	s_add_u32 s42, s42, 0x80
	s_addc_u32 s43, s43, 0
	s_add_u32 s68, s44, 0x100
	s_addc_u32 s69, s45, 0
	s_mov_b32 s44, 0
	ds_read_b128 v[150:153], v147
	ds_read_b128 v[154:157], v147 offset:1024
	ds_read_b128 v[158:161], v147 offset:2048
	ds_read_b128 v[162:165], v147 offset:3072
	ds_read_b128 v[166:169], v148
	ds_read_b128 v[170:173], v148 offset:1024
	ds_read_b128 v[174:177], v148 offset:2048
	ds_read_b128 v[178:181], v148 offset:3072
	s_add_i32 s70, s44, 2
	s_add_u32 s16, s42, 0x80
	s_addc_u32 s17, s43, 0
	s_cmp_eq_u32 s58, s44
	s_cselect_b32 s44, s0, s16
	s_cselect_b32 s45, s1, s17
	s_cselect_b32 s73, s41, s69
	s_cselect_b32 s72, s40, s68
	v_lshl_add_u64 v[198:199], s[42:43], 0, v[136:137]
	s_add_i32 m0, s50, 0xc000
	ds_read_b128 v[182:185], v149
	ds_read_b128 v[186:189], v149 offset:1024
	ds_read_b128 v[190:193], v149 offset:2048
	ds_read_b128 v[194:197], v149 offset:3072
	ds_read_b128 v[202:205], v149 offset:4096
	ds_read_b128 v[206:209], v149 offset:5120
	ds_read_b128 v[210:213], v149 offset:6144
	ds_read_b128 v[214:217], v149 offset:7168
	global_load_lds_dwordx4 v[198:199], off
	v_lshl_add_u64 v[198:199], s[42:43], 0, v[138:139]
	s_add_i32 m0, s50, 0xe000
	s_nop 0
	global_load_lds_dwordx4 v[198:199], off
	s_waitcnt vmcnt(8)
	s_waitcnt lgkmcnt(0)
	s_barrier
	s_waitcnt lgkmcnt(0)
	v_mfma_f32_16x16x32_bf16 v[124:127], v[150:153], v[182:185], 0
	v_mfma_f32_16x16x32_bf16 v[116:119], v[158:161], v[182:185], 0
	v_mfma_f32_16x16x32_bf16 v[108:111], v[150:153], v[190:193], 0
	v_mfma_f32_16x16x32_bf16 v[100:103], v[158:161], v[190:193], 0
	v_mfma_f32_16x16x32_bf16 v[92:95], v[150:153], v[202:205], 0
	v_mfma_f32_16x16x32_bf16 v[84:87], v[158:161], v[202:205], 0
	v_mfma_f32_16x16x32_bf16 v[76:79], v[150:153], v[210:213], 0
	v_mfma_f32_16x16x32_bf16 v[68:71], v[158:161], v[210:213], 0
	v_mfma_f32_16x16x32_bf16 v[124:127], v[154:157], v[186:189], v[124:127]
	v_mfma_f32_16x16x32_bf16 v[116:119], v[162:165], v[186:189], v[116:119]
	v_mfma_f32_16x16x32_bf16 v[108:111], v[154:157], v[194:197], v[108:111]
	v_mfma_f32_16x16x32_bf16 v[100:103], v[162:165], v[194:197], v[100:103]
	v_mfma_f32_16x16x32_bf16 v[92:95], v[154:157], v[206:209], v[92:95]
	v_mfma_f32_16x16x32_bf16 v[84:87], v[162:165], v[206:209], v[84:87]
	v_mfma_f32_16x16x32_bf16 v[76:79], v[154:157], v[214:217], v[76:79]
	v_mfma_f32_16x16x32_bf16 v[68:71], v[162:165], v[214:217], v[68:71]
	v_mfma_f32_16x16x32_bf16 v[120:123], v[166:169], v[182:185], 0
	v_mfma_f32_16x16x32_bf16 v[112:115], v[174:177], v[182:185], 0
	v_mfma_f32_16x16x32_bf16 v[104:107], v[166:169], v[190:193], 0
	v_mfma_f32_16x16x32_bf16 v[96:99], v[174:177], v[190:193], 0
	v_mfma_f32_16x16x32_bf16 v[88:91], v[166:169], v[202:205], 0
	v_mfma_f32_16x16x32_bf16 v[80:83], v[174:177], v[202:205], 0
	v_mfma_f32_16x16x32_bf16 v[72:75], v[166:169], v[210:213], 0
	v_mfma_f32_16x16x32_bf16 v[64:67], v[174:177], v[210:213], 0
	v_mfma_f32_16x16x32_bf16 v[120:123], v[170:173], v[186:189], v[120:123]
	v_mfma_f32_16x16x32_bf16 v[112:115], v[178:181], v[186:189], v[112:115]
	v_mfma_f32_16x16x32_bf16 v[104:107], v[170:173], v[194:197], v[104:107]
	v_mfma_f32_16x16x32_bf16 v[96:99], v[178:181], v[194:197], v[96:99]
	v_mfma_f32_16x16x32_bf16 v[88:91], v[170:173], v[206:209], v[88:91]
	v_mfma_f32_16x16x32_bf16 v[80:83], v[178:181], v[206:209], v[80:83]
	v_mfma_f32_16x16x32_bf16 v[72:75], v[170:173], v[214:217], v[72:75]
	v_mfma_f32_16x16x32_bf16 v[64:67], v[178:181], v[214:217], v[64:67]
	s_barrier
	s_add_i32 s16, s61, s47
	v_lshl_add_u64 v[198:199], s[72:73], 0, v[132:133]
	s_mov_b32 m0, s16
	ds_read_b128 v[182:185], v149 offset:16384
	ds_read_b128 v[186:189], v149 offset:17408
	ds_read_b128 v[190:193], v149 offset:18432
	ds_read_b128 v[194:197], v149 offset:19456
	ds_read_b128 v[202:205], v149 offset:20480
	ds_read_b128 v[206:209], v149 offset:21504
	ds_read_b128 v[210:213], v149 offset:22528
	ds_read_b128 v[214:217], v149 offset:23552
	global_load_lds_dwordx4 v[198:199], off
	s_add_i32 m0, s16, 0x2000
	v_lshl_add_u64 v[218:219], s[72:73], 0, v[128:129]
	s_add_u32 s72, s72, s10
	s_addc_u32 s73, s73, s11
	s_add_i32 s16, s62, s47
	global_load_lds_dwordx4 v[218:219], off
	v_lshl_add_u64 v[220:221], s[72:73], 0, v[132:133]
	s_mov_b32 m0, s16
	v_lshl_add_u64 v[222:223], s[72:73], 0, v[128:129]
	global_load_lds_dwordx4 v[220:221], off
	s_add_i32 m0, s16, 0x2000
	v_lshl_add_u64 v[224:225], s[44:45], 0, v[134:135]
	global_load_lds_dwordx4 v[222:223], off
	s_mov_b32 m0, s50
	v_lshl_add_u64 v[226:227], s[44:45], 0, v[130:131]
	global_load_lds_dwordx4 v[224:225], off
	s_mov_b32 m0, s51
	s_nop 0
	global_load_lds_dwordx4 v[226:227], off
	s_waitcnt vmcnt(8)
	s_waitcnt lgkmcnt(0)
	s_barrier
; #define PG8_STAGE(bufoff, gbase, voff) do { _Pragma("unroll") for (int _i = 0; _i < 2; ++_i) \
;         __builtin_amdgcn_global_load_lds((const unsigned*)((const char*)(gbase) + (voff)[_i]), (PG8_LAS unsigned*)(lds + (bufoff) + ldsw + _i * 8192), 16, 0, 0); } while (0)
; #define PG8_LDA(dst, b, h) do { _Pragma("unroll") for (int m = 0; m < 4; ++m) _Pragma("unroll") for (int k = 0; k < 2; ++k) dst[m][k] = *(const PG8_LAS bf16x8*)(lds + PG8_SA(b, h) + aoff + m * 2048 + k * 1024); } while (0)
; #define PG8_LDB(dst, b, h) do { _Pragma("unroll") for (int n = 0; n < 2; ++n) _Pragma("unroll") for (int k = 0; k < 2; ++k) dst[n][k] = *(const PG8_LAS bf16x8*)(lds + PG8_SB(b, h) + boff + n * 2048 + k * 1024); } while (0)
; #define PG8_MMA(ai, bj, At, Bt) do { __builtin_amdgcn_s_setprio(1); _Pragma("unroll") for (int m = 0; m < 4; ++m) _Pragma("unroll") for (int n = 0; n < 2; ++n) _Pragma("unroll") for (int k = 0; k < 2; ++k) \
;         acc[ai][bj][m][n] = __builtin_amdgcn_mfma_f32_16x16x32_bf16(Bt[n][k], At[m][k], acc[ai][bj][m][n], 0, 0, 0); __builtin_amdgcn_s_setprio(0); } while (0)
; #define PG8_WAIT_V(n) asm volatile("s_waitcnt vmcnt(" #n ")" ::: "memory")
; #define PG8_WAIT_L(n) asm volatile("s_waitcnt lgkmcnt(" #n ")" ::: "memory")
; #define PG8_BAR __builtin_amdgcn_s_barrier()
; #define PG8_SCHED __builtin_amdgcn_sched_barrier(0)
; template <class Epi, class Sched, bool ALIGN_EPI = false, bool SP2 = false>
; __device__ __forceinline__ void gemm_phase(PG8_LAS unsigned char* lds, const Gemm g, const Sched& S, const Epi& E) {
;     ...
;             PG8_WAIT_V(8); PG8_WAIT_L(0); PG8_BAR; PG8_MMA(1, 0, At, B0); PG8_MMA(1, 1, At, B1); PG8_BAR; PG8_SCHED;
;             PG8_LDB(B0, 1, 0); PG8_LDB(B1, 1, 1); PG8_SCHED; PG8_LDA(At, 1, 0); PG8_STAGE(PG8_SA(0, 1), a2 + hstep, voffA);
;             PG8_WAIT_V(8); PG8_WAIT_L(0); PG8_BAR; PG8_MMA(0, 0, At, B0); PG8_MMA(0, 1, At, B1); PG8_BAR; PG8_SCHED;
;             PG8_LDA(At, 1, 1); PG8_STAGE(PG8_SB(1, 0), b3, voffB); PG8_STAGE(PG8_SB(1, 1), b3 + hstep, voffB); PG8_STAGE(PG8_SA(1, 0), a3, voffA);
	s_waitcnt lgkmcnt(0)
	v_mfma_f32_16x16x32_bf16 v[60:63], v[150:153], v[182:185], 0
	v_mfma_f32_16x16x32_bf16 v[52:55], v[158:161], v[182:185], 0
	v_mfma_f32_16x16x32_bf16 v[44:47], v[150:153], v[190:193], 0
	v_mfma_f32_16x16x32_bf16 v[36:39], v[158:161], v[190:193], 0
	v_mfma_f32_16x16x32_bf16 v[28:31], v[150:153], v[202:205], 0
	v_mfma_f32_16x16x32_bf16 v[20:23], v[158:161], v[202:205], 0
	v_mfma_f32_16x16x32_bf16 v[12:15], v[150:153], v[210:213], 0
	v_mfma_f32_16x16x32_bf16 v[4:7], v[158:161], v[210:213], 0
	v_mfma_f32_16x16x32_bf16 v[60:63], v[154:157], v[186:189], v[60:63]
	v_mfma_f32_16x16x32_bf16 v[52:55], v[162:165], v[186:189], v[52:55]
	v_mfma_f32_16x16x32_bf16 v[44:47], v[154:157], v[194:197], v[44:47]
	v_mfma_f32_16x16x32_bf16 v[36:39], v[162:165], v[194:197], v[36:39]
	v_mfma_f32_16x16x32_bf16 v[28:31], v[154:157], v[206:209], v[28:31]
	v_mfma_f32_16x16x32_bf16 v[20:23], v[162:165], v[206:209], v[20:23]
	v_mfma_f32_16x16x32_bf16 v[12:15], v[154:157], v[214:217], v[12:15]
	v_mfma_f32_16x16x32_bf16 v[4:7], v[162:165], v[214:217], v[4:7]
	v_mfma_f32_16x16x32_bf16 v[56:59], v[166:169], v[182:185], 0
	v_mfma_f32_16x16x32_bf16 v[48:51], v[174:177], v[182:185], 0
	v_mfma_f32_16x16x32_bf16 v[40:43], v[166:169], v[190:193], 0
	v_mfma_f32_16x16x32_bf16 v[32:35], v[174:177], v[190:193], 0
	v_mfma_f32_16x16x32_bf16 v[24:27], v[166:169], v[202:205], 0
	v_mfma_f32_16x16x32_bf16 v[16:19], v[174:177], v[202:205], 0
	v_mfma_f32_16x16x32_bf16 v[8:11], v[166:169], v[210:213], 0
	v_mfma_f32_16x16x32_bf16 v[0:3], v[174:177], v[210:213], 0
	v_mfma_f32_16x16x32_bf16 v[56:59], v[170:173], v[186:189], v[56:59]
	v_mfma_f32_16x16x32_bf16 v[48:51], v[178:181], v[186:189], v[48:51]
	v_mfma_f32_16x16x32_bf16 v[40:43], v[170:173], v[194:197], v[40:43]
	v_mfma_f32_16x16x32_bf16 v[32:35], v[178:181], v[194:197], v[32:35]
	v_mfma_f32_16x16x32_bf16 v[24:27], v[170:173], v[206:209], v[24:27]
	v_mfma_f32_16x16x32_bf16 v[16:19], v[178:181], v[206:209], v[16:19]
	v_mfma_f32_16x16x32_bf16 v[8:11], v[170:173], v[214:217], v[8:11]
	v_mfma_f32_16x16x32_bf16 v[0:3], v[178:181], v[214:217], v[0:3]
	s_barrier
	s_add_i32 s16, 0, 0x18000
	s_add_i32 s17, 0, 0x1c000
	v_add_u32_e32 v162, s16, v145
	v_add_u32_e32 v178, s17, v145
	ds_read_b128 v[150:153], v162
	ds_read_b128 v[154:157], v162 offset:1024
	ds_read_b128 v[158:161], v162 offset:2048
	ds_read_b128 v[162:165], v162 offset:3072
	ds_read_b128 v[166:169], v178
	ds_read_b128 v[170:173], v178 offset:1024
	ds_read_b128 v[174:177], v178 offset:2048
	ds_read_b128 v[178:181], v178 offset:3072
	s_add_u32 s44, s44, s10
	s_addc_u32 s45, s45, s11
	s_mov_b32 m0, s52
	v_lshl_add_u64 v[228:229], s[44:45], 0, v[134:135]
	ds_read_b128 v[182:185], v149 offset:32768
	ds_read_b128 v[186:189], v149 offset:33792
	ds_read_b128 v[190:193], v149 offset:34816
	ds_read_b128 v[194:197], v149 offset:35840
	ds_read_b128 v[202:205], v149 offset:36864
	ds_read_b128 v[206:209], v149 offset:37888
	ds_read_b128 v[210:213], v149 offset:38912
	ds_read_b128 v[214:217], v149 offset:39936
	global_load_lds_dwordx4 v[228:229], off
	v_lshl_add_u64 v[228:229], s[44:45], 0, v[130:131]
	s_mov_b32 m0, s53
	s_nop 0
	global_load_lds_dwordx4 v[228:229], off
	s_waitcnt vmcnt(8)
	s_waitcnt lgkmcnt(0)
	s_barrier
	s_waitcnt lgkmcnt(0)
	v_mfma_f32_16x16x32_bf16 v[124:127], v[150:153], v[182:185], v[124:127]
	v_mfma_f32_16x16x32_bf16 v[116:119], v[158:161], v[182:185], v[116:119]
	v_mfma_f32_16x16x32_bf16 v[108:111], v[150:153], v[190:193], v[108:111]
	v_mfma_f32_16x16x32_bf16 v[100:103], v[158:161], v[190:193], v[100:103]
	v_mfma_f32_16x16x32_bf16 v[92:95], v[150:153], v[202:205], v[92:95]
	v_mfma_f32_16x16x32_bf16 v[84:87], v[158:161], v[202:205], v[84:87]
	v_mfma_f32_16x16x32_bf16 v[76:79], v[150:153], v[210:213], v[76:79]
	v_mfma_f32_16x16x32_bf16 v[68:71], v[158:161], v[210:213], v[68:71]
	v_mfma_f32_16x16x32_bf16 v[124:127], v[154:157], v[186:189], v[124:127]
	v_mfma_f32_16x16x32_bf16 v[116:119], v[162:165], v[186:189], v[116:119]
	v_mfma_f32_16x16x32_bf16 v[108:111], v[154:157], v[194:197], v[108:111]
	v_mfma_f32_16x16x32_bf16 v[100:103], v[162:165], v[194:197], v[100:103]
	v_mfma_f32_16x16x32_bf16 v[92:95], v[154:157], v[206:209], v[92:95]
	v_mfma_f32_16x16x32_bf16 v[84:87], v[162:165], v[206:209], v[84:87]
	v_mfma_f32_16x16x32_bf16 v[76:79], v[154:157], v[214:217], v[76:79]
	v_mfma_f32_16x16x32_bf16 v[68:71], v[162:165], v[214:217], v[68:71]
	v_mfma_f32_16x16x32_bf16 v[120:123], v[166:169], v[182:185], v[120:123]
	v_mfma_f32_16x16x32_bf16 v[112:115], v[174:177], v[182:185], v[112:115]
	v_mfma_f32_16x16x32_bf16 v[104:107], v[166:169], v[190:193], v[104:107]
	v_mfma_f32_16x16x32_bf16 v[96:99], v[174:177], v[190:193], v[96:99]
	v_mfma_f32_16x16x32_bf16 v[88:91], v[166:169], v[202:205], v[88:91]
	v_mfma_f32_16x16x32_bf16 v[80:83], v[174:177], v[202:205], v[80:83]
	v_mfma_f32_16x16x32_bf16 v[72:75], v[166:169], v[210:213], v[72:75]
	v_mfma_f32_16x16x32_bf16 v[64:67], v[174:177], v[210:213], v[64:67]
	v_mfma_f32_16x16x32_bf16 v[120:123], v[170:173], v[186:189], v[120:123]
	v_mfma_f32_16x16x32_bf16 v[112:115], v[178:181], v[186:189], v[112:115]
	v_mfma_f32_16x16x32_bf16 v[104:107], v[170:173], v[194:197], v[104:107]
	v_mfma_f32_16x16x32_bf16 v[96:99], v[178:181], v[194:197], v[96:99]
	v_mfma_f32_16x16x32_bf16 v[88:91], v[170:173], v[206:209], v[88:91]
	v_mfma_f32_16x16x32_bf16 v[80:83], v[178:181], v[206:209], v[80:83]
	v_mfma_f32_16x16x32_bf16 v[72:75], v[170:173], v[214:217], v[72:75]
	v_mfma_f32_16x16x32_bf16 v[64:67], v[178:181], v[214:217], v[64:67]
	s_barrier
; #define PG8_STAGE(bufoff, gbase, voff) do { _Pragma("unroll") for (int _i = 0; _i < 2; ++_i) \
;         __builtin_amdgcn_global_load_lds((const unsigned*)((const char*)(gbase) + (voff)[_i]), (PG8_LAS unsigned*)(lds + (bufoff) + ldsw + _i * 8192), 16, 0, 0); } while (0)
; #define PG8_LDA(dst, b, h) do { _Pragma("unroll") for (int m = 0; m < 4; ++m) _Pragma("unroll") for (int k = 0; k < 2; ++k) dst[m][k] = *(const PG8_LAS bf16x8*)(lds + PG8_SA(b, h) + aoff + m * 2048 + k * 1024); } while (0)
; #define PG8_LDB(dst, b, h) do { _Pragma("unroll") for (int n = 0; n < 2; ++n) _Pragma("unroll") for (int k = 0; k < 2; ++k) dst[n][k] = *(const PG8_LAS bf16x8*)(lds + PG8_SB(b, h) + boff + n * 2048 + k * 1024); } while (0)
; template <class Epi, class Sched, bool ALIGN_EPI = false, bool SP2 = false>
; __device__ __forceinline__ void gemm_phase(PG8_LAS unsigned char* lds, const Gemm g, const Sched& S, const Epi& E) {
;     ...
;         for (int t = 0; t < nt; t += 2) {
;             const bool last = (t == nt - 2);
;             const char* a1 = cA + (size_t)(t + 1) * kstep;
;             const char* a2 = last ? nA : cA + (size_t)(t + 2) * kstep; const char* b2 = last ? nB : cB + (size_t)(t + 2) * kstep;
;             const char* a3 = a2 + kstep; const char* b3 = b2 + kstep;
;             if (last && has_next) S.a_ready(nxt);
;             if constexpr (SP2) {
;             PG8_LDB(B0, 0, 0); PG8_LDB(B1, 0, 1); PG8_SCHED; PG8_LDA(At, 0, 0); PG8_STAGE(PG8_SA(1, 1), a1 + hstep, voffA);
;             PG8_WAIT_V(8); PG8_WAIT_L(0); PG8_BAR; PG8_MMA(0, 0, At, B0); PG8_MMA(0, 1, At, B1); PG8_BAR; PG8_SCHED;
;             PG8_LDA(At, 0, 1); PG8_STAGE(PG8_SB(0, 0), b2, voffB); PG8_STAGE(PG8_SB(0, 1), b2 + hstep, voffB); PG8_STAGE(PG8_SA(0, 0), a2, voffA);
;             PG8_WAIT_V(8); PG8_WAIT_L(0); PG8_BAR; PG8_MMA(1, 0, At, B0); PG8_MMA(1, 1, At, B1); PG8_BAR; PG8_SCHED;
;             PG8_LDB(B0, 1, 0); PG8_LDB(B1, 1, 1); PG8_SCHED; PG8_LDA(At, 1, 0); PG8_STAGE(PG8_SA(0, 1), a2 + hstep, voffA);
;             PG8_WAIT_V(8); PG8_WAIT_L(0); PG8_BAR; PG8_MMA(0, 0, At, B0); PG8_MMA(0, 1, At, B1); PG8_BAR; PG8_SCHED;
;             PG8_LDA(At, 1, 1); PG8_STAGE(PG8_SB(1, 0), b3, voffB); PG8_STAGE(PG8_SB(1, 1), b3 + hstep, voffB); PG8_STAGE(PG8_SA(1, 0), a3, voffA);
;             PG8_WAIT_V(8); PG8_WAIT_L(0); PG8_BAR; PG8_MMA(1, 0, At, B0); PG8_MMA(1, 1, At, B1); PG8_BAR; PG8_SCHED;
	s_add_i32 s16, s16, s47
	v_lshl_add_u64 v[198:199], v[198:199], 0, s[36:37]
	s_mov_b32 m0, s16
	ds_read_b128 v[182:185], v149 offset:49152
	ds_read_b128 v[186:189], v149 offset:50176
	ds_read_b128 v[190:193], v149 offset:51200
	ds_read_b128 v[194:197], v149 offset:52224
	ds_read_b128 v[202:205], v149 offset:53248
	ds_read_b128 v[206:209], v149 offset:54272
	ds_read_b128 v[210:213], v149 offset:55296
	ds_read_b128 v[214:217], v149 offset:56320
	global_load_lds_dwordx4 v[198:199], off
	v_lshl_add_u64 v[198:199], v[218:219], 0, s[36:37]
	s_add_i32 m0, s16, 0x2000
	s_add_i32 s16, s17, s47
	global_load_lds_dwordx4 v[198:199], off
	v_lshl_add_u64 v[198:199], v[220:221], 0, s[36:37]
	s_mov_b32 m0, s16
	s_nop 0
	global_load_lds_dwordx4 v[198:199], off
	v_lshl_add_u64 v[198:199], v[222:223], 0, s[36:37]
	s_add_i32 m0, s16, 0x2000
	s_nop 0
	global_load_lds_dwordx4 v[198:199], off
	v_lshl_add_u64 v[198:199], v[224:225], 0, s[36:37]
	s_mov_b32 m0, s55
	s_nop 0
	global_load_lds_dwordx4 v[198:199], off
	v_lshl_add_u64 v[198:199], v[226:227], 0, s[36:37]
	s_mov_b32 m0, s56
	s_nop 0
	global_load_lds_dwordx4 v[198:199], off
	s_waitcnt vmcnt(8)
	s_waitcnt lgkmcnt(0)
	s_barrier
	s_waitcnt lgkmcnt(0)
	v_mfma_f32_16x16x32_bf16 v[60:63], v[150:153], v[182:185], v[60:63]
	v_mfma_f32_16x16x32_bf16 v[52:55], v[158:161], v[182:185], v[52:55]
	v_mfma_f32_16x16x32_bf16 v[44:47], v[150:153], v[190:193], v[44:47]
	v_mfma_f32_16x16x32_bf16 v[36:39], v[158:161], v[190:193], v[36:39]
	v_mfma_f32_16x16x32_bf16 v[28:31], v[150:153], v[202:205], v[28:31]
	v_mfma_f32_16x16x32_bf16 v[20:23], v[158:161], v[202:205], v[20:23]
	v_mfma_f32_16x16x32_bf16 v[12:15], v[150:153], v[210:213], v[12:15]
	v_mfma_f32_16x16x32_bf16 v[4:7], v[158:161], v[210:213], v[4:7]
	v_mfma_f32_16x16x32_bf16 v[60:63], v[154:157], v[186:189], v[60:63]
	v_mfma_f32_16x16x32_bf16 v[52:55], v[162:165], v[186:189], v[52:55]
	v_mfma_f32_16x16x32_bf16 v[44:47], v[154:157], v[194:197], v[44:47]
	v_mfma_f32_16x16x32_bf16 v[36:39], v[162:165], v[194:197], v[36:39]
	v_mfma_f32_16x16x32_bf16 v[28:31], v[154:157], v[206:209], v[28:31]
	v_mfma_f32_16x16x32_bf16 v[20:23], v[162:165], v[206:209], v[20:23]
	v_mfma_f32_16x16x32_bf16 v[12:15], v[154:157], v[214:217], v[12:15]
	v_mfma_f32_16x16x32_bf16 v[4:7], v[162:165], v[214:217], v[4:7]
	v_mfma_f32_16x16x32_bf16 v[56:59], v[166:169], v[182:185], v[56:59]
	v_mfma_f32_16x16x32_bf16 v[48:51], v[174:177], v[182:185], v[48:51]
	v_mfma_f32_16x16x32_bf16 v[40:43], v[166:169], v[190:193], v[40:43]
	v_mfma_f32_16x16x32_bf16 v[32:35], v[174:177], v[190:193], v[32:35]
	v_mfma_f32_16x16x32_bf16 v[24:27], v[166:169], v[202:205], v[24:27]
	v_mfma_f32_16x16x32_bf16 v[16:19], v[174:177], v[202:205], v[16:19]
	v_mfma_f32_16x16x32_bf16 v[8:11], v[166:169], v[210:213], v[8:11]
	v_mfma_f32_16x16x32_bf16 v[0:3], v[174:177], v[210:213], v[0:3]
	v_mfma_f32_16x16x32_bf16 v[56:59], v[170:173], v[186:189], v[56:59]
	v_mfma_f32_16x16x32_bf16 v[48:51], v[178:181], v[186:189], v[48:51]
	v_mfma_f32_16x16x32_bf16 v[40:43], v[170:173], v[194:197], v[40:43]
	v_mfma_f32_16x16x32_bf16 v[32:35], v[178:181], v[194:197], v[32:35]
	v_mfma_f32_16x16x32_bf16 v[24:27], v[170:173], v[206:209], v[24:27]
	v_mfma_f32_16x16x32_bf16 v[16:19], v[178:181], v[206:209], v[16:19]
	v_mfma_f32_16x16x32_bf16 v[8:11], v[170:173], v[214:217], v[8:11]
	v_mfma_f32_16x16x32_bf16 v[0:3], v[178:181], v[214:217], v[0:3]
	s_barrier
	s_add_u32 s42, s42, 0x100
	s_addc_u32 s43, s43, 0
	s_add_u32 s68, s68, 0x100
	s_addc_u32 s69, s69, 0
	s_cmp_ge_i32 s70, s57
	s_mov_b32 s44, s70
	s_cbranch_scc1 .LBB0_1022
.LBB0_1021:
	ds_read_b128 v[150:153], v147
	ds_read_b128 v[154:157], v147 offset:1024
	ds_read_b128 v[158:161], v147 offset:2048
	ds_read_b128 v[162:165], v147 offset:3072
	ds_read_b128 v[166:169], v148
	ds_read_b128 v[170:173], v148 offset:1024
	ds_read_b128 v[174:177], v148 offset:2048
	ds_read_b128 v[178:181], v148 offset:3072
	s_add_i32 s70, s44, 2
	s_add_u32 s16, s42, 0x80
	s_addc_u32 s17, s43, 0
	s_cmp_eq_u32 s58, s44
	s_cselect_b32 s44, s0, s16
	s_cselect_b32 s45, s1, s17
	s_cselect_b32 s73, s41, s69
	s_cselect_b32 s72, s40, s68
	v_lshl_add_u64 v[198:199], s[42:43], 0, v[136:137]
	s_add_i32 m0, s50, 0xc000
	ds_read_b128 v[182:185], v149
	ds_read_b128 v[186:189], v149 offset:1024
	ds_read_b128 v[190:193], v149 offset:2048
	ds_read_b128 v[194:197], v149 offset:3072
	ds_read_b128 v[202:205], v149 offset:4096
	ds_read_b128 v[206:209], v149 offset:5120
	ds_read_b128 v[210:213], v149 offset:6144
	ds_read_b128 v[214:217], v149 offset:7168
	global_load_lds_dwordx4 v[198:199], off
	v_lshl_add_u64 v[198:199], s[42:43], 0, v[138:139]
	s_add_i32 m0, s50, 0xe000
	s_nop 0
	global_load_lds_dwordx4 v[198:199], off
	s_waitcnt vmcnt(8)
	s_waitcnt lgkmcnt(0)
	s_barrier
; #define PG8_STAGE(bufoff, gbase, voff) do { _Pragma("unroll") for (int _i = 0; _i < 2; ++_i) \
;         __builtin_amdgcn_global_load_lds((const unsigned*)((const char*)(gbase) + (voff)[_i]), (PG8_LAS unsigned*)(lds + (bufoff) + ldsw + _i * 8192), 16, 0, 0); } while (0)
; #define PG8_LDA(dst, b, h) do { _Pragma("unroll") for (int m = 0; m < 4; ++m) _Pragma("unroll") for (int k = 0; k < 2; ++k) dst[m][k] = *(const PG8_LAS bf16x8*)(lds + PG8_SA(b, h) + aoff + m * 2048 + k * 1024); } while (0)
; #define PG8_LDB(dst, b, h) do { _Pragma("unroll") for (int n = 0; n < 2; ++n) _Pragma("unroll") for (int k = 0; k < 2; ++k) dst[n][k] = *(const PG8_LAS bf16x8*)(lds + PG8_SB(b, h) + boff + n * 2048 + k * 1024); } while (0)
; #define PG8_MMA(ai, bj, At, Bt) do { __builtin_amdgcn_s_setprio(1); _Pragma("unroll") for (int m = 0; m < 4; ++m) _Pragma("unroll") for (int n = 0; n < 2; ++n) _Pragma("unroll") for (int k = 0; k < 2; ++k) \
;         acc[ai][bj][m][n] = __builtin_amdgcn_mfma_f32_16x16x32_bf16(Bt[n][k], At[m][k], acc[ai][bj][m][n], 0, 0, 0); __builtin_amdgcn_s_setprio(0); } while (0)
; #define PG8_WAIT_V(n) asm volatile("s_waitcnt vmcnt(" #n ")" ::: "memory")
; #define PG8_WAIT_L(n) asm volatile("s_waitcnt lgkmcnt(" #n ")" ::: "memory")
; #define PG8_BAR __builtin_amdgcn_s_barrier()
; #define PG8_SCHED __builtin_amdgcn_sched_barrier(0)
; template <class Epi, class Sched, bool ALIGN_EPI = false, bool SP2 = false>
; __device__ __forceinline__ void gemm_phase(PG8_LAS unsigned char* lds, const Gemm g, const Sched& S, const Epi& E) {
;     ...
;             PG8_LDB(B0, 0, 0); PG8_LDB(B1, 0, 1); PG8_SCHED; PG8_LDA(At, 0, 0); PG8_STAGE(PG8_SA(1, 1), a1 + hstep, voffA);
;             PG8_WAIT_V(8); PG8_WAIT_L(0); PG8_BAR; PG8_MMA(0, 0, At, B0); PG8_MMA(0, 1, At, B1); PG8_BAR; PG8_SCHED;
;             PG8_LDA(At, 0, 1); PG8_STAGE(PG8_SB(0, 0), b2, voffB); PG8_STAGE(PG8_SB(0, 1), b2 + hstep, voffB); PG8_STAGE(PG8_SA(0, 0), a2, voffA);
;             PG8_WAIT_V(8); PG8_WAIT_L(0); PG8_BAR; PG8_MMA(1, 0, At, B0); PG8_MMA(1, 1, At, B1); PG8_BAR; PG8_SCHED;
	s_waitcnt lgkmcnt(0)
	v_mfma_f32_16x16x32_bf16 v[124:127], v[150:153], v[182:185], v[124:127]
	v_mfma_f32_16x16x32_bf16 v[116:119], v[158:161], v[182:185], v[116:119]
	v_mfma_f32_16x16x32_bf16 v[108:111], v[150:153], v[190:193], v[108:111]
	v_mfma_f32_16x16x32_bf16 v[100:103], v[158:161], v[190:193], v[100:103]
	v_mfma_f32_16x16x32_bf16 v[92:95], v[150:153], v[202:205], v[92:95]
	v_mfma_f32_16x16x32_bf16 v[84:87], v[158:161], v[202:205], v[84:87]
	v_mfma_f32_16x16x32_bf16 v[76:79], v[150:153], v[210:213], v[76:79]
	v_mfma_f32_16x16x32_bf16 v[68:71], v[158:161], v[210:213], v[68:71]
	v_mfma_f32_16x16x32_bf16 v[124:127], v[154:157], v[186:189], v[124:127]
	v_mfma_f32_16x16x32_bf16 v[116:119], v[162:165], v[186:189], v[116:119]
	v_mfma_f32_16x16x32_bf16 v[108:111], v[154:157], v[194:197], v[108:111]
	v_mfma_f32_16x16x32_bf16 v[100:103], v[162:165], v[194:197], v[100:103]
	v_mfma_f32_16x16x32_bf16 v[92:95], v[154:157], v[206:209], v[92:95]
	v_mfma_f32_16x16x32_bf16 v[84:87], v[162:165], v[206:209], v[84:87]
	v_mfma_f32_16x16x32_bf16 v[76:79], v[154:157], v[214:217], v[76:79]
	v_mfma_f32_16x16x32_bf16 v[68:71], v[162:165], v[214:217], v[68:71]
	v_mfma_f32_16x16x32_bf16 v[120:123], v[166:169], v[182:185], v[120:123]
	v_mfma_f32_16x16x32_bf16 v[112:115], v[174:177], v[182:185], v[112:115]
	v_mfma_f32_16x16x32_bf16 v[104:107], v[166:169], v[190:193], v[104:107]
	v_mfma_f32_16x16x32_bf16 v[96:99], v[174:177], v[190:193], v[96:99]
	v_mfma_f32_16x16x32_bf16 v[88:91], v[166:169], v[202:205], v[88:91]
	v_mfma_f32_16x16x32_bf16 v[80:83], v[174:177], v[202:205], v[80:83]
	v_mfma_f32_16x16x32_bf16 v[72:75], v[166:169], v[210:213], v[72:75]
	v_mfma_f32_16x16x32_bf16 v[64:67], v[174:177], v[210:213], v[64:67]
	v_mfma_f32_16x16x32_bf16 v[120:123], v[170:173], v[186:189], v[120:123]
	v_mfma_f32_16x16x32_bf16 v[112:115], v[178:181], v[186:189], v[112:115]
	v_mfma_f32_16x16x32_bf16 v[104:107], v[170:173], v[194:197], v[104:107]
	v_mfma_f32_16x16x32_bf16 v[96:99], v[178:181], v[194:197], v[96:99]
	v_mfma_f32_16x16x32_bf16 v[88:91], v[170:173], v[206:209], v[88:91]
	v_mfma_f32_16x16x32_bf16 v[80:83], v[178:181], v[206:209], v[80:83]
	v_mfma_f32_16x16x32_bf16 v[72:75], v[170:173], v[214:217], v[72:75]
	v_mfma_f32_16x16x32_bf16 v[64:67], v[178:181], v[214:217], v[64:67]
	s_barrier
	s_add_i32 s16, s61, s47
	v_lshl_add_u64 v[198:199], s[72:73], 0, v[132:133]
	s_mov_b32 m0, s16
	ds_read_b128 v[182:185], v149 offset:16384
	ds_read_b128 v[186:189], v149 offset:17408
	ds_read_b128 v[190:193], v149 offset:18432
	ds_read_b128 v[194:197], v149 offset:19456
	ds_read_b128 v[202:205], v149 offset:20480
	ds_read_b128 v[206:209], v149 offset:21504
	ds_read_b128 v[210:213], v149 offset:22528
	ds_read_b128 v[214:217], v149 offset:23552
	global_load_lds_dwordx4 v[198:199], off
	s_add_i32 m0, s16, 0x2000
	v_lshl_add_u64 v[218:219], s[72:73], 0, v[128:129]
	s_add_u32 s72, s72, s10
	s_addc_u32 s73, s73, s11
	s_add_i32 s16, s62, s47
	global_load_lds_dwordx4 v[218:219], off
	v_lshl_add_u64 v[220:221], s[72:73], 0, v[132:133]
	s_mov_b32 m0, s16
	v_lshl_add_u64 v[222:223], s[72:73], 0, v[128:129]
	global_load_lds_dwordx4 v[220:221], off
	s_add_i32 m0, s16, 0x2000
	v_lshl_add_u64 v[224:225], s[44:45], 0, v[134:135]
	global_load_lds_dwordx4 v[222:223], off
	s_mov_b32 m0, s50
	v_lshl_add_u64 v[226:227], s[44:45], 0, v[130:131]
	global_load_lds_dwordx4 v[224:225], off
	s_mov_b32 m0, s51
	s_nop 0
	global_load_lds_dwordx4 v[226:227], off
	s_waitcnt vmcnt(8)
	s_waitcnt lgkmcnt(0)
	s_barrier
	s_waitcnt lgkmcnt(0)
	v_mfma_f32_16x16x32_bf16 v[60:63], v[150:153], v[182:185], v[60:63]
	v_mfma_f32_16x16x32_bf16 v[52:55], v[158:161], v[182:185], v[52:55]
	v_mfma_f32_16x16x32_bf16 v[44:47], v[150:153], v[190:193], v[44:47]
	v_mfma_f32_16x16x32_bf16 v[36:39], v[158:161], v[190:193], v[36:39]
	v_mfma_f32_16x16x32_bf16 v[28:31], v[150:153], v[202:205], v[28:31]
	v_mfma_f32_16x16x32_bf16 v[20:23], v[158:161], v[202:205], v[20:23]
	v_mfma_f32_16x16x32_bf16 v[12:15], v[150:153], v[210:213], v[12:15]
	v_mfma_f32_16x16x32_bf16 v[4:7], v[158:161], v[210:213], v[4:7]
	v_mfma_f32_16x16x32_bf16 v[60:63], v[154:157], v[186:189], v[60:63]
	v_mfma_f32_16x16x32_bf16 v[52:55], v[162:165], v[186:189], v[52:55]
	v_mfma_f32_16x16x32_bf16 v[44:47], v[154:157], v[194:197], v[44:47]
	v_mfma_f32_16x16x32_bf16 v[36:39], v[162:165], v[194:197], v[36:39]
	v_mfma_f32_16x16x32_bf16 v[28:31], v[154:157], v[206:209], v[28:31]
	v_mfma_f32_16x16x32_bf16 v[20:23], v[162:165], v[206:209], v[20:23]
	v_mfma_f32_16x16x32_bf16 v[12:15], v[154:157], v[214:217], v[12:15]
	v_mfma_f32_16x16x32_bf16 v[4:7], v[162:165], v[214:217], v[4:7]
	v_mfma_f32_16x16x32_bf16 v[56:59], v[166:169], v[182:185], v[56:59]
	v_mfma_f32_16x16x32_bf16 v[48:51], v[174:177], v[182:185], v[48:51]
	v_mfma_f32_16x16x32_bf16 v[40:43], v[166:169], v[190:193], v[40:43]
	v_mfma_f32_16x16x32_bf16 v[32:35], v[174:177], v[190:193], v[32:35]
	v_mfma_f32_16x16x32_bf16 v[24:27], v[166:169], v[202:205], v[24:27]
	v_mfma_f32_16x16x32_bf16 v[16:19], v[174:177], v[202:205], v[16:19]
	v_mfma_f32_16x16x32_bf16 v[8:11], v[166:169], v[210:213], v[8:11]
	v_mfma_f32_16x16x32_bf16 v[0:3], v[174:177], v[210:213], v[0:3]
	v_mfma_f32_16x16x32_bf16 v[56:59], v[170:173], v[186:189], v[56:59]
	v_mfma_f32_16x16x32_bf16 v[48:51], v[178:181], v[186:189], v[48:51]
	v_mfma_f32_16x16x32_bf16 v[40:43], v[170:173], v[194:197], v[40:43]
	v_mfma_f32_16x16x32_bf16 v[32:35], v[178:181], v[194:197], v[32:35]
	v_mfma_f32_16x16x32_bf16 v[24:27], v[170:173], v[206:209], v[24:27]
	v_mfma_f32_16x16x32_bf16 v[16:19], v[178:181], v[206:209], v[16:19]
	v_mfma_f32_16x16x32_bf16 v[8:11], v[170:173], v[214:217], v[8:11]
	v_mfma_f32_16x16x32_bf16 v[0:3], v[178:181], v[214:217], v[0:3]
	s_barrier
; #define PG8_STAGE(bufoff, gbase, voff) do { _Pragma("unroll") for (int _i = 0; _i < 2; ++_i) \
;         __builtin_amdgcn_global_load_lds((const unsigned*)((const char*)(gbase) + (voff)[_i]), (PG8_LAS unsigned*)(lds + (bufoff) + ldsw + _i * 8192), 16, 0, 0); } while (0)
; #define PG8_LDA(dst, b, h) do { _Pragma("unroll") for (int m = 0; m < 4; ++m) _Pragma("unroll") for (int k = 0; k < 2; ++k) dst[m][k] = *(const PG8_LAS bf16x8*)(lds + PG8_SA(b, h) + aoff + m * 2048 + k * 1024); } while (0)
; #define PG8_LDB(dst, b, h) do { _Pragma("unroll") for (int n = 0; n < 2; ++n) _Pragma("unroll") for (int k = 0; k < 2; ++k) dst[n][k] = *(const PG8_LAS bf16x8*)(lds + PG8_SB(b, h) + boff + n * 2048 + k * 1024); } while (0)
; #define PG8_MMA(ai, bj, At, Bt) do { __builtin_amdgcn_s_setprio(1); _Pragma("unroll") for (int m = 0; m < 4; ++m) _Pragma("unroll") for (int n = 0; n < 2; ++n) _Pragma("unroll") for (int k = 0; k < 2; ++k) \
;         acc[ai][bj][m][n] = __builtin_amdgcn_mfma_f32_16x16x32_bf16(Bt[n][k], At[m][k], acc[ai][bj][m][n], 0, 0, 0); __builtin_amdgcn_s_setprio(0); } while (0)
; #define PG8_WAIT_V(n) asm volatile("s_waitcnt vmcnt(" #n ")" ::: "memory")
; #define PG8_WAIT_L(n) asm volatile("s_waitcnt lgkmcnt(" #n ")" ::: "memory")
; #define PG8_BAR __builtin_amdgcn_s_barrier()
; #define PG8_SCHED __builtin_amdgcn_sched_barrier(0)
; template <class Epi, class Sched, bool ALIGN_EPI = false, bool SP2 = false>
; __device__ __forceinline__ void gemm_phase(PG8_LAS unsigned char* lds, const Gemm g, const Sched& S, const Epi& E) {
;     ...
;             PG8_LDB(B0, 1, 0); PG8_LDB(B1, 1, 1); PG8_SCHED; PG8_LDA(At, 1, 0); PG8_STAGE(PG8_SA(0, 1), a2 + hstep, voffA);
;             PG8_WAIT_V(8); PG8_WAIT_L(0); PG8_BAR; PG8_MMA(0, 0, At, B0); PG8_MMA(0, 1, At, B1); PG8_BAR; PG8_SCHED;
;             PG8_LDA(At, 1, 1); PG8_STAGE(PG8_SB(1, 0), b3, voffB); PG8_STAGE(PG8_SB(1, 1), b3 + hstep, voffB); PG8_STAGE(PG8_SA(1, 0), a3, voffA);
;             PG8_WAIT_V(8); PG8_WAIT_L(0); PG8_BAR; PG8_MMA(1, 0, At, B0); PG8_MMA(1, 1, At, B1); PG8_BAR; PG8_SCHED;
	s_add_i32 s16, 0, 0x18000
	s_add_i32 s17, 0, 0x1c000
	v_add_u32_e32 v162, s16, v145
	v_add_u32_e32 v178, s17, v145
	ds_read_b128 v[150:153], v162
	ds_read_b128 v[154:157], v162 offset:1024
	ds_read_b128 v[158:161], v162 offset:2048
	ds_read_b128 v[162:165], v162 offset:3072
	ds_read_b128 v[166:169], v178
	ds_read_b128 v[170:173], v178 offset:1024
	ds_read_b128 v[174:177], v178 offset:2048
	ds_read_b128 v[178:181], v178 offset:3072
	s_add_u32 s44, s44, s10
	s_addc_u32 s45, s45, s11
	s_mov_b32 m0, s52
	v_lshl_add_u64 v[228:229], s[44:45], 0, v[134:135]
	ds_read_b128 v[182:185], v149 offset:32768
	ds_read_b128 v[186:189], v149 offset:33792
	ds_read_b128 v[190:193], v149 offset:34816
	ds_read_b128 v[194:197], v149 offset:35840
	ds_read_b128 v[202:205], v149 offset:36864
	ds_read_b128 v[206:209], v149 offset:37888
	ds_read_b128 v[210:213], v149 offset:38912
	ds_read_b128 v[214:217], v149 offset:39936
	global_load_lds_dwordx4 v[228:229], off
	v_lshl_add_u64 v[228:229], s[44:45], 0, v[130:131]
	s_mov_b32 m0, s53
	s_nop 0
	global_load_lds_dwordx4 v[228:229], off
	s_waitcnt vmcnt(8)
	s_waitcnt lgkmcnt(0)
	s_barrier
	s_waitcnt lgkmcnt(0)
	v_mfma_f32_16x16x32_bf16 v[124:127], v[150:153], v[182:185], v[124:127]
	v_mfma_f32_16x16x32_bf16 v[116:119], v[158:161], v[182:185], v[116:119]
	v_mfma_f32_16x16x32_bf16 v[108:111], v[150:153], v[190:193], v[108:111]
	v_mfma_f32_16x16x32_bf16 v[100:103], v[158:161], v[190:193], v[100:103]
	v_mfma_f32_16x16x32_bf16 v[92:95], v[150:153], v[202:205], v[92:95]
	v_mfma_f32_16x16x32_bf16 v[84:87], v[158:161], v[202:205], v[84:87]
	v_mfma_f32_16x16x32_bf16 v[76:79], v[150:153], v[210:213], v[76:79]
	v_mfma_f32_16x16x32_bf16 v[68:71], v[158:161], v[210:213], v[68:71]
	v_mfma_f32_16x16x32_bf16 v[124:127], v[154:157], v[186:189], v[124:127]
	v_mfma_f32_16x16x32_bf16 v[116:119], v[162:165], v[186:189], v[116:119]
	v_mfma_f32_16x16x32_bf16 v[108:111], v[154:157], v[194:197], v[108:111]
	v_mfma_f32_16x16x32_bf16 v[100:103], v[162:165], v[194:197], v[100:103]
	v_mfma_f32_16x16x32_bf16 v[92:95], v[154:157], v[206:209], v[92:95]
	v_mfma_f32_16x16x32_bf16 v[84:87], v[162:165], v[206:209], v[84:87]
	v_mfma_f32_16x16x32_bf16 v[76:79], v[154:157], v[214:217], v[76:79]
	v_mfma_f32_16x16x32_bf16 v[68:71], v[162:165], v[214:217], v[68:71]
	v_mfma_f32_16x16x32_bf16 v[120:123], v[166:169], v[182:185], v[120:123]
	v_mfma_f32_16x16x32_bf16 v[112:115], v[174:177], v[182:185], v[112:115]
	v_mfma_f32_16x16x32_bf16 v[104:107], v[166:169], v[190:193], v[104:107]
	v_mfma_f32_16x16x32_bf16 v[96:99], v[174:177], v[190:193], v[96:99]
	v_mfma_f32_16x16x32_bf16 v[88:91], v[166:169], v[202:205], v[88:91]
	v_mfma_f32_16x16x32_bf16 v[80:83], v[174:177], v[202:205], v[80:83]
	v_mfma_f32_16x16x32_bf16 v[72:75], v[166:169], v[210:213], v[72:75]
	v_mfma_f32_16x16x32_bf16 v[64:67], v[174:177], v[210:213], v[64:67]
	v_mfma_f32_16x16x32_bf16 v[120:123], v[170:173], v[186:189], v[120:123]
	v_mfma_f32_16x16x32_bf16 v[112:115], v[178:181], v[186:189], v[112:115]
	v_mfma_f32_16x16x32_bf16 v[104:107], v[170:173], v[194:197], v[104:107]
	v_mfma_f32_16x16x32_bf16 v[96:99], v[178:181], v[194:197], v[96:99]
	v_mfma_f32_16x16x32_bf16 v[88:91], v[170:173], v[206:209], v[88:91]
	v_mfma_f32_16x16x32_bf16 v[80:83], v[178:181], v[206:209], v[80:83]
	v_mfma_f32_16x16x32_bf16 v[72:75], v[170:173], v[214:217], v[72:75]
	v_mfma_f32_16x16x32_bf16 v[64:67], v[178:181], v[214:217], v[64:67]
	s_barrier
	s_add_i32 s16, s16, s47
	v_lshl_add_u64 v[198:199], v[198:199], 0, s[36:37]
	s_mov_b32 m0, s16
	ds_read_b128 v[182:185], v149 offset:49152
	ds_read_b128 v[186:189], v149 offset:50176
	ds_read_b128 v[190:193], v149 offset:51200
	ds_read_b128 v[194:197], v149 offset:52224
	ds_read_b128 v[202:205], v149 offset:53248
	ds_read_b128 v[206:209], v149 offset:54272
	ds_read_b128 v[210:213], v149 offset:55296
	ds_read_b128 v[214:217], v149 offset:56320
	global_load_lds_dwordx4 v[198:199], off
	v_lshl_add_u64 v[198:199], v[218:219], 0, s[36:37]
	s_add_i32 m0, s16, 0x2000
	s_add_i32 s16, s17, s47
	global_load_lds_dwordx4 v[198:199], off
	v_lshl_add_u64 v[198:199], v[220:221], 0, s[36:37]
	s_mov_b32 m0, s16
	s_nop 0
	global_load_lds_dwordx4 v[198:199], off
	v_lshl_add_u64 v[198:199], v[222:223], 0, s[36:37]
	s_add_i32 m0, s16, 0x2000
	s_nop 0
	global_load_lds_dwordx4 v[198:199], off
	v_lshl_add_u64 v[198:199], v[224:225], 0, s[36:37]
	s_mov_b32 m0, s55
	s_nop 0
	global_load_lds_dwordx4 v[198:199], off
	v_lshl_add_u64 v[198:199], v[226:227], 0, s[36:37]
	s_mov_b32 m0, s56
	s_nop 0
	global_load_lds_dwordx4 v[198:199], off
	s_waitcnt vmcnt(8)
	s_waitcnt lgkmcnt(0)
	s_barrier
	s_waitcnt lgkmcnt(0)
	v_mfma_f32_16x16x32_bf16 v[60:63], v[150:153], v[182:185], v[60:63]
	v_mfma_f32_16x16x32_bf16 v[52:55], v[158:161], v[182:185], v[52:55]
	v_mfma_f32_16x16x32_bf16 v[44:47], v[150:153], v[190:193], v[44:47]
	v_mfma_f32_16x16x32_bf16 v[36:39], v[158:161], v[190:193], v[36:39]
	v_mfma_f32_16x16x32_bf16 v[28:31], v[150:153], v[202:205], v[28:31]
	v_mfma_f32_16x16x32_bf16 v[20:23], v[158:161], v[202:205], v[20:23]
	v_mfma_f32_16x16x32_bf16 v[12:15], v[150:153], v[210:213], v[12:15]
	v_mfma_f32_16x16x32_bf16 v[4:7], v[158:161], v[210:213], v[4:7]
	v_mfma_f32_16x16x32_bf16 v[60:63], v[154:157], v[186:189], v[60:63]
	v_mfma_f32_16x16x32_bf16 v[52:55], v[162:165], v[186:189], v[52:55]
	v_mfma_f32_16x16x32_bf16 v[44:47], v[154:157], v[194:197], v[44:47]
	v_mfma_f32_16x16x32_bf16 v[36:39], v[162:165], v[194:197], v[36:39]
	v_mfma_f32_16x16x32_bf16 v[28:31], v[154:157], v[206:209], v[28:31]
	v_mfma_f32_16x16x32_bf16 v[20:23], v[162:165], v[206:209], v[20:23]
	v_mfma_f32_16x16x32_bf16 v[12:15], v[154:157], v[214:217], v[12:15]
	v_mfma_f32_16x16x32_bf16 v[4:7], v[162:165], v[214:217], v[4:7]
	v_mfma_f32_16x16x32_bf16 v[56:59], v[166:169], v[182:185], v[56:59]
	v_mfma_f32_16x16x32_bf16 v[48:51], v[174:177], v[182:185], v[48:51]
	v_mfma_f32_16x16x32_bf16 v[40:43], v[166:169], v[190:193], v[40:43]
	v_mfma_f32_16x16x32_bf16 v[32:35], v[174:177], v[190:193], v[32:35]
	v_mfma_f32_16x16x32_bf16 v[24:27], v[166:169], v[202:205], v[24:27]
	v_mfma_f32_16x16x32_bf16 v[16:19], v[174:177], v[202:205], v[16:19]
	v_mfma_f32_16x16x32_bf16 v[8:11], v[166:169], v[210:213], v[8:11]
	v_mfma_f32_16x16x32_bf16 v[0:3], v[174:177], v[210:213], v[0:3]
	v_mfma_f32_16x16x32_bf16 v[56:59], v[170:173], v[186:189], v[56:59]
	v_mfma_f32_16x16x32_bf16 v[48:51], v[178:181], v[186:189], v[48:51]
	v_mfma_f32_16x16x32_bf16 v[40:43], v[170:173], v[194:197], v[40:43]
	v_mfma_f32_16x16x32_bf16 v[32:35], v[178:181], v[194:197], v[32:35]
	v_mfma_f32_16x16x32_bf16 v[24:27], v[170:173], v[206:209], v[24:27]
	v_mfma_f32_16x16x32_bf16 v[16:19], v[178:181], v[206:209], v[16:19]
	v_mfma_f32_16x16x32_bf16 v[8:11], v[170:173], v[214:217], v[8:11]
	v_mfma_f32_16x16x32_bf16 v[0:3], v[178:181], v[214:217], v[0:3]
	s_barrier
	s_add_u32 s42, s42, 0x100
	s_addc_u32 s43, s43, 0
	s_add_u32 s68, s68, 0x100
	s_addc_u32 s69, s69, 0
	s_cmp_ge_i32 s70, s57
	s_mov_b32 s44, s70
	s_cbranch_scc0 .LBB0_1021

; #define PG8_WAIT_V(n) asm volatile("s_waitcnt vmcnt(" #n ")" ::: "memory")
; #define PG8_BAR __builtin_amdgcn_s_barrier()
; template <class Epi, class Sched, bool ALIGN_EPI = false, bool SP2 = false>
; __device__ __forceinline__ void gemm_phase(PG8_LAS unsigned char* lds, const Gemm g, const Sched& S, const Epi& E) {
;     ...
;     PG8_WAIT_V(0);
;     if constexpr (!ALIGN_EPI) { if (wr == 0) PG8_BAR; }
;     PG8_BAR;
; __device__ __forceinline__ void xcd_barrier(const XcdBarrier& b) {
;     asm volatile("s_waitcnt vmcnt(0)" ::: "memory");
;     __syncthreads();
;     if (threadIdx.x == 0) {
;         unsigned* bar = b.bar;
;         __builtin_amdgcn_s_waitcnt(0);
;         unsigned nloc = b.st[0], nx = b.st[1];
;         if (nloc == 0u) { xcd_barrier_complete(bar, b.x, nloc, nx); b.st[0] = nloc; b.st[1] = nx; }
.LBB0_1028:
	s_waitcnt vmcnt(0)
	s_waitcnt vmcnt(0) lgkmcnt(0)
	s_barrier
	s_setprio 0
	s_and_saveexec_b64 s[0:1], s[92:93]
	s_cbranch_execz .LBB0_1080
	s_add_i32 s3, 0, 0x20400
	v_mov_b32_e32 v0, s3
	s_waitcnt vmcnt(0) expcnt(0) lgkmcnt(0)
	ds_read_b32 v2, v0
	s_add_i32 s3, 0, 0x20404
	v_mov_b32_e32 v0, s3
	ds_read_b32 v0, v0
	s_waitcnt lgkmcnt(1)
	v_cmp_ne_u32_e32 vcc, 0, v2
	s_cbranch_vccnz .LBB0_1044
	s_add_u32 s4, s28, 0x180200
	s_addc_u32 s5, s29, 0
	s_add_u32 s6, s28, 0x180400
	s_addc_u32 s7, s29, 0
	s_add_u32 s10, s28, 0x180500
	s_addc_u32 s11, s29, 0
	s_add_u32 s12, s28, 0x180600
	s_addc_u32 s13, s29, 0
	s_add_u32 s14, s28, 0x180700
	s_addc_u32 s15, s29, 0
	s_add_u32 s34, s28, 0x180800
	s_addc_u32 s35, s29, 0
	s_add_u32 s36, s28, 0x180900
	s_addc_u32 s37, s29, 0
	s_add_u32 s38, s28, 0x180a00
	s_addc_u32 s39, s29, 0
	s_add_u32 s40, s28, 0x180b00
	s_addc_u32 s41, s29, 0
	s_add_u32 s42, s28, 0x180c00
	s_addc_u32 s43, s29, 0
	s_add_u32 s44, s28, 0x180d00
	s_addc_u32 s45, s29, 0
	s_add_u32 s46, s28, 0x180e00
	s_addc_u32 s47, s29, 0
	s_add_u32 s48, s28, 0x180f00
	s_addc_u32 s49, s29, 0
	s_add_u32 s50, s28, 0x181000
	s_addc_u32 s51, s29, 0
	s_add_u32 s52, s28, 0x181100
	s_addc_u32 s53, s29, 0
	s_add_u32 s54, s28, 0x181200
	v_readlane_b32 s3, v253, 0
	s_addc_u32 s55, s29, 0
	s_mul_i32 s3, s31, s3
	s_add_u32 s56, s28, 0x181300
	s_mul_i32 s3, s3, s30
	s_addc_u32 s57, s29, 0
	s_mov_b32 s64, 1
	v_mov_b32_e32 v16, 0
	s_branch .LBB0_1032

;     __device__ bool next(int i, Unit& u) const { if (!so.next(i >> 1, u)) return false; u.sel = i & 1; return true; }
;     __host__ __device__ bool next(int i, Unit& u) const {
;         const long L = (long)i * G + c; if (L >= nwg) return false;
;         int wgid = (int)L; { const int q = nwg / NXCD, r = nwg % NXCD, xcd = wgid % NXCD, off = wgid / NXCD; wgid = (xcd < r ? xcd * (q + 1) : r * (q + 1) + (xcd - r) * q) + off; }
;         const int nig = WGM * nN, gid = wgid / nig, fm = gid * WGM, gsz = (nM - fm) < WGM ? (nM - fm) : WGM;
;         u.pm = fm + ((wgid % nig) % gsz); u.pn = (wgid % nig) / gsz; u.sel = 0; return true;
; template <class Epi, class Sched, bool ALIGN_EPI = false, bool SP2 = false>
; __device__ __forceinline__ void gemm_phase(PG8_LAS unsigned char* lds, const Gemm g, const Sched& S, const Epi& E) {
;     int tid_ = threadIdx.x; asm volatile("" : "+v"(tid_));
;     const int tid = tid_, wid = __builtin_amdgcn_readfirstlane(tid >> 6), lane = tid & 63, wr = wid >> 2, wc = wid & 3, fr = lane & 15, fq = lane >> 4;
;     int K_ = g.K; asm volatile("" : "+s"(K_));
;     const int K = K_, nt = K / BK;
.Lprio9_skip:
	v_mov_b32_e32 v12, v201
	s_waitcnt lgkmcnt(0)
	s_barrier
	s_movk_i32 s0, 0xb00
	v_readfirstlane_b32 s6, v12
	s_and_b64 vcc, exec, s[8:9]
	s_cbranch_vccnz .LBB0_1086
	s_ashr_i32 s1, s2, 31
	s_lshr_b32 s1, s1, 29
	s_add_i32 s7, s2, s1
	s_and_b32 s1, s7, -8
	s_sub_i32 s1, s2, s1
	s_cmp_gt_i32 s1, -1
	s_cbranch_scc0 .LBB0_1083
	s_lshl_b32 s3, s1, 7
	s_ashr_i32 s4, s7, 3
	s_cbranch_execz .LBB0_1084
	s_branch .LBB0_1085

;     __device__ bool next(int i, Unit& u) const { if (!so.next(i >> 1, u)) return false; u.sel = i & 1; return true; }
; #define PG8_STAGE(bufoff, gbase, voff) do { _Pragma("unroll") for (int _i = 0; _i < 2; ++_i) \
;         __builtin_amdgcn_global_load_lds((const unsigned*)((const char*)(gbase) + (voff)[_i]), (PG8_LAS unsigned*)(lds + (bufoff) + ldsw + _i * 8192), 16, 0, 0); } while (0)
; #define PG8_LDA(dst, b, h) do { _Pragma("unroll") for (int m = 0; m < 4; ++m) _Pragma("unroll") for (int k = 0; k < 2; ++k) dst[m][k] = *(const PG8_LAS bf16x8*)(lds + PG8_SA(b, h) + aoff + m * 2048 + k * 1024); } while (0)
; #define PG8_LDB(dst, b, h) do { _Pragma("unroll") for (int n = 0; n < 2; ++n) _Pragma("unroll") for (int k = 0; k < 2; ++k) dst[n][k] = *(const PG8_LAS bf16x8*)(lds + PG8_SB(b, h) + boff + n * 2048 + k * 1024); } while (0)
; #define PG8_WAIT_V(n) asm volatile("s_waitcnt vmcnt(" #n ")" ::: "memory")
; #define PG8_BAR __builtin_amdgcn_s_barrier()
; template <class Epi, class Sched, bool ALIGN_EPI = false, bool SP2 = false>
; __device__ __forceinline__ void gemm_phase(PG8_LAS unsigned char* lds, const Gemm g, const Sched& S, const Epi& E) {
;     ...
;         const bool has_next = S.next(ui + 1, nxt);
;         const char* nA = has_next ? (const char*)(nxt.sel ? g.A2 : g.A) + (size_t)nxt.pm * tstep : cA; const char* nB = has_next ? (const char*)(nxt.sel ? g.Bt2 : g.Bt) + (size_t)nxt.pn * tstep : cB;
;         for (int t = 0; t < nt; t += 2) {
;             const bool last = (t == nt - 2);
;             const char* a1 = cA + (size_t)(t + 1) * kstep;
;             const char* a2 = last ? nA : cA + (size_t)(t + 2) * kstep; const char* b2 = last ? nB : cB + (size_t)(t + 2) * kstep;
;             const char* a3 = a2 + kstep; const char* b3 = b2 + kstep;
;             if (last && has_next) S.a_ready(nxt);
;             if constexpr (SP2) {
;             PG8_LDB(B0, 0, 0); PG8_LDB(B1, 0, 1); PG8_SCHED; PG8_LDA(At, 0, 0); PG8_STAGE(PG8_SA(1, 1), a1 + hstep, voffA);
;             PG8_WAIT_V(8); PG8_WAIT_L(0); PG8_BAR; PG8_MMA(0, 0, At, B0); PG8_MMA(0, 1, At, B1); PG8_BAR; PG8_SCHED;
;             PG8_LDA(At, 0, 1); PG8_STAGE(PG8_SB(0, 0), b2, voffB); PG8_STAGE(PG8_SB(0, 1), b2 + hstep, voffB); PG8_STAGE(PG8_SA(0, 0), a2, voffA);
;             PG8_WAIT_V(8); PG8_WAIT_L(0); PG8_BAR; PG8_MMA(1, 0, At, B0); PG8_MMA(1, 1, At, B1); PG8_BAR; PG8_SCHED;
.Lcz_go_1104:
	s_add_u32 s44, s44, 0x8000
	s_addc_u32 s45, s45, 0
	s_add_u32 s68, s46, 0x100
	s_addc_u32 s69, s47, 0
	s_mov_b32 s46, 0
	ds_read_b128 v[144:147], v151
	ds_read_b128 v[156:159], v151 offset:1024
	ds_read_b128 v[160:163], v151 offset:2048
	ds_read_b128 v[164:167], v151 offset:3072
	ds_read_b128 v[168:171], v152
	ds_read_b128 v[172:175], v152 offset:1024
	ds_read_b128 v[176:179], v152 offset:2048
	ds_read_b128 v[180:183], v152 offset:3072
	s_add_i32 s70, s46, 2
	s_add_u32 s16, s44, 0x8000
	s_addc_u32 s17, s45, 0
	s_cmp_eq_u32 s58, s46
	s_cselect_b32 s46, s0, s16
	s_cselect_b32 s47, s1, s17
	s_cselect_b32 s73, s43, s69
	s_cselect_b32 s72, s42, s68
	v_lshl_add_u64 v[218:219], s[44:45], 0, v[136:137]
	s_add_i32 m0, s50, 0xc000
	ds_read_b128 v[184:187], v153
	ds_read_b128 v[188:191], v153 offset:1024
	ds_read_b128 v[192:195], v153 offset:2048
	ds_read_b128 v[196:199], v153 offset:3072
	ds_read_b128 v[202:205], v153 offset:4096
	ds_read_b128 v[206:209], v153 offset:5120
	ds_read_b128 v[210:213], v153 offset:6144
	ds_read_b128 v[214:217], v153 offset:7168
	global_load_lds_dwordx4 v[218:219], off
	v_lshl_add_u64 v[218:219], s[44:45], 0, v[138:139]
	s_add_i32 m0, s50, 0xe000
	s_nop 0
	global_load_lds_dwordx4 v[218:219], off
	s_waitcnt vmcnt(8)
	s_waitcnt lgkmcnt(0)
	s_barrier
	s_waitcnt lgkmcnt(0)
	v_mfma_f32_16x16x32_bf16 v[124:127], v[144:147], v[184:187], 0
	v_mfma_f32_16x16x32_bf16 v[120:123], v[160:163], v[184:187], 0
	v_mfma_f32_16x16x32_bf16 v[108:111], v[144:147], v[192:195], 0
	v_mfma_f32_16x16x32_bf16 v[104:107], v[160:163], v[192:195], 0
	v_mfma_f32_16x16x32_bf16 v[92:95], v[144:147], v[202:205], 0
	v_mfma_f32_16x16x32_bf16 v[88:91], v[160:163], v[202:205], 0
	v_mfma_f32_16x16x32_bf16 v[76:79], v[144:147], v[210:213], 0
	v_mfma_f32_16x16x32_bf16 v[72:75], v[160:163], v[210:213], 0
	v_mfma_f32_16x16x32_bf16 v[124:127], v[156:159], v[188:191], v[124:127]
	v_mfma_f32_16x16x32_bf16 v[120:123], v[164:167], v[188:191], v[120:123]
	v_mfma_f32_16x16x32_bf16 v[108:111], v[156:159], v[196:199], v[108:111]
	v_mfma_f32_16x16x32_bf16 v[104:107], v[164:167], v[196:199], v[104:107]
	v_mfma_f32_16x16x32_bf16 v[92:95], v[156:159], v[206:209], v[92:95]
	v_mfma_f32_16x16x32_bf16 v[88:91], v[164:167], v[206:209], v[88:91]
	v_mfma_f32_16x16x32_bf16 v[76:79], v[156:159], v[214:217], v[76:79]
	v_mfma_f32_16x16x32_bf16 v[72:75], v[164:167], v[214:217], v[72:75]
	v_mfma_f32_16x16x32_bf16 v[116:119], v[168:171], v[184:187], 0
	v_mfma_f32_16x16x32_bf16 v[112:115], v[176:179], v[184:187], 0
	v_mfma_f32_16x16x32_bf16 v[100:103], v[168:171], v[192:195], 0
	v_mfma_f32_16x16x32_bf16 v[96:99], v[176:179], v[192:195], 0
	v_mfma_f32_16x16x32_bf16 v[84:87], v[168:171], v[202:205], 0
	v_mfma_f32_16x16x32_bf16 v[80:83], v[176:179], v[202:205], 0
	v_mfma_f32_16x16x32_bf16 v[68:71], v[168:171], v[210:213], 0
	v_mfma_f32_16x16x32_bf16 v[64:67], v[176:179], v[210:213], 0
	v_mfma_f32_16x16x32_bf16 v[116:119], v[172:175], v[188:191], v[116:119]
	v_mfma_f32_16x16x32_bf16 v[112:115], v[180:183], v[188:191], v[112:115]
	v_mfma_f32_16x16x32_bf16 v[100:103], v[172:175], v[196:199], v[100:103]
	v_mfma_f32_16x16x32_bf16 v[96:99], v[180:183], v[196:199], v[96:99]
	v_mfma_f32_16x16x32_bf16 v[84:87], v[172:175], v[206:209], v[84:87]
	v_mfma_f32_16x16x32_bf16 v[80:83], v[180:183], v[206:209], v[80:83]
	v_mfma_f32_16x16x32_bf16 v[68:71], v[172:175], v[214:217], v[68:71]
	v_mfma_f32_16x16x32_bf16 v[64:67], v[180:183], v[214:217], v[64:67]
	s_barrier
	s_add_i32 s16, s62, s49
	v_lshl_add_u64 v[218:219], s[72:73], 0, v[130:131]
	s_mov_b32 m0, s16
	ds_read_b128 v[184:187], v153 offset:16384
	ds_read_b128 v[188:191], v153 offset:17408
	ds_read_b128 v[192:195], v153 offset:18432
	ds_read_b128 v[196:199], v153 offset:19456
	ds_read_b128 v[202:205], v153 offset:20480
	ds_read_b128 v[206:209], v153 offset:21504
	ds_read_b128 v[210:213], v153 offset:22528
	ds_read_b128 v[214:217], v153 offset:23552
	global_load_lds_dwordx4 v[218:219], off
	s_add_i32 m0, s16, 0x2000
	v_lshl_add_u64 v[220:221], s[72:73], 0, v[134:135]
	s_add_u32 s72, s72, s8
	s_addc_u32 s73, s73, s9
	s_add_i32 s16, s63, s49
	global_load_lds_dwordx4 v[220:221], off
	v_lshl_add_u64 v[222:223], s[72:73], 0, v[130:131]
	s_mov_b32 m0, s16
	v_lshl_add_u64 v[224:225], s[72:73], 0, v[134:135]
	global_load_lds_dwordx4 v[222:223], off
	s_add_i32 m0, s16, 0x2000
	v_lshl_add_u64 v[226:227], s[46:47], 0, v[128:129]
	global_load_lds_dwordx4 v[224:225], off
	s_mov_b32 m0, s50
	v_lshl_add_u64 v[228:229], s[46:47], 0, v[132:133]
	global_load_lds_dwordx4 v[226:227], off
	s_mov_b32 m0, s51
	s_nop 0
	global_load_lds_dwordx4 v[228:229], off
	s_waitcnt vmcnt(8)
	s_waitcnt lgkmcnt(0)
	s_barrier
; #define PG8_STAGE(bufoff, gbase, voff) do { _Pragma("unroll") for (int _i = 0; _i < 2; ++_i) \
;         __builtin_amdgcn_global_load_lds((const unsigned*)((const char*)(gbase) + (voff)[_i]), (PG8_LAS unsigned*)(lds + (bufoff) + ldsw + _i * 8192), 16, 0, 0); } while (0)
; #define PG8_LDA(dst, b, h) do { _Pragma("unroll") for (int m = 0; m < 4; ++m) _Pragma("unroll") for (int k = 0; k < 2; ++k) dst[m][k] = *(const PG8_LAS bf16x8*)(lds + PG8_SA(b, h) + aoff + m * 2048 + k * 1024); } while (0)
; #define PG8_LDB(dst, b, h) do { _Pragma("unroll") for (int n = 0; n < 2; ++n) _Pragma("unroll") for (int k = 0; k < 2; ++k) dst[n][k] = *(const PG8_LAS bf16x8*)(lds + PG8_SB(b, h) + boff + n * 2048 + k * 1024); } while (0)
; #define PG8_MMA(ai, bj, At, Bt) do { __builtin_amdgcn_s_setprio(1); _Pragma("unroll") for (int m = 0; m < 4; ++m) _Pragma("unroll") for (int n = 0; n < 2; ++n) _Pragma("unroll") for (int k = 0; k < 2; ++k) \
;         acc[ai][bj][m][n] = __builtin_amdgcn_mfma_f32_16x16x32_bf16(Bt[n][k], At[m][k], acc[ai][bj][m][n], 0, 0, 0); __builtin_amdgcn_s_setprio(0); } while (0)
; #define PG8_WAIT_V(n) asm volatile("s_waitcnt vmcnt(" #n ")" ::: "memory")
; #define PG8_WAIT_L(n) asm volatile("s_waitcnt lgkmcnt(" #n ")" ::: "memory")
; #define PG8_BAR __builtin_amdgcn_s_barrier()
; #define PG8_SCHED __builtin_amdgcn_sched_barrier(0)
; template <class Epi, class Sched, bool ALIGN_EPI = false, bool SP2 = false>
; __device__ __forceinline__ void gemm_phase(PG8_LAS unsigned char* lds, const Gemm g, const Sched& S, const Epi& E) {
;     ...
;             PG8_WAIT_V(8); PG8_WAIT_L(0); PG8_BAR; PG8_MMA(1, 0, At, B0); PG8_MMA(1, 1, At, B1); PG8_BAR; PG8_SCHED;
;             PG8_LDB(B0, 1, 0); PG8_LDB(B1, 1, 1); PG8_SCHED; PG8_LDA(At, 1, 0); PG8_STAGE(PG8_SA(0, 1), a2 + hstep, voffA);
;             PG8_WAIT_V(8); PG8_WAIT_L(0); PG8_BAR; PG8_MMA(0, 0, At, B0); PG8_MMA(0, 1, At, B1); PG8_BAR; PG8_SCHED;
;             PG8_LDA(At, 1, 1); PG8_STAGE(PG8_SB(1, 0), b3, voffB); PG8_STAGE(PG8_SB(1, 1), b3 + hstep, voffB); PG8_STAGE(PG8_SA(1, 0), a3, voffA);
	s_waitcnt lgkmcnt(0)
	v_mfma_f32_16x16x32_bf16 v[60:63], v[144:147], v[184:187], 0
	v_mfma_f32_16x16x32_bf16 v[56:59], v[160:163], v[184:187], 0
	v_mfma_f32_16x16x32_bf16 v[44:47], v[144:147], v[192:195], 0
	v_mfma_f32_16x16x32_bf16 v[40:43], v[160:163], v[192:195], 0
	v_mfma_f32_16x16x32_bf16 v[28:31], v[144:147], v[202:205], 0
	v_mfma_f32_16x16x32_bf16 v[24:27], v[160:163], v[202:205], 0
	v_mfma_f32_16x16x32_bf16 v[12:15], v[144:147], v[210:213], 0
	v_mfma_f32_16x16x32_bf16 v[8:11], v[160:163], v[210:213], 0
	v_mfma_f32_16x16x32_bf16 v[60:63], v[156:159], v[188:191], v[60:63]
	v_mfma_f32_16x16x32_bf16 v[56:59], v[164:167], v[188:191], v[56:59]
	v_mfma_f32_16x16x32_bf16 v[44:47], v[156:159], v[196:199], v[44:47]
	v_mfma_f32_16x16x32_bf16 v[40:43], v[164:167], v[196:199], v[40:43]
	v_mfma_f32_16x16x32_bf16 v[28:31], v[156:159], v[206:209], v[28:31]
	v_mfma_f32_16x16x32_bf16 v[24:27], v[164:167], v[206:209], v[24:27]
	v_mfma_f32_16x16x32_bf16 v[12:15], v[156:159], v[214:217], v[12:15]
	v_mfma_f32_16x16x32_bf16 v[8:11], v[164:167], v[214:217], v[8:11]
	v_mfma_f32_16x16x32_bf16 v[52:55], v[168:171], v[184:187], 0
	v_mfma_f32_16x16x32_bf16 v[48:51], v[176:179], v[184:187], 0
	v_mfma_f32_16x16x32_bf16 v[36:39], v[168:171], v[192:195], 0
	v_mfma_f32_16x16x32_bf16 v[32:35], v[176:179], v[192:195], 0
	v_mfma_f32_16x16x32_bf16 v[20:23], v[168:171], v[202:205], 0
	v_mfma_f32_16x16x32_bf16 v[16:19], v[176:179], v[202:205], 0
	v_mfma_f32_16x16x32_bf16 v[4:7], v[168:171], v[210:213], 0
	v_mfma_f32_16x16x32_bf16 v[0:3], v[176:179], v[210:213], 0
	v_mfma_f32_16x16x32_bf16 v[52:55], v[172:175], v[188:191], v[52:55]
	v_mfma_f32_16x16x32_bf16 v[48:51], v[180:183], v[188:191], v[48:51]
	v_mfma_f32_16x16x32_bf16 v[36:39], v[172:175], v[196:199], v[36:39]
	v_mfma_f32_16x16x32_bf16 v[32:35], v[180:183], v[196:199], v[32:35]
	v_mfma_f32_16x16x32_bf16 v[20:23], v[172:175], v[206:209], v[20:23]
	v_mfma_f32_16x16x32_bf16 v[16:19], v[180:183], v[206:209], v[16:19]
	v_mfma_f32_16x16x32_bf16 v[4:7], v[172:175], v[214:217], v[4:7]
	v_mfma_f32_16x16x32_bf16 v[0:3], v[180:183], v[214:217], v[0:3]
	s_barrier
	s_add_i32 s16, 0, 0x18000
	v_add_u32_e32 v155, s16, v149
	s_add_i32 s17, 0, 0x1c000
	ds_read_b128 v[144:147], v155
	ds_read_b128 v[156:159], v155 offset:1024
	ds_read_b128 v[160:163], v155 offset:2048
	ds_read_b128 v[164:167], v155 offset:3072
	v_add_u32_e32 v155, s17, v149
	ds_read_b128 v[168:171], v155
	ds_read_b128 v[172:175], v155 offset:1024
	ds_read_b128 v[176:179], v155 offset:2048
	ds_read_b128 v[180:183], v155 offset:3072
	s_add_u32 s46, s46, 0x2000
	s_addc_u32 s47, s47, 0
	s_mov_b32 m0, s52
	v_lshl_add_u64 v[230:231], s[46:47], 0, v[128:129]
	ds_read_b128 v[184:187], v153 offset:32768
	ds_read_b128 v[188:191], v153 offset:33792
	ds_read_b128 v[192:195], v153 offset:34816
	ds_read_b128 v[196:199], v153 offset:35840
	ds_read_b128 v[202:205], v153 offset:36864
	ds_read_b128 v[206:209], v153 offset:37888
	ds_read_b128 v[210:213], v153 offset:38912
	ds_read_b128 v[214:217], v153 offset:39936
	global_load_lds_dwordx4 v[230:231], off
	v_lshl_add_u64 v[230:231], s[46:47], 0, v[132:133]
	s_mov_b32 m0, s53
	s_nop 0
	global_load_lds_dwordx4 v[230:231], off
	s_waitcnt vmcnt(8)
	s_waitcnt lgkmcnt(0)
	s_barrier
	s_waitcnt lgkmcnt(0)
	v_mfma_f32_16x16x32_bf16 v[124:127], v[144:147], v[184:187], v[124:127]
	v_mfma_f32_16x16x32_bf16 v[120:123], v[160:163], v[184:187], v[120:123]
	v_mfma_f32_16x16x32_bf16 v[108:111], v[144:147], v[192:195], v[108:111]
	v_mfma_f32_16x16x32_bf16 v[104:107], v[160:163], v[192:195], v[104:107]
	v_mfma_f32_16x16x32_bf16 v[92:95], v[144:147], v[202:205], v[92:95]
	v_mfma_f32_16x16x32_bf16 v[88:91], v[160:163], v[202:205], v[88:91]
	v_mfma_f32_16x16x32_bf16 v[76:79], v[144:147], v[210:213], v[76:79]
	v_mfma_f32_16x16x32_bf16 v[72:75], v[160:163], v[210:213], v[72:75]
	v_mfma_f32_16x16x32_bf16 v[124:127], v[156:159], v[188:191], v[124:127]
	v_mfma_f32_16x16x32_bf16 v[120:123], v[164:167], v[188:191], v[120:123]
	v_mfma_f32_16x16x32_bf16 v[108:111], v[156:159], v[196:199], v[108:111]
	v_mfma_f32_16x16x32_bf16 v[104:107], v[164:167], v[196:199], v[104:107]
	v_mfma_f32_16x16x32_bf16 v[92:95], v[156:159], v[206:209], v[92:95]
	v_mfma_f32_16x16x32_bf16 v[88:91], v[164:167], v[206:209], v[88:91]
	v_mfma_f32_16x16x32_bf16 v[76:79], v[156:159], v[214:217], v[76:79]
	v_mfma_f32_16x16x32_bf16 v[72:75], v[164:167], v[214:217], v[72:75]
	v_mfma_f32_16x16x32_bf16 v[116:119], v[168:171], v[184:187], v[116:119]
	v_mfma_f32_16x16x32_bf16 v[112:115], v[176:179], v[184:187], v[112:115]
	v_mfma_f32_16x16x32_bf16 v[100:103], v[168:171], v[192:195], v[100:103]
	v_mfma_f32_16x16x32_bf16 v[96:99], v[176:179], v[192:195], v[96:99]
	v_mfma_f32_16x16x32_bf16 v[84:87], v[168:171], v[202:205], v[84:87]
	v_mfma_f32_16x16x32_bf16 v[80:83], v[176:179], v[202:205], v[80:83]
	v_mfma_f32_16x16x32_bf16 v[68:71], v[168:171], v[210:213], v[68:71]
	v_mfma_f32_16x16x32_bf16 v[64:67], v[176:179], v[210:213], v[64:67]
	v_mfma_f32_16x16x32_bf16 v[116:119], v[172:175], v[188:191], v[116:119]
	v_mfma_f32_16x16x32_bf16 v[112:115], v[180:183], v[188:191], v[112:115]
	v_mfma_f32_16x16x32_bf16 v[100:103], v[172:175], v[196:199], v[100:103]
	v_mfma_f32_16x16x32_bf16 v[96:99], v[180:183], v[196:199], v[96:99]
	v_mfma_f32_16x16x32_bf16 v[84:87], v[172:175], v[206:209], v[84:87]
	v_mfma_f32_16x16x32_bf16 v[80:83], v[180:183], v[206:209], v[80:83]
	v_mfma_f32_16x16x32_bf16 v[68:71], v[172:175], v[214:217], v[68:71]
	v_mfma_f32_16x16x32_bf16 v[64:67], v[180:183], v[214:217], v[64:67]
	s_barrier
; #define PG8_STAGE(bufoff, gbase, voff) do { _Pragma("unroll") for (int _i = 0; _i < 2; ++_i) \
;         __builtin_amdgcn_global_load_lds((const unsigned*)((const char*)(gbase) + (voff)[_i]), (PG8_LAS unsigned*)(lds + (bufoff) + ldsw + _i * 8192), 16, 0, 0); } while (0)
; #define PG8_LDA(dst, b, h) do { _Pragma("unroll") for (int m = 0; m < 4; ++m) _Pragma("unroll") for (int k = 0; k < 2; ++k) dst[m][k] = *(const PG8_LAS bf16x8*)(lds + PG8_SA(b, h) + aoff + m * 2048 + k * 1024); } while (0)
; #define PG8_LDB(dst, b, h) do { _Pragma("unroll") for (int n = 0; n < 2; ++n) _Pragma("unroll") for (int k = 0; k < 2; ++k) dst[n][k] = *(const PG8_LAS bf16x8*)(lds + PG8_SB(b, h) + boff + n * 2048 + k * 1024); } while (0)
; template <class Epi, class Sched, bool ALIGN_EPI = false, bool SP2 = false>
; __device__ __forceinline__ void gemm_phase(PG8_LAS unsigned char* lds, const Gemm g, const Sched& S, const Epi& E) {
;     ...
;         for (int t = 0; t < nt; t += 2) {
;             const bool last = (t == nt - 2);
;             const char* a1 = cA + (size_t)(t + 1) * kstep;
;             const char* a2 = last ? nA : cA + (size_t)(t + 2) * kstep; const char* b2 = last ? nB : cB + (size_t)(t + 2) * kstep;
;             const char* a3 = a2 + kstep; const char* b3 = b2 + kstep;
;             if (last && has_next) S.a_ready(nxt);
;             if constexpr (SP2) {
;             PG8_LDB(B0, 0, 0); PG8_LDB(B1, 0, 1); PG8_SCHED; PG8_LDA(At, 0, 0); PG8_STAGE(PG8_SA(1, 1), a1 + hstep, voffA);
;             PG8_WAIT_V(8); PG8_WAIT_L(0); PG8_BAR; PG8_MMA(0, 0, At, B0); PG8_MMA(0, 1, At, B1); PG8_BAR; PG8_SCHED;
;             PG8_LDA(At, 0, 1); PG8_STAGE(PG8_SB(0, 0), b2, voffB); PG8_STAGE(PG8_SB(0, 1), b2 + hstep, voffB); PG8_STAGE(PG8_SA(0, 0), a2, voffA);
;             PG8_WAIT_V(8); PG8_WAIT_L(0); PG8_BAR; PG8_MMA(1, 0, At, B0); PG8_MMA(1, 1, At, B1); PG8_BAR; PG8_SCHED;
;             PG8_LDB(B0, 1, 0); PG8_LDB(B1, 1, 1); PG8_SCHED; PG8_LDA(At, 1, 0); PG8_STAGE(PG8_SA(0, 1), a2 + hstep, voffA);
;             PG8_WAIT_V(8); PG8_WAIT_L(0); PG8_BAR; PG8_MMA(0, 0, At, B0); PG8_MMA(0, 1, At, B1); PG8_BAR; PG8_SCHED;
;             PG8_LDA(At, 1, 1); PG8_STAGE(PG8_SB(1, 0), b3, voffB); PG8_STAGE(PG8_SB(1, 1), b3 + hstep, voffB); PG8_STAGE(PG8_SA(1, 0), a3, voffA);
;             PG8_WAIT_V(8); PG8_WAIT_L(0); PG8_BAR; PG8_MMA(1, 0, At, B0); PG8_MMA(1, 1, At, B1); PG8_BAR; PG8_SCHED;
	s_add_i32 s16, s16, s49
	v_lshl_add_u64 v[218:219], v[218:219], 0, s[36:37]
	s_mov_b32 m0, s16
	ds_read_b128 v[184:187], v153 offset:49152
	ds_read_b128 v[188:191], v153 offset:50176
	ds_read_b128 v[192:195], v153 offset:51200
	ds_read_b128 v[196:199], v153 offset:52224
	ds_read_b128 v[202:205], v153 offset:53248
	ds_read_b128 v[206:209], v153 offset:54272
	ds_read_b128 v[210:213], v153 offset:55296
	ds_read_b128 v[214:217], v153 offset:56320
	global_load_lds_dwordx4 v[218:219], off
	v_lshl_add_u64 v[218:219], v[220:221], 0, s[36:37]
	s_add_i32 m0, s16, 0x2000
	s_add_i32 s16, s17, s49
	global_load_lds_dwordx4 v[218:219], off
	v_lshl_add_u64 v[218:219], v[222:223], 0, s[36:37]
	s_mov_b32 m0, s16
	s_nop 0
	global_load_lds_dwordx4 v[218:219], off
	v_lshl_add_u64 v[218:219], v[224:225], 0, s[36:37]
	s_add_i32 m0, s16, 0x2000
	s_nop 0
	global_load_lds_dwordx4 v[218:219], off
	v_lshl_add_u64 v[218:219], v[226:227], 0, s[100:101]
	s_mov_b32 m0, s54
	s_nop 0
	global_load_lds_dwordx4 v[218:219], off
	v_lshl_add_u64 v[218:219], v[228:229], 0, s[100:101]
	s_mov_b32 m0, s55
	s_nop 0
	global_load_lds_dwordx4 v[218:219], off
	s_waitcnt vmcnt(8)
	s_waitcnt lgkmcnt(0)
	s_barrier
	s_waitcnt lgkmcnt(0)
	v_mfma_f32_16x16x32_bf16 v[60:63], v[144:147], v[184:187], v[60:63]
	v_mfma_f32_16x16x32_bf16 v[56:59], v[160:163], v[184:187], v[56:59]
	v_mfma_f32_16x16x32_bf16 v[44:47], v[144:147], v[192:195], v[44:47]
	v_mfma_f32_16x16x32_bf16 v[40:43], v[160:163], v[192:195], v[40:43]
	v_mfma_f32_16x16x32_bf16 v[28:31], v[144:147], v[202:205], v[28:31]
	v_mfma_f32_16x16x32_bf16 v[24:27], v[160:163], v[202:205], v[24:27]
	v_mfma_f32_16x16x32_bf16 v[12:15], v[144:147], v[210:213], v[12:15]
	v_mfma_f32_16x16x32_bf16 v[8:11], v[160:163], v[210:213], v[8:11]
	v_mfma_f32_16x16x32_bf16 v[60:63], v[156:159], v[188:191], v[60:63]
	v_mfma_f32_16x16x32_bf16 v[56:59], v[164:167], v[188:191], v[56:59]
	v_mfma_f32_16x16x32_bf16 v[44:47], v[156:159], v[196:199], v[44:47]
	v_mfma_f32_16x16x32_bf16 v[40:43], v[164:167], v[196:199], v[40:43]
	v_mfma_f32_16x16x32_bf16 v[28:31], v[156:159], v[206:209], v[28:31]
	v_mfma_f32_16x16x32_bf16 v[24:27], v[164:167], v[206:209], v[24:27]
	v_mfma_f32_16x16x32_bf16 v[12:15], v[156:159], v[214:217], v[12:15]
	v_mfma_f32_16x16x32_bf16 v[8:11], v[164:167], v[214:217], v[8:11]
	v_mfma_f32_16x16x32_bf16 v[52:55], v[168:171], v[184:187], v[52:55]
	v_mfma_f32_16x16x32_bf16 v[48:51], v[176:179], v[184:187], v[48:51]
	v_mfma_f32_16x16x32_bf16 v[36:39], v[168:171], v[192:195], v[36:39]
	v_mfma_f32_16x16x32_bf16 v[32:35], v[176:179], v[192:195], v[32:35]
	v_mfma_f32_16x16x32_bf16 v[20:23], v[168:171], v[202:205], v[20:23]
	v_mfma_f32_16x16x32_bf16 v[16:19], v[176:179], v[202:205], v[16:19]
	v_mfma_f32_16x16x32_bf16 v[4:7], v[168:171], v[210:213], v[4:7]
	v_mfma_f32_16x16x32_bf16 v[0:3], v[176:179], v[210:213], v[0:3]
	v_mfma_f32_16x16x32_bf16 v[52:55], v[172:175], v[188:191], v[52:55]
	v_mfma_f32_16x16x32_bf16 v[48:51], v[180:183], v[188:191], v[48:51]
	v_mfma_f32_16x16x32_bf16 v[36:39], v[172:175], v[196:199], v[36:39]
	v_mfma_f32_16x16x32_bf16 v[32:35], v[180:183], v[196:199], v[32:35]
	v_mfma_f32_16x16x32_bf16 v[20:23], v[172:175], v[206:209], v[20:23]
	v_mfma_f32_16x16x32_bf16 v[16:19], v[180:183], v[206:209], v[16:19]
	v_mfma_f32_16x16x32_bf16 v[4:7], v[172:175], v[214:217], v[4:7]
	v_mfma_f32_16x16x32_bf16 v[0:3], v[180:183], v[214:217], v[0:3]
	s_barrier
	s_add_u32 s44, s44, 0x10000
	s_addc_u32 s45, s45, 0
	s_add_u32 s68, s68, 0x100
	s_addc_u32 s69, s69, 0
	s_cmp_ge_i32 s70, s57
	s_mov_b32 s46, s70
	s_cbranch_scc1 .LBB0_1105
.LBB0_1104:
	ds_read_b128 v[144:147], v151
	ds_read_b128 v[156:159], v151 offset:1024
	ds_read_b128 v[160:163], v151 offset:2048
	ds_read_b128 v[164:167], v151 offset:3072
	ds_read_b128 v[168:171], v152
	ds_read_b128 v[172:175], v152 offset:1024
	ds_read_b128 v[176:179], v152 offset:2048
	ds_read_b128 v[180:183], v152 offset:3072
	s_add_i32 s70, s46, 2
	s_add_u32 s16, s44, 0x8000
	s_addc_u32 s17, s45, 0
	s_cmp_eq_u32 s58, s46
	s_cselect_b32 s46, s0, s16
	s_cselect_b32 s47, s1, s17
	s_cselect_b32 s73, s43, s69
	s_cselect_b32 s72, s42, s68
	v_lshl_add_u64 v[218:219], s[44:45], 0, v[136:137]
	s_add_i32 m0, s50, 0xc000
	ds_read_b128 v[184:187], v153
	ds_read_b128 v[188:191], v153 offset:1024
	ds_read_b128 v[192:195], v153 offset:2048
	ds_read_b128 v[196:199], v153 offset:3072
	ds_read_b128 v[202:205], v153 offset:4096
	ds_read_b128 v[206:209], v153 offset:5120
	ds_read_b128 v[210:213], v153 offset:6144
	ds_read_b128 v[214:217], v153 offset:7168
	global_load_lds_dwordx4 v[218:219], off
	v_lshl_add_u64 v[218:219], s[44:45], 0, v[138:139]
	s_add_i32 m0, s50, 0xe000
	s_nop 0
	global_load_lds_dwordx4 v[218:219], off
	s_waitcnt vmcnt(8)
	s_waitcnt lgkmcnt(0)
	s_barrier
; #define PG8_STAGE(bufoff, gbase, voff) do { _Pragma("unroll") for (int _i = 0; _i < 2; ++_i) \
;         __builtin_amdgcn_global_load_lds((const unsigned*)((const char*)(gbase) + (voff)[_i]), (PG8_LAS unsigned*)(lds + (bufoff) + ldsw + _i * 8192), 16, 0, 0); } while (0)
; #define PG8_LDA(dst, b, h) do { _Pragma("unroll") for (int m = 0; m < 4; ++m) _Pragma("unroll") for (int k = 0; k < 2; ++k) dst[m][k] = *(const PG8_LAS bf16x8*)(lds + PG8_SA(b, h) + aoff + m * 2048 + k * 1024); } while (0)
; #define PG8_LDB(dst, b, h) do { _Pragma("unroll") for (int n = 0; n < 2; ++n) _Pragma("unroll") for (int k = 0; k < 2; ++k) dst[n][k] = *(const PG8_LAS bf16x8*)(lds + PG8_SB(b, h) + boff + n * 2048 + k * 1024); } while (0)
; #define PG8_MMA(ai, bj, At, Bt) do { __builtin_amdgcn_s_setprio(1); _Pragma("unroll") for (int m = 0; m < 4; ++m) _Pragma("unroll") for (int n = 0; n < 2; ++n) _Pragma("unroll") for (int k = 0; k < 2; ++k) \
;         acc[ai][bj][m][n] = __builtin_amdgcn_mfma_f32_16x16x32_bf16(Bt[n][k], At[m][k], acc[ai][bj][m][n], 0, 0, 0); __builtin_amdgcn_s_setprio(0); } while (0)
; #define PG8_WAIT_V(n) asm volatile("s_waitcnt vmcnt(" #n ")" ::: "memory")
; #define PG8_WAIT_L(n) asm volatile("s_waitcnt lgkmcnt(" #n ")" ::: "memory")
; #define PG8_BAR __builtin_amdgcn_s_barrier()
; #define PG8_SCHED __builtin_amdgcn_sched_barrier(0)
; template <class Epi, class Sched, bool ALIGN_EPI = false, bool SP2 = false>
; __device__ __forceinline__ void gemm_phase(PG8_LAS unsigned char* lds, const Gemm g, const Sched& S, const Epi& E) {
;     ...
;             PG8_LDB(B0, 0, 0); PG8_LDB(B1, 0, 1); PG8_SCHED; PG8_LDA(At, 0, 0); PG8_STAGE(PG8_SA(1, 1), a1 + hstep, voffA);
;             PG8_WAIT_V(8); PG8_WAIT_L(0); PG8_BAR; PG8_MMA(0, 0, At, B0); PG8_MMA(0, 1, At, B1); PG8_BAR; PG8_SCHED;
;             PG8_LDA(At, 0, 1); PG8_STAGE(PG8_SB(0, 0), b2, voffB); PG8_STAGE(PG8_SB(0, 1), b2 + hstep, voffB); PG8_STAGE(PG8_SA(0, 0), a2, voffA);
;             PG8_WAIT_V(8); PG8_WAIT_L(0); PG8_BAR; PG8_MMA(1, 0, At, B0); PG8_MMA(1, 1, At, B1); PG8_BAR; PG8_SCHED;
	s_waitcnt lgkmcnt(0)
	v_mfma_f32_16x16x32_bf16 v[124:127], v[144:147], v[184:187], v[124:127]
	v_mfma_f32_16x16x32_bf16 v[120:123], v[160:163], v[184:187], v[120:123]
	v_mfma_f32_16x16x32_bf16 v[108:111], v[144:147], v[192:195], v[108:111]
	v_mfma_f32_16x16x32_bf16 v[104:107], v[160:163], v[192:195], v[104:107]
	v_mfma_f32_16x16x32_bf16 v[92:95], v[144:147], v[202:205], v[92:95]
	v_mfma_f32_16x16x32_bf16 v[88:91], v[160:163], v[202:205], v[88:91]
	v_mfma_f32_16x16x32_bf16 v[76:79], v[144:147], v[210:213], v[76:79]
	v_mfma_f32_16x16x32_bf16 v[72:75], v[160:163], v[210:213], v[72:75]
	v_mfma_f32_16x16x32_bf16 v[124:127], v[156:159], v[188:191], v[124:127]
	v_mfma_f32_16x16x32_bf16 v[120:123], v[164:167], v[188:191], v[120:123]
	v_mfma_f32_16x16x32_bf16 v[108:111], v[156:159], v[196:199], v[108:111]
	v_mfma_f32_16x16x32_bf16 v[104:107], v[164:167], v[196:199], v[104:107]
	v_mfma_f32_16x16x32_bf16 v[92:95], v[156:159], v[206:209], v[92:95]
	v_mfma_f32_16x16x32_bf16 v[88:91], v[164:167], v[206:209], v[88:91]
	v_mfma_f32_16x16x32_bf16 v[76:79], v[156:159], v[214:217], v[76:79]
	v_mfma_f32_16x16x32_bf16 v[72:75], v[164:167], v[214:217], v[72:75]
	v_mfma_f32_16x16x32_bf16 v[116:119], v[168:171], v[184:187], v[116:119]
	v_mfma_f32_16x16x32_bf16 v[112:115], v[176:179], v[184:187], v[112:115]
	v_mfma_f32_16x16x32_bf16 v[100:103], v[168:171], v[192:195], v[100:103]
	v_mfma_f32_16x16x32_bf16 v[96:99], v[176:179], v[192:195], v[96:99]
	v_mfma_f32_16x16x32_bf16 v[84:87], v[168:171], v[202:205], v[84:87]
	v_mfma_f32_16x16x32_bf16 v[80:83], v[176:179], v[202:205], v[80:83]
	v_mfma_f32_16x16x32_bf16 v[68:71], v[168:171], v[210:213], v[68:71]
	v_mfma_f32_16x16x32_bf16 v[64:67], v[176:179], v[210:213], v[64:67]
	v_mfma_f32_16x16x32_bf16 v[116:119], v[172:175], v[188:191], v[116:119]
	v_mfma_f32_16x16x32_bf16 v[112:115], v[180:183], v[188:191], v[112:115]
	v_mfma_f32_16x16x32_bf16 v[100:103], v[172:175], v[196:199], v[100:103]
	v_mfma_f32_16x16x32_bf16 v[96:99], v[180:183], v[196:199], v[96:99]
	v_mfma_f32_16x16x32_bf16 v[84:87], v[172:175], v[206:209], v[84:87]
	v_mfma_f32_16x16x32_bf16 v[80:83], v[180:183], v[206:209], v[80:83]
	v_mfma_f32_16x16x32_bf16 v[68:71], v[172:175], v[214:217], v[68:71]
	v_mfma_f32_16x16x32_bf16 v[64:67], v[180:183], v[214:217], v[64:67]
	s_barrier
	s_add_i32 s16, s62, s49
	v_lshl_add_u64 v[218:219], s[72:73], 0, v[130:131]
	s_mov_b32 m0, s16
	ds_read_b128 v[184:187], v153 offset:16384
	ds_read_b128 v[188:191], v153 offset:17408
	ds_read_b128 v[192:195], v153 offset:18432
	ds_read_b128 v[196:199], v153 offset:19456
	ds_read_b128 v[202:205], v153 offset:20480
	ds_read_b128 v[206:209], v153 offset:21504
	ds_read_b128 v[210:213], v153 offset:22528
	ds_read_b128 v[214:217], v153 offset:23552
	global_load_lds_dwordx4 v[218:219], off
	s_add_i32 m0, s16, 0x2000
	v_lshl_add_u64 v[220:221], s[72:73], 0, v[134:135]
	s_add_u32 s72, s72, s8
	s_addc_u32 s73, s73, s9
	s_add_i32 s16, s63, s49
	global_load_lds_dwordx4 v[220:221], off
	v_lshl_add_u64 v[222:223], s[72:73], 0, v[130:131]
	s_mov_b32 m0, s16
	v_lshl_add_u64 v[224:225], s[72:73], 0, v[134:135]
	global_load_lds_dwordx4 v[222:223], off
	s_add_i32 m0, s16, 0x2000
	v_lshl_add_u64 v[226:227], s[46:47], 0, v[128:129]
	global_load_lds_dwordx4 v[224:225], off
	s_mov_b32 m0, s50
	v_lshl_add_u64 v[228:229], s[46:47], 0, v[132:133]
	global_load_lds_dwordx4 v[226:227], off
	s_mov_b32 m0, s51
	s_nop 0
	global_load_lds_dwordx4 v[228:229], off
	s_waitcnt vmcnt(8)
	s_waitcnt lgkmcnt(0)
	s_barrier
	s_waitcnt lgkmcnt(0)
	v_mfma_f32_16x16x32_bf16 v[60:63], v[144:147], v[184:187], v[60:63]
	v_mfma_f32_16x16x32_bf16 v[56:59], v[160:163], v[184:187], v[56:59]
	v_mfma_f32_16x16x32_bf16 v[44:47], v[144:147], v[192:195], v[44:47]
	v_mfma_f32_16x16x32_bf16 v[40:43], v[160:163], v[192:195], v[40:43]
	v_mfma_f32_16x16x32_bf16 v[28:31], v[144:147], v[202:205], v[28:31]
	v_mfma_f32_16x16x32_bf16 v[24:27], v[160:163], v[202:205], v[24:27]
	v_mfma_f32_16x16x32_bf16 v[12:15], v[144:147], v[210:213], v[12:15]
	v_mfma_f32_16x16x32_bf16 v[8:11], v[160:163], v[210:213], v[8:11]
	v_mfma_f32_16x16x32_bf16 v[60:63], v[156:159], v[188:191], v[60:63]
	v_mfma_f32_16x16x32_bf16 v[56:59], v[164:167], v[188:191], v[56:59]
	v_mfma_f32_16x16x32_bf16 v[44:47], v[156:159], v[196:199], v[44:47]
	v_mfma_f32_16x16x32_bf16 v[40:43], v[164:167], v[196:199], v[40:43]
	v_mfma_f32_16x16x32_bf16 v[28:31], v[156:159], v[206:209], v[28:31]
	v_mfma_f32_16x16x32_bf16 v[24:27], v[164:167], v[206:209], v[24:27]
	v_mfma_f32_16x16x32_bf16 v[12:15], v[156:159], v[214:217], v[12:15]
	v_mfma_f32_16x16x32_bf16 v[8:11], v[164:167], v[214:217], v[8:11]
	v_mfma_f32_16x16x32_bf16 v[52:55], v[168:171], v[184:187], v[52:55]
	v_mfma_f32_16x16x32_bf16 v[48:51], v[176:179], v[184:187], v[48:51]
	v_mfma_f32_16x16x32_bf16 v[36:39], v[168:171], v[192:195], v[36:39]
	v_mfma_f32_16x16x32_bf16 v[32:35], v[176:179], v[192:195], v[32:35]
	v_mfma_f32_16x16x32_bf16 v[20:23], v[168:171], v[202:205], v[20:23]
	v_mfma_f32_16x16x32_bf16 v[16:19], v[176:179], v[202:205], v[16:19]
	v_mfma_f32_16x16x32_bf16 v[4:7], v[168:171], v[210:213], v[4:7]
	v_mfma_f32_16x16x32_bf16 v[0:3], v[176:179], v[210:213], v[0:3]
	v_mfma_f32_16x16x32_bf16 v[52:55], v[172:175], v[188:191], v[52:55]
	v_mfma_f32_16x16x32_bf16 v[48:51], v[180:183], v[188:191], v[48:51]
	v_mfma_f32_16x16x32_bf16 v[36:39], v[172:175], v[196:199], v[36:39]
	v_mfma_f32_16x16x32_bf16 v[32:35], v[180:183], v[196:199], v[32:35]
	v_mfma_f32_16x16x32_bf16 v[20:23], v[172:175], v[206:209], v[20:23]
	v_mfma_f32_16x16x32_bf16 v[16:19], v[180:183], v[206:209], v[16:19]
	v_mfma_f32_16x16x32_bf16 v[4:7], v[172:175], v[214:217], v[4:7]
	v_mfma_f32_16x16x32_bf16 v[0:3], v[180:183], v[214:217], v[0:3]
	s_barrier
; #define PG8_STAGE(bufoff, gbase, voff) do { _Pragma("unroll") for (int _i = 0; _i < 2; ++_i) \
;         __builtin_amdgcn_global_load_lds((const unsigned*)((const char*)(gbase) + (voff)[_i]), (PG8_LAS unsigned*)(lds + (bufoff) + ldsw + _i * 8192), 16, 0, 0); } while (0)
; #define PG8_LDA(dst, b, h) do { _Pragma("unroll") for (int m = 0; m < 4; ++m) _Pragma("unroll") for (int k = 0; k < 2; ++k) dst[m][k] = *(const PG8_LAS bf16x8*)(lds + PG8_SA(b, h) + aoff + m * 2048 + k * 1024); } while (0)
; #define PG8_LDB(dst, b, h) do { _Pragma("unroll") for (int n = 0; n < 2; ++n) _Pragma("unroll") for (int k = 0; k < 2; ++k) dst[n][k] = *(const PG8_LAS bf16x8*)(lds + PG8_SB(b, h) + boff + n * 2048 + k * 1024); } while (0)
; #define PG8_MMA(ai, bj, At, Bt) do { __builtin_amdgcn_s_setprio(1); _Pragma("unroll") for (int m = 0; m < 4; ++m) _Pragma("unroll") for (int n = 0; n < 2; ++n) _Pragma("unroll") for (int k = 0; k < 2; ++k) \
;         acc[ai][bj][m][n] = __builtin_amdgcn_mfma_f32_16x16x32_bf16(Bt[n][k], At[m][k], acc[ai][bj][m][n], 0, 0, 0); __builtin_amdgcn_s_setprio(0); } while (0)
; #define PG8_WAIT_V(n) asm volatile("s_waitcnt vmcnt(" #n ")" ::: "memory")
; #define PG8_WAIT_L(n) asm volatile("s_waitcnt lgkmcnt(" #n ")" ::: "memory")
; #define PG8_BAR __builtin_amdgcn_s_barrier()
; #define PG8_SCHED __builtin_amdgcn_sched_barrier(0)
; template <class Epi, class Sched, bool ALIGN_EPI = false, bool SP2 = false>
; __device__ __forceinline__ void gemm_phase(PG8_LAS unsigned char* lds, const Gemm g, const Sched& S, const Epi& E) {
;     ...
;             PG8_LDB(B0, 1, 0); PG8_LDB(B1, 1, 1); PG8_SCHED; PG8_LDA(At, 1, 0); PG8_STAGE(PG8_SA(0, 1), a2 + hstep, voffA);
;             PG8_WAIT_V(8); PG8_WAIT_L(0); PG8_BAR; PG8_MMA(0, 0, At, B0); PG8_MMA(0, 1, At, B1); PG8_BAR; PG8_SCHED;
;             PG8_LDA(At, 1, 1); PG8_STAGE(PG8_SB(1, 0), b3, voffB); PG8_STAGE(PG8_SB(1, 1), b3 + hstep, voffB); PG8_STAGE(PG8_SA(1, 0), a3, voffA);
;             PG8_WAIT_V(8); PG8_WAIT_L(0); PG8_BAR; PG8_MMA(1, 0, At, B0); PG8_MMA(1, 1, At, B1); PG8_BAR; PG8_SCHED;
	s_add_i32 s16, 0, 0x18000
	v_add_u32_e32 v155, s16, v149
	s_add_i32 s17, 0, 0x1c000
	ds_read_b128 v[144:147], v155
	ds_read_b128 v[156:159], v155 offset:1024
	ds_read_b128 v[160:163], v155 offset:2048
	ds_read_b128 v[164:167], v155 offset:3072
	v_add_u32_e32 v155, s17, v149
	ds_read_b128 v[168:171], v155
	ds_read_b128 v[172:175], v155 offset:1024
	ds_read_b128 v[176:179], v155 offset:2048
	ds_read_b128 v[180:183], v155 offset:3072
	s_add_u32 s46, s46, 0x2000
	s_addc_u32 s47, s47, 0
	s_mov_b32 m0, s52
	v_lshl_add_u64 v[230:231], s[46:47], 0, v[128:129]
	ds_read_b128 v[184:187], v153 offset:32768
	ds_read_b128 v[188:191], v153 offset:33792
	ds_read_b128 v[192:195], v153 offset:34816
	ds_read_b128 v[196:199], v153 offset:35840
	ds_read_b128 v[202:205], v153 offset:36864
	ds_read_b128 v[206:209], v153 offset:37888
	ds_read_b128 v[210:213], v153 offset:38912
	ds_read_b128 v[214:217], v153 offset:39936
	global_load_lds_dwordx4 v[230:231], off
	v_lshl_add_u64 v[230:231], s[46:47], 0, v[132:133]
	s_mov_b32 m0, s53
	s_nop 0
	global_load_lds_dwordx4 v[230:231], off
	s_waitcnt vmcnt(8)
	s_waitcnt lgkmcnt(0)
	s_barrier
	s_waitcnt lgkmcnt(0)
	v_mfma_f32_16x16x32_bf16 v[124:127], v[144:147], v[184:187], v[124:127]
	v_mfma_f32_16x16x32_bf16 v[120:123], v[160:163], v[184:187], v[120:123]
	v_mfma_f32_16x16x32_bf16 v[108:111], v[144:147], v[192:195], v[108:111]
	v_mfma_f32_16x16x32_bf16 v[104:107], v[160:163], v[192:195], v[104:107]
	v_mfma_f32_16x16x32_bf16 v[92:95], v[144:147], v[202:205], v[92:95]
	v_mfma_f32_16x16x32_bf16 v[88:91], v[160:163], v[202:205], v[88:91]
	v_mfma_f32_16x16x32_bf16 v[76:79], v[144:147], v[210:213], v[76:79]
	v_mfma_f32_16x16x32_bf16 v[72:75], v[160:163], v[210:213], v[72:75]
	v_mfma_f32_16x16x32_bf16 v[124:127], v[156:159], v[188:191], v[124:127]
	v_mfma_f32_16x16x32_bf16 v[120:123], v[164:167], v[188:191], v[120:123]
	v_mfma_f32_16x16x32_bf16 v[108:111], v[156:159], v[196:199], v[108:111]
	v_mfma_f32_16x16x32_bf16 v[104:107], v[164:167], v[196:199], v[104:107]
	v_mfma_f32_16x16x32_bf16 v[92:95], v[156:159], v[206:209], v[92:95]
	v_mfma_f32_16x16x32_bf16 v[88:91], v[164:167], v[206:209], v[88:91]
	v_mfma_f32_16x16x32_bf16 v[76:79], v[156:159], v[214:217], v[76:79]
	v_mfma_f32_16x16x32_bf16 v[72:75], v[164:167], v[214:217], v[72:75]
	v_mfma_f32_16x16x32_bf16 v[116:119], v[168:171], v[184:187], v[116:119]
	v_mfma_f32_16x16x32_bf16 v[112:115], v[176:179], v[184:187], v[112:115]
	v_mfma_f32_16x16x32_bf16 v[100:103], v[168:171], v[192:195], v[100:103]
	v_mfma_f32_16x16x32_bf16 v[96:99], v[176:179], v[192:195], v[96:99]
	v_mfma_f32_16x16x32_bf16 v[84:87], v[168:171], v[202:205], v[84:87]
	v_mfma_f32_16x16x32_bf16 v[80:83], v[176:179], v[202:205], v[80:83]
	v_mfma_f32_16x16x32_bf16 v[68:71], v[168:171], v[210:213], v[68:71]
	v_mfma_f32_16x16x32_bf16 v[64:67], v[176:179], v[210:213], v[64:67]
	v_mfma_f32_16x16x32_bf16 v[116:119], v[172:175], v[188:191], v[116:119]
	v_mfma_f32_16x16x32_bf16 v[112:115], v[180:183], v[188:191], v[112:115]
	v_mfma_f32_16x16x32_bf16 v[100:103], v[172:175], v[196:199], v[100:103]
	v_mfma_f32_16x16x32_bf16 v[96:99], v[180:183], v[196:199], v[96:99]
	v_mfma_f32_16x16x32_bf16 v[84:87], v[172:175], v[206:209], v[84:87]
	v_mfma_f32_16x16x32_bf16 v[80:83], v[180:183], v[206:209], v[80:83]
	v_mfma_f32_16x16x32_bf16 v[68:71], v[172:175], v[214:217], v[68:71]
	v_mfma_f32_16x16x32_bf16 v[64:67], v[180:183], v[214:217], v[64:67]
	s_barrier
	s_add_i32 s16, s16, s49
	v_lshl_add_u64 v[218:219], v[218:219], 0, s[36:37]
	s_mov_b32 m0, s16
	ds_read_b128 v[184:187], v153 offset:49152
	ds_read_b128 v[188:191], v153 offset:50176
	ds_read_b128 v[192:195], v153 offset:51200
	ds_read_b128 v[196:199], v153 offset:52224
	ds_read_b128 v[202:205], v153 offset:53248
	ds_read_b128 v[206:209], v153 offset:54272
	ds_read_b128 v[210:213], v153 offset:55296
	ds_read_b128 v[214:217], v153 offset:56320
	global_load_lds_dwordx4 v[218:219], off
	v_lshl_add_u64 v[218:219], v[220:221], 0, s[36:37]
	s_add_i32 m0, s16, 0x2000
	s_add_i32 s16, s17, s49
	global_load_lds_dwordx4 v[218:219], off
	v_lshl_add_u64 v[218:219], v[222:223], 0, s[36:37]
	s_mov_b32 m0, s16
	s_nop 0
	global_load_lds_dwordx4 v[218:219], off
	v_lshl_add_u64 v[218:219], v[224:225], 0, s[36:37]
	s_add_i32 m0, s16, 0x2000
	s_nop 0
	global_load_lds_dwordx4 v[218:219], off
	v_lshl_add_u64 v[218:219], v[226:227], 0, s[100:101]
	s_mov_b32 m0, s54
	s_nop 0
	global_load_lds_dwordx4 v[218:219], off
	v_lshl_add_u64 v[218:219], v[228:229], 0, s[100:101]
	s_mov_b32 m0, s55
	s_nop 0
	global_load_lds_dwordx4 v[218:219], off
	s_waitcnt vmcnt(8)
	s_waitcnt lgkmcnt(0)
	s_barrier
	s_waitcnt lgkmcnt(0)
	v_mfma_f32_16x16x32_bf16 v[60:63], v[144:147], v[184:187], v[60:63]
	v_mfma_f32_16x16x32_bf16 v[56:59], v[160:163], v[184:187], v[56:59]
	v_mfma_f32_16x16x32_bf16 v[44:47], v[144:147], v[192:195], v[44:47]
	v_mfma_f32_16x16x32_bf16 v[40:43], v[160:163], v[192:195], v[40:43]
	v_mfma_f32_16x16x32_bf16 v[28:31], v[144:147], v[202:205], v[28:31]
	v_mfma_f32_16x16x32_bf16 v[24:27], v[160:163], v[202:205], v[24:27]
	v_mfma_f32_16x16x32_bf16 v[12:15], v[144:147], v[210:213], v[12:15]
	v_mfma_f32_16x16x32_bf16 v[8:11], v[160:163], v[210:213], v[8:11]
	v_mfma_f32_16x16x32_bf16 v[60:63], v[156:159], v[188:191], v[60:63]
	v_mfma_f32_16x16x32_bf16 v[56:59], v[164:167], v[188:191], v[56:59]
	v_mfma_f32_16x16x32_bf16 v[44:47], v[156:159], v[196:199], v[44:47]
	v_mfma_f32_16x16x32_bf16 v[40:43], v[164:167], v[196:199], v[40:43]
	v_mfma_f32_16x16x32_bf16 v[28:31], v[156:159], v[206:209], v[28:31]
	v_mfma_f32_16x16x32_bf16 v[24:27], v[164:167], v[206:209], v[24:27]
	v_mfma_f32_16x16x32_bf16 v[12:15], v[156:159], v[214:217], v[12:15]
	v_mfma_f32_16x16x32_bf16 v[8:11], v[164:167], v[214:217], v[8:11]
	v_mfma_f32_16x16x32_bf16 v[52:55], v[168:171], v[184:187], v[52:55]
	v_mfma_f32_16x16x32_bf16 v[48:51], v[176:179], v[184:187], v[48:51]
	v_mfma_f32_16x16x32_bf16 v[36:39], v[168:171], v[192:195], v[36:39]
	v_mfma_f32_16x16x32_bf16 v[32:35], v[176:179], v[192:195], v[32:35]
	v_mfma_f32_16x16x32_bf16 v[20:23], v[168:171], v[202:205], v[20:23]
	v_mfma_f32_16x16x32_bf16 v[16:19], v[176:179], v[202:205], v[16:19]
	v_mfma_f32_16x16x32_bf16 v[4:7], v[168:171], v[210:213], v[4:7]
	v_mfma_f32_16x16x32_bf16 v[0:3], v[176:179], v[210:213], v[0:3]
	v_mfma_f32_16x16x32_bf16 v[52:55], v[172:175], v[188:191], v[52:55]
	v_mfma_f32_16x16x32_bf16 v[48:51], v[180:183], v[188:191], v[48:51]
	v_mfma_f32_16x16x32_bf16 v[36:39], v[172:175], v[196:199], v[36:39]
	v_mfma_f32_16x16x32_bf16 v[32:35], v[180:183], v[196:199], v[32:35]
	v_mfma_f32_16x16x32_bf16 v[20:23], v[172:175], v[206:209], v[20:23]
	v_mfma_f32_16x16x32_bf16 v[16:19], v[180:183], v[206:209], v[16:19]
	v_mfma_f32_16x16x32_bf16 v[4:7], v[172:175], v[214:217], v[4:7]
	v_mfma_f32_16x16x32_bf16 v[0:3], v[180:183], v[214:217], v[0:3]
	s_barrier
	s_add_u32 s44, s44, 0x10000
	s_addc_u32 s45, s45, 0
	s_add_u32 s68, s68, 0x100
	s_addc_u32 s69, s69, 0
	s_cmp_ge_i32 s70, s57
	s_mov_b32 s46, s70
	s_cbranch_scc0 .LBB0_1104

; #define PG8_WAIT_V(n) asm volatile("s_waitcnt vmcnt(" #n ")" ::: "memory")
; #define PG8_BAR __builtin_amdgcn_s_barrier()
; template <class Epi, class Sched, bool ALIGN_EPI = false, bool SP2 = false>
; __device__ __forceinline__ void gemm_phase(PG8_LAS unsigned char* lds, const Gemm g, const Sched& S, const Epi& E) {
;     ...
;     PG8_WAIT_V(0);
;     if constexpr (!ALIGN_EPI) { if (wr == 0) PG8_BAR; }
;     PG8_BAR;
; __device__ __forceinline__ void xcd_barrier(const XcdBarrier& b) {
;     asm volatile("s_waitcnt vmcnt(0)" ::: "memory");
;     __syncthreads();
;     if (threadIdx.x == 0) {
;         unsigned* bar = b.bar;
;         __builtin_amdgcn_s_waitcnt(0);
;         unsigned nloc = b.st[0], nx = b.st[1];
;         if (nloc == 0u) { xcd_barrier_complete(bar, b.x, nloc, nx); b.st[0] = nloc; b.st[1] = nx; }
.LBB0_1127:
	s_waitcnt vmcnt(0)
	s_waitcnt vmcnt(0) lgkmcnt(0)
	s_barrier
	s_setprio 0
	s_and_saveexec_b64 s[0:1], s[92:93]
	s_cbranch_execz .LBB0_1179
	s_add_i32 s2, 0, 0x20400
	v_mov_b32_e32 v0, s2
	s_waitcnt vmcnt(0) expcnt(0) lgkmcnt(0)
	ds_read_b32 v2, v0
	s_add_i32 s2, 0, 0x20404
	v_mov_b32_e32 v0, s2
	ds_read_b32 v0, v0
	s_waitcnt lgkmcnt(1)
	v_cmp_ne_u32_e32 vcc, 0, v2
	s_cbranch_vccnz .LBB0_1143
	v_readlane_b32 s2, v253, 0
	s_mul_i32 s56, s31, s2
	s_add_u32 s2, s28, 0x180200
	s_addc_u32 s3, s29, 0
	s_add_u32 s4, s28, 0x180400
	s_addc_u32 s5, s29, 0
	s_add_u32 s6, s28, 0x180500
	s_addc_u32 s7, s29, 0
	s_add_u32 s8, s28, 0x180600
	s_addc_u32 s9, s29, 0
	s_add_u32 s12, s28, 0x180700
	s_addc_u32 s13, s29, 0
	s_add_u32 s14, s28, 0x180800
	s_addc_u32 s15, s29, 0
	s_add_u32 s16, s28, 0x180900
	s_addc_u32 s17, s29, 0
	s_add_u32 s24, s28, 0x180a00
	s_addc_u32 s25, s29, 0
	s_mul_i32 s56, s56, s30
	s_add_u32 s30, s28, 0x180b00
	s_addc_u32 s31, s29, 0
	s_add_u32 s34, s28, 0x180c00
	s_addc_u32 s35, s29, 0
	s_add_u32 s36, s28, 0x180d00
	s_addc_u32 s37, s29, 0
	s_add_u32 s38, s28, 0x180e00
	s_addc_u32 s39, s29, 0
	s_add_u32 s40, s28, 0x180f00
	s_addc_u32 s41, s29, 0
	s_add_u32 s42, s28, 0x181000
	s_addc_u32 s43, s29, 0
	s_add_u32 s44, s28, 0x181100
	s_addc_u32 s45, s29, 0
	s_add_u32 s46, s28, 0x181200
	s_addc_u32 s47, s29, 0
	s_add_u32 s48, s28, 0x181300
	s_addc_u32 s49, s29, 0
	s_mov_b32 s57, 1
	v_mov_b32_e32 v16, 0
	s_branch .LBB0_1131
